# GEMM main loops (5 sites): per-phase s_setprio flips deleted, one static s_setprio 1 for the lagging wave group set at the stagger barrier, reset at phase exit
# speedup vs baseline: 1.0086x; 1.0037x over previous
; #define PG8_STAGE(bufoff, gbase, voff) do { _Pragma("unroll") for (int _i = 0; _i < 2; ++_i) \
;         __builtin_amdgcn_global_load_lds((const unsigned*)((const char*)(gbase) + (voff)[_i]), (PG8_LAS unsigned*)(lds + (bufoff) + ldsw + _i * 8192), 16, 0, 0); } while (0)
; #define PG8_WAIT_V(n) asm volatile("s_waitcnt vmcnt(" #n ")" ::: "memory")
; #define PG8_BAR __builtin_amdgcn_s_barrier()
; template <class Epi, class Sched, bool ALIGN_EPI = false, bool SP2 = false>
; __device__ __forceinline__ void gemm_phase(PG8_LAS unsigned char* lds, const Gemm g, const Sched& S, const Epi& E) {
;     int tid_ = threadIdx.x; asm volatile("" : "+v"(tid_)); const int tid = tid_, wid = __builtin_amdgcn_readfirstlane(tid >> 6), lane = tid & 63, wr = wid >> 2, wc = wid & 3, fr = lane & 15, fq = lane >> 4;
;     const int K = g.K, nt = K / BK;
;     unsigned voffA[2], voffB[2];
; #pragma unroll
;     for (int i = 0; i < 2; ++i) { int R, C; stage_rc(tid * 16 + i * 8192, R, C); const int Rb = Epi::PERM ? ((R & ~31) + perm32(R & 31)) : R;
;         voffA[i] = (unsigned)(R * K + C) * 2u; voffB[i] = (unsigned)(Rb * K + C) * 2u; }
;     ...
;     const char* cA = (const char*)g.A + (size_t)cur.pm * tstep; const char* cB = (const char*)g.Bt + (size_t)cur.pn * tstep;
;     S.a_ready(cur);
;     if constexpr (SP2) {
;         PG8_STAGE(PG8_SB(0, 0), cB, voffB); PG8_STAGE(PG8_SB(0, 1), cB + hstep, voffB); PG8_STAGE(PG8_SA(0, 0), cA, voffA); PG8_STAGE(PG8_SA(0, 1), cA + hstep, voffA);
;         if (wr == 1) PG8_BAR;
;         PG8_WAIT_V(2); PG8_BAR;
;         PG8_STAGE(PG8_SB(1, 0), cB + kstep, voffB); PG8_STAGE(PG8_SA(1, 0), cA + kstep, voffA); PG8_STAGE(PG8_SB(1, 1), cB + hstep + kstep, voffB);
;         PG8_WAIT_V(6); PG8_BAR;
.LBB0_135:
	s_andn2_b64 vcc, exec, s[6:7]
	s_cbranch_vccnz .LBB0_224
	s_mov_b64 s[6:7], s[56:57]
	s_waitcnt vmcnt(0)
	v_mov_b32_e32 v0, v228
	v_readlane_b32 s4, v254, 0
	s_waitcnt vmcnt(21)
	v_mov_b32_e32 v14, v228
	s_cmpk_gt_i32 s4, 0x2ff
	s_waitcnt lgkmcnt(0)
	v_readfirstlane_b32 s26, v14
	s_cbranch_scc1 .LBB0_157
	v_lshlrev_b32_e32 v0, 4, v14
	v_add_u32_e32 v1, 0x2000, v0
	v_ashrrev_i32_e32 v2, 31, v1
	v_lshrrev_b32_e32 v2, 22, v2
	v_add_u32_e32 v2, v1, v2
	v_ashrrev_i32_e32 v8, 10, v2
	v_mul_i32_i24_e32 v2, 0x400, v8
	v_sub_u32_e32 v1, v1, v2
	v_lshrrev_b32_e32 v2, 4, v1
	v_bitop3_b32 v1, v2, v1, 32 bitop3:0x6c
	v_ashrrev_i32_e32 v2, 31, v1
	v_lshrrev_b32_e32 v2, 26, v2
	v_add_u32_e32 v2, v1, v2
	v_lshlrev_b32_e32 v3, 3, v8
	v_ashrrev_i32_e32 v9, 6, v2
	v_and_b32_e32 v3, -16, v3
	v_add_u32_e32 v3, v9, v3
	v_and_b32_e32 v4, 3, v9
	s_mov_b32 s22, 0x1fffe0
	v_lshrrev_b32_e32 v5, 2, v3
	v_lshlrev_b32_e32 v6, 1, v3
	v_and_b32_e32 v2, 0xc0, v2
	v_and_or_b32 v4, v3, s22, v4
	v_and_b32_e32 v5, 4, v5
	v_and_b32_e32 v6, 24, v6
	v_sub_u32_e32 v1, v1, v2
	v_or3_b32 v4, v4, v5, v6
	v_lshlrev_b32_e32 v5, 5, v8
	v_ashrrev_i16_sdwa v1, v229, sext(v1) dst_sel:DWORD dst_unused:UNUSED_PAD src0_sel:DWORD src1_sel:BYTE_0
	v_and_b32_e32 v5, 32, v5
	v_bfe_i32 v10, v1, 0, 16
	v_add_lshl_u32 v1, v5, v10, 1
	v_lshl_add_u32 v130, v4, 11, v1
	v_lshl_add_u32 v132, v3, 11, v1
	v_bfe_i32 v1, v14, 27, 1
	v_lshrrev_b32_e32 v1, 22, v1
	v_add_u32_e32 v1, v0, v1
	s_load_dwordx2 s[6:7], s[6:7], 0x68
	v_and_b32_e32 v1, 0xfffffc00, v1
	v_sub_u32_e32 v0, v0, v1
	v_lshrrev_b32_e32 v1, 4, v0
	v_ashrrev_i32_e32 v2, 31, v14
	v_bitop3_b32 v0, v1, v0, 32 bitop3:0x6c
	v_lshrrev_b32_e32 v2, 26, v2
	v_ashrrev_i32_e32 v1, 31, v0
	v_add_u32_e32 v2, v14, v2
	s_waitcnt lgkmcnt(0)
	s_add_u32 s5, s6, 0xe300000
	v_lshrrev_b32_e32 v1, 26, v1
	v_ashrrev_i32_e32 v12, 6, v2
	s_addc_u32 s18, s7, 0
	v_add_u32_e32 v1, v0, v1
	v_lshlrev_b32_e32 v2, 3, v12
	s_add_u32 s19, s6, 0x200000
	v_ashrrev_i32_e32 v11, 6, v1
	v_and_b32_e32 v2, -16, v2
	s_addc_u32 s44, s7, 0
	v_add_u32_e32 v2, v11, v2
	v_and_b32_e32 v3, 3, v11
	s_ashr_i32 s49, s4, 31
	v_and_or_b32 v3, v2, s22, v3
	s_lshr_b32 s22, s49, 29
	s_add_i32 s22, s4, s22
	s_ashr_i32 s27, s26, 6
	s_ashr_i32 s23, s22, 3
	s_and_b32 s22, s22, -8
	s_ashr_i32 s28, s26, 8
	s_lshl_b32 s45, s27, 10
	s_sub_i32 s22, s4, s22
	s_cmp_lt_i32 s22, 0
	s_movk_i32 s24, 0x61
	s_cselect_b32 s24, s24, 0x60
	s_mul_i32 s22, s22, s24
	s_add_i32 s22, s22, s23
	s_mul_hi_i32 s23, s22, 0x2aaaaaab
	s_lshr_b32 s24, s23, 31
	s_ashr_i32 s23, s23, 4
	s_add_i32 s23, s23, s24
	s_lshl_b32 s25, s23, 3
	s_mulk_i32 s23, 0x60
	s_sub_i32 s22, s22, s23
	s_bfe_i32 s23, s22, 0x80000
	s_bfe_u32 s23, s23, 0x3000c
	s_add_i32 s23, s22, s23
	s_bfe_i32 s24, s23, 0x80000
	s_and_b32 s23, s23, 0xf8
	s_sub_i32 s22, s22, s23
	s_sext_i32_i16 s24, s24
	s_sext_i32_i8 s22, s22
	v_lshrrev_b32_e32 v4, 2, v2
	v_lshlrev_b32_e32 v5, 1, v2
	v_and_b32_e32 v1, 0xc0, v1
	s_lshr_b32 s24, s24, 3
	s_add_i32 s42, s25, s22
	v_and_b32_e32 v4, 4, v4
	v_and_b32_e32 v5, 24, v5
	v_sub_u32_e32 v0, v0, v1
	s_ashr_i32 s43, s42, 31
	s_bfe_i64 s[30:31], s[24:25], 0x100000
	v_or3_b32 v3, v3, v4, v5
	v_lshlrev_b32_e32 v4, 5, v12
	v_ashrrev_i16_sdwa v0, v229, sext(v0) dst_sel:DWORD dst_unused:UNUSED_PAD src0_sel:DWORD src1_sel:BYTE_0
	s_lshl_b64 s[22:23], s[42:43], 19
	s_lshl_b64 s[30:31], s[30:31], 19
	v_and_b32_e32 v4, 32, v4
	v_bfe_i32 v13, v0, 0, 16
	s_add_u32 s50, s19, s30
	v_add_lshl_u32 v0, v4, v13, 1
	s_addc_u32 s51, s44, s31
	s_add_i32 s52, s45, 0
	v_lshl_add_u32 v134, v3, 11, v0
	s_add_i32 m0, s52, 0x10000
	v_lshl_add_u32 v136, v2, 11, v0
	global_load_lds_dwordx4 v134, s[50:51]
	s_add_i32 m0, s52, 0x12000
	s_add_u32 s30, s50, 0x40000
	global_load_lds_dwordx4 v130, s[50:51]
	s_addc_u32 s31, s51, 0
	s_add_i32 m0, s52, 0x14000
	v_mov_b32_e32 v135, v32
	global_load_lds_dwordx4 v134, s[30:31]
	s_add_i32 m0, s52, 0x16000
	s_add_u32 s90, s5, s22
	s_addc_u32 s91, s18, s23
	s_add_i32 s53, s52, 0x2000
	global_load_lds_dwordx4 v130, s[30:31]
	s_mov_b32 m0, s52
	s_add_u32 s22, s90, 0x40000
	global_load_lds_dwordx4 v136, s[90:91]
	s_mov_b32 m0, s53
	s_addc_u32 s23, s91, 0
	s_add_i32 s55, s52, 0x4000
	global_load_lds_dwordx4 v132, s[90:91]
	s_mov_b32 m0, s55
	s_add_i32 s56, s52, 0x6000
	global_load_lds_dwordx4 v136, s[22:23]
	s_mov_b32 m0, s56
	v_mov_b32_e32 v131, v32
	global_load_lds_dwordx4 v132, s[22:23]
	v_mov_b32_e32 v137, v32
	v_mov_b32_e32 v133, v32
	s_cmp_eq_u32 s28, 1
	v_lshl_add_u64 v[6:7], s[50:51], 0, v[134:135]
	v_lshl_add_u64 v[4:5], s[50:51], 0, v[130:131]
	v_lshl_add_u64 v[0:1], s[90:91], 0, v[136:137]
	s_cselect_b64 s[22:23], -1, 0
	s_cmp_lg_u32 s28, 1
	v_lshl_add_u64 v[2:3], s[90:91], 0, v[132:133]
	s_cbranch_scc1 .LBB0_139
	s_barrier
	s_setprio 1

; #define PG8_STAGE(bufoff, gbase, voff) do { _Pragma("unroll") for (int _i = 0; _i < 2; ++_i) \
;         __builtin_amdgcn_global_load_lds((const unsigned*)((const char*)(gbase) + (voff)[_i]), (PG8_LAS unsigned*)(lds + (bufoff) + ldsw + _i * 8192), 16, 0, 0); } while (0)
; #define PG8_LDA(dst, b, h) do { _Pragma("unroll") for (int m = 0; m < 4; ++m) _Pragma("unroll") for (int k = 0; k < 2; ++k) dst[m][k] = *(const PG8_LAS bf16x8*)(lds + PG8_SA(b, h) + aoff + m * 2048 + k * 1024); } while (0)
; #define PG8_LDB(dst, b, h) do { _Pragma("unroll") for (int n = 0; n < 2; ++n) _Pragma("unroll") for (int k = 0; k < 2; ++k) dst[n][k] = *(const PG8_LAS bf16x8*)(lds + PG8_SB(b, h) + boff + n * 2048 + k * 1024); } while (0)
; #define PG8_MMA(ai, bj, At, Bt) do { __builtin_amdgcn_s_setprio(1); _Pragma("unroll") for (int m = 0; m < 4; ++m) _Pragma("unroll") for (int n = 0; n < 2; ++n) _Pragma("unroll") for (int k = 0; k < 2; ++k) \
;         acc[ai][bj][m][n] = __builtin_amdgcn_mfma_f32_16x16x32_bf16(Bt[n][k], At[m][k], acc[ai][bj][m][n], 0, 0, 0); __builtin_amdgcn_s_setprio(0); } while (0)
; #define PG8_WAIT_V(n) asm volatile("s_waitcnt vmcnt(" #n ")" ::: "memory")
; #define PG8_WAIT_L(n) asm volatile("s_waitcnt lgkmcnt(" #n ")" ::: "memory")
; #define PG8_BAR __builtin_amdgcn_s_barrier()
; #define PG8_SCHED __builtin_amdgcn_sched_barrier(0)
; template <class Epi, class Sched, bool ALIGN_EPI = false, bool SP2 = false>
; __device__ __forceinline__ void gemm_phase(PG8_LAS unsigned char* lds, const Gemm g, const Sched& S, const Epi& E) {
;     ...
;             PG8_LDB(B0, 0, 0); PG8_LDB(B1, 0, 1); PG8_SCHED; PG8_LDA(At, 0, 0); PG8_STAGE(PG8_SA(1, 1), a1 + hstep, voffA);
;             PG8_WAIT_V(8); PG8_WAIT_L(0); PG8_BAR; PG8_MMA(0, 0, At, B0); PG8_MMA(0, 1, At, B1); PG8_BAR; PG8_SCHED;
;             PG8_LDA(At, 0, 1); PG8_STAGE(PG8_SB(0, 0), b2, voffB); PG8_STAGE(PG8_SB(0, 1), b2 + hstep, voffB); PG8_STAGE(PG8_SA(0, 0), a2, voffA);
;             PG8_WAIT_V(8); PG8_WAIT_L(0); PG8_BAR; PG8_MMA(1, 0, At, B0); PG8_MMA(1, 1, At, B1); PG8_BAR; PG8_SCHED;
.LBB0_145:
	s_add_u32 s46, s90, 0xfffc0080
	s_addc_u32 s47, s91, -1
	s_add_i32 s66, 0, 0x10000
	s_cmp_eq_u32 s65, 12
	s_cselect_b32 s51, s31, s47
	s_cselect_b32 s50, s43, s46
	v_add_u32_e32 v142, s66, v145
	s_cselect_b32 s47, s29, s64
	s_cselect_b32 s46, s62, s63
	s_add_i32 s68, 0, 0x14000
	ds_read_b128 v[150:153], v142
	ds_read_b128 v[154:157], v142 offset:1024
	ds_read_b128 v[158:161], v142 offset:2048
	ds_read_b128 v[162:165], v142 offset:3072
	v_add_u32_e32 v142, s68, v145
	ds_read_b128 v[166:169], v142
	ds_read_b128 v[170:173], v142 offset:1024
	ds_read_b128 v[174:177], v142 offset:2048
	ds_read_b128 v[178:181], v142 offset:3072
	v_lshl_add_u64 v[142:143], s[90:91], 0, v[138:139]
	s_add_i32 m0, s52, 0xc000
	ds_read_b128 v[182:185], v149
	ds_read_b128 v[186:189], v149 offset:1024
	ds_read_b128 v[190:193], v149 offset:2048
	ds_read_b128 v[204:207], v149 offset:3072
	ds_read_b128 v[208:211], v149 offset:4096
	ds_read_b128 v[212:215], v149 offset:5120
	ds_read_b128 v[216:219], v149 offset:6144
	ds_read_b128 v[220:223], v149 offset:7168
	global_load_lds_dwordx4 v[142:143], off
	v_lshl_add_u64 v[142:143], s[90:91], 0, v[140:141]
	s_add_i32 m0, s52, 0xe000
	s_nop 0
	global_load_lds_dwordx4 v[142:143], off
	s_waitcnt vmcnt(8)
	s_waitcnt lgkmcnt(0)
	s_barrier
	s_waitcnt lgkmcnt(0)
	v_mfma_f32_16x16x32_bf16 v[126:129], v[150:153], v[182:185], v[126:129]
	v_mfma_f32_16x16x32_bf16 v[122:125], v[158:161], v[182:185], v[122:125]
	v_mfma_f32_16x16x32_bf16 v[114:117], v[150:153], v[190:193], v[114:117]
	v_mfma_f32_16x16x32_bf16 v[106:109], v[158:161], v[190:193], v[106:109]
	v_mfma_f32_16x16x32_bf16 v[98:101], v[150:153], v[208:211], v[98:101]
	v_mfma_f32_16x16x32_bf16 v[90:93], v[158:161], v[208:211], v[90:93]
	v_mfma_f32_16x16x32_bf16 v[82:85], v[150:153], v[216:219], v[82:85]
	v_mfma_f32_16x16x32_bf16 v[74:77], v[158:161], v[216:219], v[74:77]
	v_mfma_f32_16x16x32_bf16 v[126:129], v[154:157], v[186:189], v[126:129]
	v_mfma_f32_16x16x32_bf16 v[122:125], v[162:165], v[186:189], v[122:125]
	v_mfma_f32_16x16x32_bf16 v[114:117], v[154:157], v[204:207], v[114:117]
	v_mfma_f32_16x16x32_bf16 v[106:109], v[162:165], v[204:207], v[106:109]
	v_mfma_f32_16x16x32_bf16 v[98:101], v[154:157], v[212:215], v[98:101]
	v_mfma_f32_16x16x32_bf16 v[90:93], v[162:165], v[212:215], v[90:93]
	v_mfma_f32_16x16x32_bf16 v[82:85], v[154:157], v[220:223], v[82:85]
	v_mfma_f32_16x16x32_bf16 v[74:77], v[162:165], v[220:223], v[74:77]
	v_mfma_f32_16x16x32_bf16 v[118:121], v[166:169], v[182:185], v[118:121]
	v_mfma_f32_16x16x32_bf16 v[110:113], v[174:177], v[182:185], v[110:113]
	v_mfma_f32_16x16x32_bf16 v[102:105], v[166:169], v[190:193], v[102:105]
	v_mfma_f32_16x16x32_bf16 v[94:97], v[174:177], v[190:193], v[94:97]
	v_mfma_f32_16x16x32_bf16 v[86:89], v[166:169], v[208:211], v[86:89]
	v_mfma_f32_16x16x32_bf16 v[78:81], v[174:177], v[208:211], v[78:81]
	v_mfma_f32_16x16x32_bf16 v[70:73], v[166:169], v[216:219], v[70:73]
	v_mfma_f32_16x16x32_bf16 v[66:69], v[174:177], v[216:219], v[66:69]
	v_mfma_f32_16x16x32_bf16 v[118:121], v[170:173], v[186:189], v[118:121]
	v_mfma_f32_16x16x32_bf16 v[110:113], v[178:181], v[186:189], v[110:113]
	v_mfma_f32_16x16x32_bf16 v[102:105], v[170:173], v[204:207], v[102:105]
	v_mfma_f32_16x16x32_bf16 v[94:97], v[178:181], v[204:207], v[94:97]
	v_mfma_f32_16x16x32_bf16 v[86:89], v[170:173], v[212:215], v[86:89]
	v_mfma_f32_16x16x32_bf16 v[78:81], v[178:181], v[212:215], v[78:81]
	v_mfma_f32_16x16x32_bf16 v[70:73], v[170:173], v[220:223], v[70:73]
	v_mfma_f32_16x16x32_bf16 v[66:69], v[178:181], v[220:223], v[66:69]
	s_barrier
	s_add_i32 s66, s66, s45
	v_lshl_add_u64 v[142:143], s[46:47], 0, v[134:135]
	s_mov_b32 m0, s66
	ds_read_b128 v[182:185], v149 offset:16384
	ds_read_b128 v[186:189], v149 offset:17408
	ds_read_b128 v[190:193], v149 offset:18432
	ds_read_b128 v[204:207], v149 offset:19456
	ds_read_b128 v[208:211], v149 offset:20480
	ds_read_b128 v[212:215], v149 offset:21504
	ds_read_b128 v[216:219], v149 offset:22528
	ds_read_b128 v[220:223], v149 offset:23552
	global_load_lds_dwordx4 v[142:143], off
	s_add_i32 m0, s66, 0x2000
	s_add_u32 s66, s46, 0x40000
	v_lshl_add_u64 v[146:147], s[46:47], 0, v[130:131]
	s_addc_u32 s67, s47, 0
	s_add_i32 s68, s68, s45
	global_load_lds_dwordx4 v[146:147], off
	v_lshl_add_u64 v[224:225], s[66:67], 0, v[134:135]
	s_mov_b32 m0, s68
	v_lshl_add_u64 v[226:227], s[50:51], 0, v[132:133]
	global_load_lds_dwordx4 v[224:225], off
	v_lshl_add_u64 v[224:225], s[66:67], 0, v[130:131]
	s_add_i32 m0, s68, 0x2000
	s_nop 0
	global_load_lds_dwordx4 v[224:225], off
	v_lshl_add_u64 v[224:225], s[50:51], 0, v[136:137]
	s_mov_b32 m0, s52
	s_nop 0
	global_load_lds_dwordx4 v[224:225], off
	s_mov_b32 m0, s53
	s_nop 0
	global_load_lds_dwordx4 v[226:227], off
	s_waitcnt vmcnt(8)
	s_waitcnt lgkmcnt(0)
	s_barrier
; #define PG8_STAGE(bufoff, gbase, voff) do { _Pragma("unroll") for (int _i = 0; _i < 2; ++_i) \
;         __builtin_amdgcn_global_load_lds((const unsigned*)((const char*)(gbase) + (voff)[_i]), (PG8_LAS unsigned*)(lds + (bufoff) + ldsw + _i * 8192), 16, 0, 0); } while (0)
; #define PG8_LDA(dst, b, h) do { _Pragma("unroll") for (int m = 0; m < 4; ++m) _Pragma("unroll") for (int k = 0; k < 2; ++k) dst[m][k] = *(const PG8_LAS bf16x8*)(lds + PG8_SA(b, h) + aoff + m * 2048 + k * 1024); } while (0)
; #define PG8_LDB(dst, b, h) do { _Pragma("unroll") for (int n = 0; n < 2; ++n) _Pragma("unroll") for (int k = 0; k < 2; ++k) dst[n][k] = *(const PG8_LAS bf16x8*)(lds + PG8_SB(b, h) + boff + n * 2048 + k * 1024); } while (0)
; #define PG8_MMA(ai, bj, At, Bt) do { __builtin_amdgcn_s_setprio(1); _Pragma("unroll") for (int m = 0; m < 4; ++m) _Pragma("unroll") for (int n = 0; n < 2; ++n) _Pragma("unroll") for (int k = 0; k < 2; ++k) \
;         acc[ai][bj][m][n] = __builtin_amdgcn_mfma_f32_16x16x32_bf16(Bt[n][k], At[m][k], acc[ai][bj][m][n], 0, 0, 0); __builtin_amdgcn_s_setprio(0); } while (0)
; #define PG8_WAIT_V(n) asm volatile("s_waitcnt vmcnt(" #n ")" ::: "memory")
; #define PG8_WAIT_L(n) asm volatile("s_waitcnt lgkmcnt(" #n ")" ::: "memory")
; #define PG8_BAR __builtin_amdgcn_s_barrier()
; #define PG8_SCHED __builtin_amdgcn_sched_barrier(0)
; template <class Epi, class Sched, bool ALIGN_EPI = false, bool SP2 = false>
; __device__ __forceinline__ void gemm_phase(PG8_LAS unsigned char* lds, const Gemm g, const Sched& S, const Epi& E) {
;     ...
;             PG8_WAIT_V(8); PG8_WAIT_L(0); PG8_BAR; PG8_MMA(1, 0, At, B0); PG8_MMA(1, 1, At, B1); PG8_BAR; PG8_SCHED;
;             PG8_LDB(B0, 1, 0); PG8_LDB(B1, 1, 1); PG8_SCHED; PG8_LDA(At, 1, 0); PG8_STAGE(PG8_SA(0, 1), a2 + hstep, voffA);
;             PG8_WAIT_V(8); PG8_WAIT_L(0); PG8_BAR; PG8_MMA(0, 0, At, B0); PG8_MMA(0, 1, At, B1); PG8_BAR; PG8_SCHED;
	s_waitcnt lgkmcnt(0)
	v_mfma_f32_16x16x32_bf16 v[62:65], v[150:153], v[182:185], v[62:65]
	v_mfma_f32_16x16x32_bf16 v[58:61], v[158:161], v[182:185], v[58:61]
	v_mfma_f32_16x16x32_bf16 v[50:53], v[150:153], v[190:193], v[50:53]
	v_mfma_f32_16x16x32_bf16 v[42:45], v[158:161], v[190:193], v[42:45]
	v_mfma_f32_16x16x32_bf16 v[34:37], v[150:153], v[208:211], v[34:37]
	v_mfma_f32_16x16x32_bf16 v[24:27], v[158:161], v[208:211], v[24:27]
	v_mfma_f32_16x16x32_bf16 v[16:19], v[150:153], v[216:219], v[16:19]
	v_mfma_f32_16x16x32_bf16 v[8:11], v[158:161], v[216:219], v[8:11]
	v_mfma_f32_16x16x32_bf16 v[62:65], v[154:157], v[186:189], v[62:65]
	v_mfma_f32_16x16x32_bf16 v[58:61], v[162:165], v[186:189], v[58:61]
	v_mfma_f32_16x16x32_bf16 v[50:53], v[154:157], v[204:207], v[50:53]
	v_mfma_f32_16x16x32_bf16 v[42:45], v[162:165], v[204:207], v[42:45]
	v_mfma_f32_16x16x32_bf16 v[34:37], v[154:157], v[212:215], v[34:37]
	v_mfma_f32_16x16x32_bf16 v[24:27], v[162:165], v[212:215], v[24:27]
	v_mfma_f32_16x16x32_bf16 v[16:19], v[154:157], v[220:223], v[16:19]
	v_mfma_f32_16x16x32_bf16 v[8:11], v[162:165], v[220:223], v[8:11]
	v_mfma_f32_16x16x32_bf16 v[54:57], v[166:169], v[182:185], v[54:57]
	v_mfma_f32_16x16x32_bf16 v[46:49], v[174:177], v[182:185], v[46:49]
	v_mfma_f32_16x16x32_bf16 v[38:41], v[166:169], v[190:193], v[38:41]
	v_mfma_f32_16x16x32_bf16 v[28:31], v[174:177], v[190:193], v[28:31]
	v_mfma_f32_16x16x32_bf16 v[20:23], v[166:169], v[208:211], v[20:23]
	v_mfma_f32_16x16x32_bf16 v[12:15], v[174:177], v[208:211], v[12:15]
	v_mfma_f32_16x16x32_bf16 v[4:7], v[166:169], v[216:219], v[4:7]
	v_mfma_f32_16x16x32_bf16 v[0:3], v[174:177], v[216:219], v[0:3]
	v_mfma_f32_16x16x32_bf16 v[54:57], v[170:173], v[186:189], v[54:57]
	v_mfma_f32_16x16x32_bf16 v[46:49], v[178:181], v[186:189], v[46:49]
	v_mfma_f32_16x16x32_bf16 v[38:41], v[170:173], v[204:207], v[38:41]
	v_mfma_f32_16x16x32_bf16 v[28:31], v[178:181], v[204:207], v[28:31]
	v_mfma_f32_16x16x32_bf16 v[20:23], v[170:173], v[212:215], v[20:23]
	v_mfma_f32_16x16x32_bf16 v[12:15], v[178:181], v[212:215], v[12:15]
	v_mfma_f32_16x16x32_bf16 v[4:7], v[170:173], v[220:223], v[4:7]
	v_mfma_f32_16x16x32_bf16 v[0:3], v[178:181], v[220:223], v[0:3]
	s_barrier
	s_add_i32 s66, 0, 0x18000
	v_add_u32_e32 v144, s66, v145
	s_add_i32 s67, 0, 0x1c000
	ds_read_b128 v[150:153], v144
	ds_read_b128 v[154:157], v144 offset:1024
	ds_read_b128 v[158:161], v144 offset:2048
	ds_read_b128 v[162:165], v144 offset:3072
	v_add_u32_e32 v144, s67, v145
	ds_read_b128 v[166:169], v144
	ds_read_b128 v[170:173], v144 offset:1024
	ds_read_b128 v[174:177], v144 offset:2048
	ds_read_b128 v[178:181], v144 offset:3072
	s_add_u32 s50, s50, 0x40000
	s_addc_u32 s51, s51, 0
	s_mov_b32 m0, s55
	v_lshl_add_u64 v[238:239], s[50:51], 0, v[136:137]
	ds_read_b128 v[182:185], v149 offset:32768
	ds_read_b128 v[186:189], v149 offset:33792
	ds_read_b128 v[190:193], v149 offset:34816
	ds_read_b128 v[204:207], v149 offset:35840
	ds_read_b128 v[208:211], v149 offset:36864
	ds_read_b128 v[212:215], v149 offset:37888
	ds_read_b128 v[216:219], v149 offset:38912
	ds_read_b128 v[220:223], v149 offset:39936
	global_load_lds_dwordx4 v[238:239], off
	v_lshl_add_u64 v[238:239], s[50:51], 0, v[132:133]
	s_mov_b32 m0, s56
	s_nop 0
	global_load_lds_dwordx4 v[238:239], off
	s_waitcnt vmcnt(8)
	s_waitcnt lgkmcnt(0)
	s_barrier
	s_waitcnt lgkmcnt(0)
	v_mfma_f32_16x16x32_bf16 v[126:129], v[150:153], v[182:185], v[126:129]
	v_mfma_f32_16x16x32_bf16 v[122:125], v[158:161], v[182:185], v[122:125]
	v_mfma_f32_16x16x32_bf16 v[114:117], v[150:153], v[190:193], v[114:117]
	v_mfma_f32_16x16x32_bf16 v[106:109], v[158:161], v[190:193], v[106:109]
	v_mfma_f32_16x16x32_bf16 v[98:101], v[150:153], v[208:211], v[98:101]
	v_mfma_f32_16x16x32_bf16 v[90:93], v[158:161], v[208:211], v[90:93]
	v_mfma_f32_16x16x32_bf16 v[82:85], v[150:153], v[216:219], v[82:85]
	v_mfma_f32_16x16x32_bf16 v[74:77], v[158:161], v[216:219], v[74:77]
	v_mfma_f32_16x16x32_bf16 v[126:129], v[154:157], v[186:189], v[126:129]
	v_mfma_f32_16x16x32_bf16 v[122:125], v[162:165], v[186:189], v[122:125]
	v_mfma_f32_16x16x32_bf16 v[114:117], v[154:157], v[204:207], v[114:117]
	v_mfma_f32_16x16x32_bf16 v[106:109], v[162:165], v[204:207], v[106:109]
	v_mfma_f32_16x16x32_bf16 v[98:101], v[154:157], v[212:215], v[98:101]
	v_mfma_f32_16x16x32_bf16 v[90:93], v[162:165], v[212:215], v[90:93]
	v_mfma_f32_16x16x32_bf16 v[82:85], v[154:157], v[220:223], v[82:85]
	v_mfma_f32_16x16x32_bf16 v[74:77], v[162:165], v[220:223], v[74:77]
	v_mfma_f32_16x16x32_bf16 v[118:121], v[166:169], v[182:185], v[118:121]
	v_mfma_f32_16x16x32_bf16 v[110:113], v[174:177], v[182:185], v[110:113]
	v_mfma_f32_16x16x32_bf16 v[102:105], v[166:169], v[190:193], v[102:105]
	v_mfma_f32_16x16x32_bf16 v[94:97], v[174:177], v[190:193], v[94:97]
	v_mfma_f32_16x16x32_bf16 v[86:89], v[166:169], v[208:211], v[86:89]
	v_mfma_f32_16x16x32_bf16 v[78:81], v[174:177], v[208:211], v[78:81]
	v_mfma_f32_16x16x32_bf16 v[70:73], v[166:169], v[216:219], v[70:73]
	v_mfma_f32_16x16x32_bf16 v[66:69], v[174:177], v[216:219], v[66:69]
	v_mfma_f32_16x16x32_bf16 v[118:121], v[170:173], v[186:189], v[118:121]
	v_mfma_f32_16x16x32_bf16 v[110:113], v[178:181], v[186:189], v[110:113]
	v_mfma_f32_16x16x32_bf16 v[102:105], v[170:173], v[204:207], v[102:105]
	v_mfma_f32_16x16x32_bf16 v[94:97], v[178:181], v[204:207], v[94:97]
	v_mfma_f32_16x16x32_bf16 v[86:89], v[170:173], v[212:215], v[86:89]
	v_mfma_f32_16x16x32_bf16 v[78:81], v[178:181], v[212:215], v[78:81]
	v_mfma_f32_16x16x32_bf16 v[70:73], v[170:173], v[220:223], v[70:73]
	v_mfma_f32_16x16x32_bf16 v[66:69], v[178:181], v[220:223], v[66:69]
	s_barrier
; #define PG8_STAGE(bufoff, gbase, voff) do { _Pragma("unroll") for (int _i = 0; _i < 2; ++_i) \
;         __builtin_amdgcn_global_load_lds((const unsigned*)((const char*)(gbase) + (voff)[_i]), (PG8_LAS unsigned*)(lds + (bufoff) + ldsw + _i * 8192), 16, 0, 0); } while (0)
; #define PG8_LDA(dst, b, h) do { _Pragma("unroll") for (int m = 0; m < 4; ++m) _Pragma("unroll") for (int k = 0; k < 2; ++k) dst[m][k] = *(const PG8_LAS bf16x8*)(lds + PG8_SA(b, h) + aoff + m * 2048 + k * 1024); } while (0)
; #define PG8_MMA(ai, bj, At, Bt) do { __builtin_amdgcn_s_setprio(1); _Pragma("unroll") for (int m = 0; m < 4; ++m) _Pragma("unroll") for (int n = 0; n < 2; ++n) _Pragma("unroll") for (int k = 0; k < 2; ++k) \
;         acc[ai][bj][m][n] = __builtin_amdgcn_mfma_f32_16x16x32_bf16(Bt[n][k], At[m][k], acc[ai][bj][m][n], 0, 0, 0); __builtin_amdgcn_s_setprio(0); } while (0)
; #define PG8_WAIT_V(n) asm volatile("s_waitcnt vmcnt(" #n ")" ::: "memory")
; #define PG8_WAIT_L(n) asm volatile("s_waitcnt lgkmcnt(" #n ")" ::: "memory")
; #define PG8_BAR __builtin_amdgcn_s_barrier()
; #define PG8_SCHED __builtin_amdgcn_sched_barrier(0)
; template <class Epi, class Sched, bool ALIGN_EPI = false, bool SP2 = false>
; __device__ __forceinline__ void gemm_phase(PG8_LAS unsigned char* lds, const Gemm g, const Sched& S, const Epi& E) {
;     ...
;             PG8_WAIT_V(8); PG8_WAIT_L(0); PG8_BAR; PG8_MMA(0, 0, At, B0); PG8_MMA(0, 1, At, B1); PG8_BAR; PG8_SCHED;
;             PG8_LDA(At, 1, 1); PG8_STAGE(PG8_SB(1, 0), b3, voffB); PG8_STAGE(PG8_SB(1, 1), b3 + hstep, voffB); PG8_STAGE(PG8_SA(1, 0), a3, voffA);
;             PG8_WAIT_V(8); PG8_WAIT_L(0); PG8_BAR; PG8_MMA(1, 0, At, B0); PG8_MMA(1, 1, At, B1); PG8_BAR; PG8_SCHED;
;     ...
;         if constexpr (ALIGN_EPI) { if (wr == 0) PG8_BAR; }
	s_add_i32 s50, s66, s45
	v_lshl_add_u64 v[142:143], v[142:143], 0, s[8:9]
	s_mov_b32 m0, s50
	ds_read_b128 v[182:185], v149 offset:49152
	ds_read_b128 v[186:189], v149 offset:50176
	ds_read_b128 v[190:193], v149 offset:51200
	ds_read_b128 v[204:207], v149 offset:52224
	ds_read_b128 v[208:211], v149 offset:53248
	ds_read_b128 v[212:215], v149 offset:54272
	ds_read_b128 v[216:219], v149 offset:55296
	ds_read_b128 v[220:223], v149 offset:56320
	global_load_lds_dwordx4 v[142:143], off
	s_add_i32 m0, s50, 0x2000
	s_add_u32 s46, s46, 0x40080
	v_lshl_add_u64 v[142:143], v[146:147], 0, s[8:9]
	s_addc_u32 s47, s47, 0
	s_add_i32 s50, s67, s45
	global_load_lds_dwordx4 v[142:143], off
	v_lshl_add_u64 v[142:143], s[46:47], 0, v[134:135]
	s_mov_b32 m0, s50
	s_nop 0
	global_load_lds_dwordx4 v[142:143], off
	v_lshl_add_u64 v[142:143], s[46:47], 0, v[130:131]
	s_add_i32 m0, s50, 0x2000
	s_nop 0
	global_load_lds_dwordx4 v[142:143], off
	v_lshl_add_u64 v[142:143], v[224:225], 0, s[8:9]
	s_mov_b32 m0, s58
	s_nop 0
	global_load_lds_dwordx4 v[142:143], off
	v_lshl_add_u64 v[142:143], v[226:227], 0, s[8:9]
	s_mov_b32 m0, s59
	s_nop 0
	global_load_lds_dwordx4 v[142:143], off
	s_waitcnt vmcnt(8)
	s_waitcnt lgkmcnt(0)
	s_barrier
	s_waitcnt lgkmcnt(0)
	v_mfma_f32_16x16x32_bf16 v[62:65], v[150:153], v[182:185], v[62:65]
	v_mfma_f32_16x16x32_bf16 v[58:61], v[158:161], v[182:185], v[58:61]
	v_mfma_f32_16x16x32_bf16 v[50:53], v[150:153], v[190:193], v[50:53]
	v_mfma_f32_16x16x32_bf16 v[42:45], v[158:161], v[190:193], v[42:45]
	v_mfma_f32_16x16x32_bf16 v[34:37], v[150:153], v[208:211], v[34:37]
	v_mfma_f32_16x16x32_bf16 v[24:27], v[158:161], v[208:211], v[24:27]
	v_mfma_f32_16x16x32_bf16 v[16:19], v[150:153], v[216:219], v[16:19]
	v_mfma_f32_16x16x32_bf16 v[8:11], v[158:161], v[216:219], v[8:11]
	v_mfma_f32_16x16x32_bf16 v[62:65], v[154:157], v[186:189], v[62:65]
	v_mfma_f32_16x16x32_bf16 v[58:61], v[162:165], v[186:189], v[58:61]
	v_mfma_f32_16x16x32_bf16 v[50:53], v[154:157], v[204:207], v[50:53]
	v_mfma_f32_16x16x32_bf16 v[42:45], v[162:165], v[204:207], v[42:45]
	v_mfma_f32_16x16x32_bf16 v[34:37], v[154:157], v[212:215], v[34:37]
	v_mfma_f32_16x16x32_bf16 v[24:27], v[162:165], v[212:215], v[24:27]
	v_mfma_f32_16x16x32_bf16 v[16:19], v[154:157], v[220:223], v[16:19]
	v_mfma_f32_16x16x32_bf16 v[8:11], v[162:165], v[220:223], v[8:11]
	v_mfma_f32_16x16x32_bf16 v[54:57], v[166:169], v[182:185], v[54:57]
	v_mfma_f32_16x16x32_bf16 v[46:49], v[174:177], v[182:185], v[46:49]
	v_mfma_f32_16x16x32_bf16 v[38:41], v[166:169], v[190:193], v[38:41]
	v_mfma_f32_16x16x32_bf16 v[28:31], v[174:177], v[190:193], v[28:31]
	v_mfma_f32_16x16x32_bf16 v[20:23], v[166:169], v[208:211], v[20:23]
	v_mfma_f32_16x16x32_bf16 v[12:15], v[174:177], v[208:211], v[12:15]
	v_mfma_f32_16x16x32_bf16 v[4:7], v[166:169], v[216:219], v[4:7]
	v_mfma_f32_16x16x32_bf16 v[0:3], v[174:177], v[216:219], v[0:3]
	v_mfma_f32_16x16x32_bf16 v[54:57], v[170:173], v[186:189], v[54:57]
	v_mfma_f32_16x16x32_bf16 v[46:49], v[178:181], v[186:189], v[46:49]
	v_mfma_f32_16x16x32_bf16 v[38:41], v[170:173], v[204:207], v[38:41]
	v_mfma_f32_16x16x32_bf16 v[28:31], v[178:181], v[204:207], v[28:31]
	v_mfma_f32_16x16x32_bf16 v[20:23], v[170:173], v[212:215], v[20:23]
	v_mfma_f32_16x16x32_bf16 v[12:15], v[178:181], v[212:215], v[12:15]
	v_mfma_f32_16x16x32_bf16 v[4:7], v[170:173], v[220:223], v[4:7]
	v_mfma_f32_16x16x32_bf16 v[0:3], v[178:181], v[220:223], v[0:3]
	s_barrier
	s_add_i32 s65, s65, 2
	s_add_u32 s90, s90, 0x100
	s_addc_u32 s91, s91, 0
	s_add_u32 s63, s63, 0x100
	s_addc_u32 s64, s64, 0
	s_cmp_gt_u32 s65, 13
	s_cbranch_scc0 .LBB0_145
	s_and_b64 vcc, exec, s[26:27]
	s_cbranch_vccz .LBB0_148
	s_barrier

; #define PG8_WAIT_V(n) asm volatile("s_waitcnt vmcnt(" #n ")" ::: "memory")
; #define PG8_BAR __builtin_amdgcn_s_barrier()
; template <class Epi, class Sched, bool ALIGN_EPI = false, bool SP2 = false>
; __device__ __forceinline__ void gemm_phase(PG8_LAS unsigned char* lds, const Gemm g, const Sched& S, const Epi& E) {
;     ...
;     PG8_WAIT_V(0);
;     if constexpr (!ALIGN_EPI) { if (wr == 0) PG8_BAR; }
;     PG8_BAR;
.LBB0_156:
	s_setprio 0
	s_waitcnt vmcnt(0)
	v_readlane_b32 s56, v255, 4
	v_readlane_b32 s58, v255, 6
	v_readlane_b32 s52, v255, 8
	v_readlane_b32 s57, v255, 5
	v_readlane_b32 s59, v255, 7
	v_readlane_b32 s53, v255, 9
	v_readlane_b32 s55, v255, 10
	s_barrier

; #define PG8_STAGE(bufoff, gbase, voff) do { _Pragma("unroll") for (int _i = 0; _i < 2; ++_i) \
;         __builtin_amdgcn_global_load_lds((const unsigned*)((const char*)(gbase) + (voff)[_i]), (PG8_LAS unsigned*)(lds + (bufoff) + ldsw + _i * 8192), 16, 0, 0); } while (0)
; #define PG8_WAIT_V(n) asm volatile("s_waitcnt vmcnt(" #n ")" ::: "memory")
; #define PG8_BAR __builtin_amdgcn_s_barrier()
; template <class Epi, class Sched, bool ALIGN_EPI = false, bool SP2 = false>
; __device__ __forceinline__ void gemm_phase(PG8_LAS unsigned char* lds, const Gemm g, const Sched& S, const Epi& E) {
;     int tid_ = threadIdx.x; asm volatile("" : "+v"(tid_)); const int tid = tid_, wid = __builtin_amdgcn_readfirstlane(tid >> 6), lane = tid & 63, wr = wid >> 2, wc = wid & 3, fr = lane & 15, fq = lane >> 4;
;     const int K = g.K, nt = K / BK;
;     unsigned voffA[2], voffB[2];
; #pragma unroll
;     for (int i = 0; i < 2; ++i) { int R, C; stage_rc(tid * 16 + i * 8192, R, C); const int Rb = Epi::PERM ? ((R & ~31) + perm32(R & 31)) : R;
;         voffA[i] = (unsigned)(R * K + C) * 2u; voffB[i] = (unsigned)(Rb * K + C) * 2u; }
;     ...
;     const char* cA = (const char*)g.A + (size_t)cur.pm * tstep; const char* cB = (const char*)g.Bt + (size_t)cur.pn * tstep;
;     S.a_ready(cur);
;     if constexpr (SP2) {
;         PG8_STAGE(PG8_SB(0, 0), cB, voffB); PG8_STAGE(PG8_SB(0, 1), cB + hstep, voffB); PG8_STAGE(PG8_SA(0, 0), cA, voffA); PG8_STAGE(PG8_SA(0, 1), cA + hstep, voffA);
;         if (wr == 1) PG8_BAR;
;         PG8_WAIT_V(2); PG8_BAR;
;         PG8_STAGE(PG8_SB(1, 0), cB + kstep, voffB); PG8_STAGE(PG8_SA(1, 0), cA + kstep, voffA); PG8_STAGE(PG8_SB(1, 1), cB + hstep + kstep, voffB);
;         PG8_WAIT_V(6); PG8_BAR;
.LBB0_539:
	s_andn2_b64 vcc, exec, s[20:21]
	s_cbranch_vccnz .LBB0_565
	s_mov_b64 s[6:7], s[56:57]
	s_waitcnt vmcnt(0)
	v_mov_b32_e32 v0, v228
	v_readlane_b32 s18, v254, 0
	v_mov_b32_e32 v11, v228
	s_cmpk_gt_i32 s18, 0x5ff
	v_readfirstlane_b32 s31, v11
	s_cbranch_scc1 .LBB0_565
	v_lshlrev_b32_e32 v0, 4, v11
	v_add_u32_e32 v1, 0x2000, v0
	v_ashrrev_i32_e32 v2, 31, v1
	v_lshrrev_b32_e32 v2, 22, v2
	v_add_u32_e32 v2, v1, v2
	v_ashrrev_i32_e32 v8, 10, v2
	v_mul_i32_i24_e32 v2, 0x400, v8
	v_sub_u32_e32 v1, v1, v2
	v_lshrrev_b32_e32 v2, 4, v1
	v_bitop3_b32 v1, v2, v1, 32 bitop3:0x6c
	v_ashrrev_i32_e32 v2, 31, v1
	v_lshrrev_b32_e32 v2, 26, v2
	v_add_u32_e32 v2, v1, v2
	v_lshlrev_b32_e32 v3, 3, v8
	v_ashrrev_i32_e32 v9, 6, v2
	v_and_b32_e32 v3, -16, v3
	v_add_u32_e32 v3, v9, v3
	v_and_b32_e32 v4, 3, v9
	s_mov_b32 s4, 0x1fffe0
	v_lshrrev_b32_e32 v5, 2, v3
	v_lshlrev_b32_e32 v6, 1, v3
	v_and_b32_e32 v2, 0xc0, v2
	v_and_or_b32 v4, v3, s4, v4
	v_and_b32_e32 v5, 4, v5
	v_and_b32_e32 v6, 24, v6
	v_sub_u32_e32 v1, v1, v2
	v_or3_b32 v4, v4, v5, v6
	v_lshlrev_b32_e32 v5, 5, v8
	v_ashrrev_i16_sdwa v1, v229, sext(v1) dst_sel:DWORD dst_unused:UNUSED_PAD src0_sel:DWORD src1_sel:BYTE_0
	v_and_b32_e32 v5, 32, v5
	v_bfe_i32 v10, v1, 0, 16
	v_add_lshl_u32 v1, v5, v10, 1
	v_lshl_add_u32 v130, v4, 11, v1
	v_lshl_add_u32 v132, v3, 11, v1
	v_bfe_i32 v1, v11, 27, 1
	v_lshrrev_b32_e32 v1, 22, v1
	v_add_u32_e32 v1, v0, v1
	s_load_dwordx2 s[6:7], s[6:7], 0x68
	v_and_b32_e32 v1, 0xfffffc00, v1
	v_sub_u32_e32 v0, v0, v1
	v_lshrrev_b32_e32 v1, 4, v0
	v_ashrrev_i32_e32 v2, 31, v11
	v_bitop3_b32 v0, v1, v0, 32 bitop3:0x6c
	v_lshrrev_b32_e32 v2, 26, v2
	v_ashrrev_i32_e32 v1, 31, v0
	v_add_u32_e32 v2, v11, v2
	s_waitcnt lgkmcnt(0)
	s_add_u32 s19, s6, 0xe300000
	v_lshrrev_b32_e32 v1, 26, v1
	v_ashrrev_i32_e32 v13, 6, v2
	s_addc_u32 s44, s7, 0
	v_add_u32_e32 v1, v0, v1
	v_lshlrev_b32_e32 v2, 3, v13
	s_add_u32 s45, s6, 0x200000
	v_ashrrev_i32_e32 v12, 6, v1
	v_and_b32_e32 v2, -16, v2
	s_addc_u32 s55, s7, 0
	v_add_u32_e32 v2, v12, v2
	v_and_b32_e32 v3, 3, v12
	s_ashr_i32 s57, s18, 31
	v_and_or_b32 v3, v2, s4, v3
	s_lshr_b32 s4, s57, 29
	s_add_i32 s4, s18, s4
	s_ashr_i32 s40, s31, 6
	s_ashr_i32 s5, s4, 3
	s_and_b32 s4, s4, -8
	s_ashr_i32 s41, s31, 8
	s_lshl_b32 s56, s40, 10
	s_sub_i32 s4, s18, s4
	s_cmp_lt_i32 s4, 0
	s_movk_i32 s24, 0xc1
	s_cselect_b32 s24, s24, 0xc0
	s_mul_i32 s4, s4, s24
	s_add_i32 s4, s4, s5
	s_mul_hi_i32 s5, s4, 0x2aaaaaab
	s_lshr_b32 s24, s5, 31
	s_ashr_i32 s5, s5, 5
	s_add_i32 s5, s5, s24
	s_lshl_b32 s24, s5, 3
	s_mulk_i32 s5, 0xc0
	s_sub_i32 s4, s4, s5
	s_bfe_u32 s5, s4, 0x3001c
	s_add_i32 s5, s4, s5
	s_sext_i32_i16 s25, s5
	s_and_b32 s5, s5, 0xfff8
	s_sub_i32 s4, s4, s5
	s_sext_i32_i16 s4, s4
	v_lshrrev_b32_e32 v4, 2, v2
	v_lshlrev_b32_e32 v5, 1, v2
	v_and_b32_e32 v1, 0xc0, v1
	s_lshr_b32 s30, s25, 3
	s_add_i32 s34, s24, s4
	v_and_b32_e32 v4, 4, v4
	v_and_b32_e32 v5, 24, v5
	v_sub_u32_e32 v0, v0, v1
	s_ashr_i32 s35, s34, 31
	s_bfe_i64 s[4:5], s[30:31], 0x100000
	v_or3_b32 v3, v3, v4, v5
	v_lshlrev_b32_e32 v4, 5, v13
	v_ashrrev_i16_sdwa v0, v229, sext(v0) dst_sel:DWORD dst_unused:UNUSED_PAD src0_sel:DWORD src1_sel:BYTE_0
	s_lshl_b64 s[24:25], s[34:35], 19
	s_lshl_b64 s[4:5], s[4:5], 19
	v_and_b32_e32 v4, 32, v4
	v_bfe_i32 v14, v0, 0, 16
	s_add_u32 s50, s45, s4
	v_add_lshl_u32 v0, v4, v14, 1
	s_addc_u32 s51, s55, s5
	s_add_i32 s4, s56, 0
	v_lshl_add_u32 v134, v3, 11, v0
	s_add_i32 m0, s4, 0x10000
	v_lshl_add_u32 v136, v2, 11, v0
	global_load_lds_dwordx4 v134, s[50:51]
	s_add_i32 m0, s4, 0x12000
	s_add_u32 s26, s50, 0x40000
	global_load_lds_dwordx4 v130, s[50:51]
	s_addc_u32 s27, s51, 0
	s_add_i32 m0, s4, 0x14000
	v_mov_b32_e32 v135, v32
	global_load_lds_dwordx4 v134, s[26:27]
	s_add_i32 m0, s4, 0x16000
	s_add_u32 s36, s19, s24
	s_addc_u32 s37, s44, s25
	s_add_i32 s5, s4, 0x2000
	global_load_lds_dwordx4 v130, s[26:27]
	s_mov_b32 m0, s4
	s_add_u32 s24, s36, 0x40000
	global_load_lds_dwordx4 v136, s[36:37]
	s_mov_b32 m0, s5
	s_addc_u32 s25, s37, 0
	s_add_i32 s52, s4, 0x4000
	global_load_lds_dwordx4 v132, s[36:37]
	s_mov_b32 m0, s52
	s_add_i32 s53, s4, 0x6000
	global_load_lds_dwordx4 v136, s[24:25]
	s_mov_b32 m0, s53
	v_mov_b32_e32 v131, v32
	global_load_lds_dwordx4 v132, s[24:25]
	v_mov_b32_e32 v137, v32
	v_mov_b32_e32 v133, v32
	s_cmp_eq_u32 s41, 1
	v_lshl_add_u64 v[6:7], s[50:51], 0, v[134:135]
	v_lshl_add_u64 v[4:5], s[50:51], 0, v[130:131]
	v_lshl_add_u64 v[0:1], s[36:37], 0, v[136:137]
	s_cselect_b64 s[24:25], -1, 0
	s_cmp_lg_u32 s41, 1
	v_lshl_add_u64 v[2:3], s[36:37], 0, v[132:133]
	s_cbranch_scc1 .LBB0_543
	s_barrier
	s_setprio 1

; #define PG8_STAGE(bufoff, gbase, voff) do { _Pragma("unroll") for (int _i = 0; _i < 2; ++_i) \
;         __builtin_amdgcn_global_load_lds((const unsigned*)((const char*)(gbase) + (voff)[_i]), (PG8_LAS unsigned*)(lds + (bufoff) + ldsw + _i * 8192), 16, 0, 0); } while (0)
; #define PG8_LDA(dst, b, h) do { _Pragma("unroll") for (int m = 0; m < 4; ++m) _Pragma("unroll") for (int k = 0; k < 2; ++k) dst[m][k] = *(const PG8_LAS bf16x8*)(lds + PG8_SA(b, h) + aoff + m * 2048 + k * 1024); } while (0)
; #define PG8_LDB(dst, b, h) do { _Pragma("unroll") for (int n = 0; n < 2; ++n) _Pragma("unroll") for (int k = 0; k < 2; ++k) dst[n][k] = *(const PG8_LAS bf16x8*)(lds + PG8_SB(b, h) + boff + n * 2048 + k * 1024); } while (0)
; #define PG8_MMA(ai, bj, At, Bt) do { __builtin_amdgcn_s_setprio(1); _Pragma("unroll") for (int m = 0; m < 4; ++m) _Pragma("unroll") for (int n = 0; n < 2; ++n) _Pragma("unroll") for (int k = 0; k < 2; ++k) \
;         acc[ai][bj][m][n] = __builtin_amdgcn_mfma_f32_16x16x32_bf16(Bt[n][k], At[m][k], acc[ai][bj][m][n], 0, 0, 0); __builtin_amdgcn_s_setprio(0); } while (0)
; #define PG8_WAIT_V(n) asm volatile("s_waitcnt vmcnt(" #n ")" ::: "memory")
; #define PG8_WAIT_L(n) asm volatile("s_waitcnt lgkmcnt(" #n ")" ::: "memory")
; #define PG8_BAR __builtin_amdgcn_s_barrier()
; #define PG8_SCHED __builtin_amdgcn_sched_barrier(0)
; template <class Epi, class Sched, bool ALIGN_EPI = false, bool SP2 = false>
; __device__ __forceinline__ void gemm_phase(PG8_LAS unsigned char* lds, const Gemm g, const Sched& S, const Epi& E) {
;     ...
;             PG8_LDB(B0, 0, 0); PG8_LDB(B1, 0, 1); PG8_SCHED; PG8_LDA(At, 0, 0); PG8_STAGE(PG8_SA(1, 1), a1 + hstep, voffA);
;             PG8_WAIT_V(8); PG8_WAIT_L(0); PG8_BAR; PG8_MMA(0, 0, At, B0); PG8_MMA(0, 1, At, B1); PG8_BAR; PG8_SCHED;
;             PG8_LDA(At, 0, 1); PG8_STAGE(PG8_SB(0, 0), b2, voffB); PG8_STAGE(PG8_SB(0, 1), b2 + hstep, voffB); PG8_STAGE(PG8_SA(0, 0), a2, voffA);
;             PG8_WAIT_V(8); PG8_WAIT_L(0); PG8_BAR; PG8_MMA(1, 0, At, B0); PG8_MMA(1, 1, At, B1); PG8_BAR; PG8_SCHED;
.LBB0_549:
	s_add_u32 s36, vcc_lo, 0xfffc0080
	s_addc_u32 s37, vcc_hi, -1
	s_add_i32 s66, 0, 0x10000
	s_cmp_eq_u32 s91, 12
	s_cselect_b32 s51, s35, s37
	s_cselect_b32 s50, s62, s36
	v_add_u32_e32 v148, s66, v150
	s_cselect_b32 s37, s43, s65
	s_cselect_b32 s36, s63, s64
	s_add_i32 s68, 0, 0x14000
	ds_read_b128 v[144:147], v148
	ds_read_b128 v[162:165], v148 offset:1024
	ds_read_b128 v[166:169], v148 offset:2048
	ds_read_b128 v[170:173], v148 offset:3072
	v_add_u32_e32 v148, s68, v150
	ds_read_b128 v[174:177], v148
	ds_read_b128 v[178:181], v148 offset:1024
	ds_read_b128 v[182:185], v148 offset:2048
	ds_read_b128 v[186:189], v148 offset:3072
	v_lshl_add_u64 v[148:149], vcc, 0, v[140:141]
	s_add_i32 m0, s4, 0xc000
	ds_read_b128 v[190:193], v161
	ds_read_b128 v[204:207], v161 offset:1024
	ds_read_b128 v[208:211], v161 offset:2048
	ds_read_b128 v[212:215], v161 offset:3072
	ds_read_b128 v[216:219], v161 offset:4096
	ds_read_b128 v[220:223], v161 offset:5120
	ds_read_b128 v[224:227], v161 offset:6144
	ds_read_b128 v[238:241], v161 offset:7168
	global_load_lds_dwordx4 v[148:149], off
	v_lshl_add_u64 v[148:149], vcc, 0, v[142:143]
	s_add_i32 m0, s4, 0xe000
	s_nop 0
	global_load_lds_dwordx4 v[148:149], off
	s_waitcnt vmcnt(8)
	s_waitcnt lgkmcnt(0)
	s_barrier
	s_waitcnt lgkmcnt(0)
	v_mfma_f32_16x16x32_bf16 v[126:129], v[144:147], v[190:193], v[126:129]
	v_mfma_f32_16x16x32_bf16 v[118:121], v[166:169], v[190:193], v[118:121]
	v_mfma_f32_16x16x32_bf16 v[110:113], v[144:147], v[208:211], v[110:113]
	v_mfma_f32_16x16x32_bf16 v[102:105], v[166:169], v[208:211], v[102:105]
	v_mfma_f32_16x16x32_bf16 v[94:97], v[144:147], v[216:219], v[94:97]
	v_mfma_f32_16x16x32_bf16 v[86:89], v[166:169], v[216:219], v[86:89]
	v_mfma_f32_16x16x32_bf16 v[78:81], v[144:147], v[224:227], v[78:81]
	v_mfma_f32_16x16x32_bf16 v[70:73], v[166:169], v[224:227], v[70:73]
	v_mfma_f32_16x16x32_bf16 v[126:129], v[162:165], v[204:207], v[126:129]
	v_mfma_f32_16x16x32_bf16 v[118:121], v[170:173], v[204:207], v[118:121]
	v_mfma_f32_16x16x32_bf16 v[110:113], v[162:165], v[212:215], v[110:113]
	v_mfma_f32_16x16x32_bf16 v[102:105], v[170:173], v[212:215], v[102:105]
	v_mfma_f32_16x16x32_bf16 v[94:97], v[162:165], v[220:223], v[94:97]
	v_mfma_f32_16x16x32_bf16 v[86:89], v[170:173], v[220:223], v[86:89]
	v_mfma_f32_16x16x32_bf16 v[78:81], v[162:165], v[238:241], v[78:81]
	v_mfma_f32_16x16x32_bf16 v[70:73], v[170:173], v[238:241], v[70:73]
	v_mfma_f32_16x16x32_bf16 v[122:125], v[174:177], v[190:193], v[122:125]
	v_mfma_f32_16x16x32_bf16 v[114:117], v[182:185], v[190:193], v[114:117]
	v_mfma_f32_16x16x32_bf16 v[106:109], v[174:177], v[208:211], v[106:109]
	v_mfma_f32_16x16x32_bf16 v[98:101], v[182:185], v[208:211], v[98:101]
	v_mfma_f32_16x16x32_bf16 v[90:93], v[174:177], v[216:219], v[90:93]
	v_mfma_f32_16x16x32_bf16 v[82:85], v[182:185], v[216:219], v[82:85]
	v_mfma_f32_16x16x32_bf16 v[74:77], v[174:177], v[224:227], v[74:77]
	v_mfma_f32_16x16x32_bf16 v[66:69], v[182:185], v[224:227], v[66:69]
	v_mfma_f32_16x16x32_bf16 v[122:125], v[178:181], v[204:207], v[122:125]
	v_mfma_f32_16x16x32_bf16 v[114:117], v[186:189], v[204:207], v[114:117]
	v_mfma_f32_16x16x32_bf16 v[106:109], v[178:181], v[212:215], v[106:109]
	v_mfma_f32_16x16x32_bf16 v[98:101], v[186:189], v[212:215], v[98:101]
	v_mfma_f32_16x16x32_bf16 v[90:93], v[178:181], v[220:223], v[90:93]
	v_mfma_f32_16x16x32_bf16 v[82:85], v[186:189], v[220:223], v[82:85]
	v_mfma_f32_16x16x32_bf16 v[74:77], v[178:181], v[238:241], v[74:77]
	v_mfma_f32_16x16x32_bf16 v[66:69], v[186:189], v[238:241], v[66:69]
	s_barrier
	s_add_i32 s66, s66, s56
	v_lshl_add_u64 v[148:149], s[36:37], 0, v[134:135]
	s_mov_b32 m0, s66
	ds_read_b128 v[190:193], v161 offset:16384
	ds_read_b128 v[204:207], v161 offset:17408
	ds_read_b128 v[208:211], v161 offset:18432
	ds_read_b128 v[212:215], v161 offset:19456
	ds_read_b128 v[216:219], v161 offset:20480
	ds_read_b128 v[220:223], v161 offset:21504
	ds_read_b128 v[224:227], v161 offset:22528
	ds_read_b128 v[238:241], v161 offset:23552
	global_load_lds_dwordx4 v[148:149], off
	s_add_i32 m0, s66, 0x2000
	s_add_u32 s66, s36, 0x40000
	v_lshl_add_u64 v[242:243], s[36:37], 0, v[130:131]
	s_addc_u32 s67, s37, 0
	s_add_i32 s68, s68, s56
	global_load_lds_dwordx4 v[242:243], off
	v_lshl_add_u64 v[244:245], s[66:67], 0, v[134:135]
	s_mov_b32 m0, s68
	v_lshl_add_u64 v[246:247], s[50:51], 0, v[132:133]
	global_load_lds_dwordx4 v[244:245], off
	v_lshl_add_u64 v[244:245], s[66:67], 0, v[130:131]
	s_add_i32 m0, s68, 0x2000
	s_nop 0
	global_load_lds_dwordx4 v[244:245], off
	v_lshl_add_u64 v[244:245], s[50:51], 0, v[136:137]
	s_mov_b32 m0, s4
	s_nop 0
	global_load_lds_dwordx4 v[244:245], off
	s_mov_b32 m0, s5
	s_nop 0
	global_load_lds_dwordx4 v[246:247], off
	s_waitcnt vmcnt(8)
	s_waitcnt lgkmcnt(0)
	s_barrier
; #define PG8_STAGE(bufoff, gbase, voff) do { _Pragma("unroll") for (int _i = 0; _i < 2; ++_i) \
;         __builtin_amdgcn_global_load_lds((const unsigned*)((const char*)(gbase) + (voff)[_i]), (PG8_LAS unsigned*)(lds + (bufoff) + ldsw + _i * 8192), 16, 0, 0); } while (0)
; #define PG8_LDA(dst, b, h) do { _Pragma("unroll") for (int m = 0; m < 4; ++m) _Pragma("unroll") for (int k = 0; k < 2; ++k) dst[m][k] = *(const PG8_LAS bf16x8*)(lds + PG8_SA(b, h) + aoff + m * 2048 + k * 1024); } while (0)
; #define PG8_LDB(dst, b, h) do { _Pragma("unroll") for (int n = 0; n < 2; ++n) _Pragma("unroll") for (int k = 0; k < 2; ++k) dst[n][k] = *(const PG8_LAS bf16x8*)(lds + PG8_SB(b, h) + boff + n * 2048 + k * 1024); } while (0)
; #define PG8_MMA(ai, bj, At, Bt) do { __builtin_amdgcn_s_setprio(1); _Pragma("unroll") for (int m = 0; m < 4; ++m) _Pragma("unroll") for (int n = 0; n < 2; ++n) _Pragma("unroll") for (int k = 0; k < 2; ++k) \
;         acc[ai][bj][m][n] = __builtin_amdgcn_mfma_f32_16x16x32_bf16(Bt[n][k], At[m][k], acc[ai][bj][m][n], 0, 0, 0); __builtin_amdgcn_s_setprio(0); } while (0)
; #define PG8_WAIT_V(n) asm volatile("s_waitcnt vmcnt(" #n ")" ::: "memory")
; #define PG8_WAIT_L(n) asm volatile("s_waitcnt lgkmcnt(" #n ")" ::: "memory")
; #define PG8_BAR __builtin_amdgcn_s_barrier()
; #define PG8_SCHED __builtin_amdgcn_sched_barrier(0)
; template <class Epi, class Sched, bool ALIGN_EPI = false, bool SP2 = false>
; __device__ __forceinline__ void gemm_phase(PG8_LAS unsigned char* lds, const Gemm g, const Sched& S, const Epi& E) {
;     ...
;             PG8_WAIT_V(8); PG8_WAIT_L(0); PG8_BAR; PG8_MMA(1, 0, At, B0); PG8_MMA(1, 1, At, B1); PG8_BAR; PG8_SCHED;
;             PG8_LDB(B0, 1, 0); PG8_LDB(B1, 1, 1); PG8_SCHED; PG8_LDA(At, 1, 0); PG8_STAGE(PG8_SA(0, 1), a2 + hstep, voffA);
;             PG8_WAIT_V(8); PG8_WAIT_L(0); PG8_BAR; PG8_MMA(0, 0, At, B0); PG8_MMA(0, 1, At, B1); PG8_BAR; PG8_SCHED;
	s_waitcnt lgkmcnt(0)
	v_mfma_f32_16x16x32_bf16 v[62:65], v[144:147], v[190:193], v[62:65]
	v_mfma_f32_16x16x32_bf16 v[54:57], v[166:169], v[190:193], v[54:57]
	v_mfma_f32_16x16x32_bf16 v[46:49], v[144:147], v[208:211], v[46:49]
	v_mfma_f32_16x16x32_bf16 v[38:41], v[166:169], v[208:211], v[38:41]
	v_mfma_f32_16x16x32_bf16 v[28:31], v[144:147], v[216:219], v[28:31]
	v_mfma_f32_16x16x32_bf16 v[20:23], v[166:169], v[216:219], v[20:23]
	v_mfma_f32_16x16x32_bf16 v[12:15], v[144:147], v[224:227], v[12:15]
	v_mfma_f32_16x16x32_bf16 v[4:7], v[166:169], v[224:227], v[4:7]
	v_mfma_f32_16x16x32_bf16 v[62:65], v[162:165], v[204:207], v[62:65]
	v_mfma_f32_16x16x32_bf16 v[54:57], v[170:173], v[204:207], v[54:57]
	v_mfma_f32_16x16x32_bf16 v[46:49], v[162:165], v[212:215], v[46:49]
	v_mfma_f32_16x16x32_bf16 v[38:41], v[170:173], v[212:215], v[38:41]
	v_mfma_f32_16x16x32_bf16 v[28:31], v[162:165], v[220:223], v[28:31]
	v_mfma_f32_16x16x32_bf16 v[20:23], v[170:173], v[220:223], v[20:23]
	v_mfma_f32_16x16x32_bf16 v[12:15], v[162:165], v[238:241], v[12:15]
	v_mfma_f32_16x16x32_bf16 v[4:7], v[170:173], v[238:241], v[4:7]
	v_mfma_f32_16x16x32_bf16 v[58:61], v[174:177], v[190:193], v[58:61]
	v_mfma_f32_16x16x32_bf16 v[50:53], v[182:185], v[190:193], v[50:53]
	v_mfma_f32_16x16x32_bf16 v[42:45], v[174:177], v[208:211], v[42:45]
	v_mfma_f32_16x16x32_bf16 v[34:37], v[182:185], v[208:211], v[34:37]
	v_mfma_f32_16x16x32_bf16 v[24:27], v[174:177], v[216:219], v[24:27]
	v_mfma_f32_16x16x32_bf16 v[16:19], v[182:185], v[216:219], v[16:19]
	v_mfma_f32_16x16x32_bf16 v[8:11], v[174:177], v[224:227], v[8:11]
	v_mfma_f32_16x16x32_bf16 v[0:3], v[182:185], v[224:227], v[0:3]
	v_mfma_f32_16x16x32_bf16 v[58:61], v[178:181], v[204:207], v[58:61]
	v_mfma_f32_16x16x32_bf16 v[50:53], v[186:189], v[204:207], v[50:53]
	v_mfma_f32_16x16x32_bf16 v[42:45], v[178:181], v[212:215], v[42:45]
	v_mfma_f32_16x16x32_bf16 v[34:37], v[186:189], v[212:215], v[34:37]
	v_mfma_f32_16x16x32_bf16 v[24:27], v[178:181], v[220:223], v[24:27]
	v_mfma_f32_16x16x32_bf16 v[16:19], v[186:189], v[220:223], v[16:19]
	v_mfma_f32_16x16x32_bf16 v[8:11], v[178:181], v[238:241], v[8:11]
	v_mfma_f32_16x16x32_bf16 v[0:3], v[186:189], v[238:241], v[0:3]
	s_barrier
	s_add_i32 s66, 0, 0x18000
	s_add_i32 s67, 0, 0x1c000
	v_add_u32_e32 v170, s66, v150
	v_add_u32_e32 v186, s67, v150
	ds_read_b128 v[144:147], v170
	ds_read_b128 v[162:165], v170 offset:1024
	ds_read_b128 v[166:169], v170 offset:2048
	ds_read_b128 v[170:173], v170 offset:3072
	ds_read_b128 v[174:177], v186
	ds_read_b128 v[178:181], v186 offset:1024
	ds_read_b128 v[182:185], v186 offset:2048
	ds_read_b128 v[186:189], v186 offset:3072
	s_add_u32 s50, s50, 0x40000
	s_addc_u32 s51, s51, 0
	s_mov_b32 m0, s52
	v_lshl_add_u64 v[248:249], s[50:51], 0, v[136:137]
	ds_read_b128 v[190:193], v161 offset:32768
	ds_read_b128 v[204:207], v161 offset:33792
	ds_read_b128 v[208:211], v161 offset:34816
	ds_read_b128 v[212:215], v161 offset:35840
	ds_read_b128 v[216:219], v161 offset:36864
	ds_read_b128 v[220:223], v161 offset:37888
	ds_read_b128 v[224:227], v161 offset:38912
	ds_read_b128 v[238:241], v161 offset:39936
	global_load_lds_dwordx4 v[248:249], off
	v_lshl_add_u64 v[248:249], s[50:51], 0, v[132:133]
	s_mov_b32 m0, s53
	s_nop 0
	global_load_lds_dwordx4 v[248:249], off
	s_waitcnt vmcnt(8)
	s_waitcnt lgkmcnt(0)
	s_barrier
	s_waitcnt lgkmcnt(0)
	v_mfma_f32_16x16x32_bf16 v[126:129], v[144:147], v[190:193], v[126:129]
	v_mfma_f32_16x16x32_bf16 v[118:121], v[166:169], v[190:193], v[118:121]
	v_mfma_f32_16x16x32_bf16 v[110:113], v[144:147], v[208:211], v[110:113]
	v_mfma_f32_16x16x32_bf16 v[102:105], v[166:169], v[208:211], v[102:105]
	v_mfma_f32_16x16x32_bf16 v[94:97], v[144:147], v[216:219], v[94:97]
	v_mfma_f32_16x16x32_bf16 v[86:89], v[166:169], v[216:219], v[86:89]
	v_mfma_f32_16x16x32_bf16 v[78:81], v[144:147], v[224:227], v[78:81]
	v_mfma_f32_16x16x32_bf16 v[70:73], v[166:169], v[224:227], v[70:73]
	v_mfma_f32_16x16x32_bf16 v[126:129], v[162:165], v[204:207], v[126:129]
	v_mfma_f32_16x16x32_bf16 v[118:121], v[170:173], v[204:207], v[118:121]
	v_mfma_f32_16x16x32_bf16 v[110:113], v[162:165], v[212:215], v[110:113]
	v_mfma_f32_16x16x32_bf16 v[102:105], v[170:173], v[212:215], v[102:105]
	v_mfma_f32_16x16x32_bf16 v[94:97], v[162:165], v[220:223], v[94:97]
	v_mfma_f32_16x16x32_bf16 v[86:89], v[170:173], v[220:223], v[86:89]
	v_mfma_f32_16x16x32_bf16 v[78:81], v[162:165], v[238:241], v[78:81]
	v_mfma_f32_16x16x32_bf16 v[70:73], v[170:173], v[238:241], v[70:73]
	v_mfma_f32_16x16x32_bf16 v[122:125], v[174:177], v[190:193], v[122:125]
	v_mfma_f32_16x16x32_bf16 v[114:117], v[182:185], v[190:193], v[114:117]
	v_mfma_f32_16x16x32_bf16 v[106:109], v[174:177], v[208:211], v[106:109]
	v_mfma_f32_16x16x32_bf16 v[98:101], v[182:185], v[208:211], v[98:101]
	v_mfma_f32_16x16x32_bf16 v[90:93], v[174:177], v[216:219], v[90:93]
	v_mfma_f32_16x16x32_bf16 v[82:85], v[182:185], v[216:219], v[82:85]
	v_mfma_f32_16x16x32_bf16 v[74:77], v[174:177], v[224:227], v[74:77]
	v_mfma_f32_16x16x32_bf16 v[66:69], v[182:185], v[224:227], v[66:69]
	v_mfma_f32_16x16x32_bf16 v[122:125], v[178:181], v[204:207], v[122:125]
	v_mfma_f32_16x16x32_bf16 v[114:117], v[186:189], v[204:207], v[114:117]
	v_mfma_f32_16x16x32_bf16 v[106:109], v[178:181], v[212:215], v[106:109]
	v_mfma_f32_16x16x32_bf16 v[98:101], v[186:189], v[212:215], v[98:101]
	v_mfma_f32_16x16x32_bf16 v[90:93], v[178:181], v[220:223], v[90:93]
	v_mfma_f32_16x16x32_bf16 v[82:85], v[186:189], v[220:223], v[82:85]
	v_mfma_f32_16x16x32_bf16 v[74:77], v[178:181], v[238:241], v[74:77]
	v_mfma_f32_16x16x32_bf16 v[66:69], v[186:189], v[238:241], v[66:69]
	s_barrier
; #define PG8_STAGE(bufoff, gbase, voff) do { _Pragma("unroll") for (int _i = 0; _i < 2; ++_i) \
;         __builtin_amdgcn_global_load_lds((const unsigned*)((const char*)(gbase) + (voff)[_i]), (PG8_LAS unsigned*)(lds + (bufoff) + ldsw + _i * 8192), 16, 0, 0); } while (0)
; #define PG8_LDA(dst, b, h) do { _Pragma("unroll") for (int m = 0; m < 4; ++m) _Pragma("unroll") for (int k = 0; k < 2; ++k) dst[m][k] = *(const PG8_LAS bf16x8*)(lds + PG8_SA(b, h) + aoff + m * 2048 + k * 1024); } while (0)
; #define PG8_MMA(ai, bj, At, Bt) do { __builtin_amdgcn_s_setprio(1); _Pragma("unroll") for (int m = 0; m < 4; ++m) _Pragma("unroll") for (int n = 0; n < 2; ++n) _Pragma("unroll") for (int k = 0; k < 2; ++k) \
;         acc[ai][bj][m][n] = __builtin_amdgcn_mfma_f32_16x16x32_bf16(Bt[n][k], At[m][k], acc[ai][bj][m][n], 0, 0, 0); __builtin_amdgcn_s_setprio(0); } while (0)
; #define PG8_WAIT_V(n) asm volatile("s_waitcnt vmcnt(" #n ")" ::: "memory")
; #define PG8_WAIT_L(n) asm volatile("s_waitcnt lgkmcnt(" #n ")" ::: "memory")
; #define PG8_BAR __builtin_amdgcn_s_barrier()
; #define PG8_SCHED __builtin_amdgcn_sched_barrier(0)
; template <class Epi, class Sched, bool ALIGN_EPI = false, bool SP2 = false>
; __device__ __forceinline__ void gemm_phase(PG8_LAS unsigned char* lds, const Gemm g, const Sched& S, const Epi& E) {
;     ...
;             PG8_WAIT_V(8); PG8_WAIT_L(0); PG8_BAR; PG8_MMA(0, 0, At, B0); PG8_MMA(0, 1, At, B1); PG8_BAR; PG8_SCHED;
;             PG8_LDA(At, 1, 1); PG8_STAGE(PG8_SB(1, 0), b3, voffB); PG8_STAGE(PG8_SB(1, 1), b3 + hstep, voffB); PG8_STAGE(PG8_SA(1, 0), a3, voffA);
;             PG8_WAIT_V(8); PG8_WAIT_L(0); PG8_BAR; PG8_MMA(1, 0, At, B0); PG8_MMA(1, 1, At, B1); PG8_BAR; PG8_SCHED;
;     ...
;         if constexpr (ALIGN_EPI) { if (wr == 0) PG8_BAR; }
	s_add_i32 s50, s66, s56
	v_lshl_add_u64 v[148:149], v[148:149], 0, s[8:9]
	s_mov_b32 m0, s50
	ds_read_b128 v[190:193], v161 offset:49152
	ds_read_b128 v[204:207], v161 offset:50176
	ds_read_b128 v[208:211], v161 offset:51200
	ds_read_b128 v[212:215], v161 offset:52224
	ds_read_b128 v[216:219], v161 offset:53248
	ds_read_b128 v[220:223], v161 offset:54272
	ds_read_b128 v[224:227], v161 offset:55296
	ds_read_b128 v[238:241], v161 offset:56320
	global_load_lds_dwordx4 v[148:149], off
	s_add_i32 m0, s50, 0x2000
	s_add_u32 s36, s36, 0x40080
	v_lshl_add_u64 v[148:149], v[242:243], 0, s[8:9]
	s_addc_u32 s37, s37, 0
	s_add_i32 s50, s67, s56
	global_load_lds_dwordx4 v[148:149], off
	v_lshl_add_u64 v[148:149], s[36:37], 0, v[134:135]
	s_mov_b32 m0, s50
	s_nop 0
	global_load_lds_dwordx4 v[148:149], off
	v_lshl_add_u64 v[148:149], s[36:37], 0, v[130:131]
	s_add_i32 m0, s50, 0x2000
	s_nop 0
	global_load_lds_dwordx4 v[148:149], off
	v_lshl_add_u64 v[148:149], v[244:245], 0, s[8:9]
	s_mov_b32 m0, s58
	s_nop 0
	global_load_lds_dwordx4 v[148:149], off
	v_lshl_add_u64 v[148:149], v[246:247], 0, s[8:9]
	s_mov_b32 m0, s59
	s_nop 0
	global_load_lds_dwordx4 v[148:149], off
	s_waitcnt vmcnt(8)
	s_waitcnt lgkmcnt(0)
	s_barrier
	s_waitcnt lgkmcnt(0)
	v_mfma_f32_16x16x32_bf16 v[62:65], v[144:147], v[190:193], v[62:65]
	v_mfma_f32_16x16x32_bf16 v[54:57], v[166:169], v[190:193], v[54:57]
	v_mfma_f32_16x16x32_bf16 v[46:49], v[144:147], v[208:211], v[46:49]
	v_mfma_f32_16x16x32_bf16 v[38:41], v[166:169], v[208:211], v[38:41]
	v_mfma_f32_16x16x32_bf16 v[28:31], v[144:147], v[216:219], v[28:31]
	v_mfma_f32_16x16x32_bf16 v[20:23], v[166:169], v[216:219], v[20:23]
	v_mfma_f32_16x16x32_bf16 v[12:15], v[144:147], v[224:227], v[12:15]
	v_mfma_f32_16x16x32_bf16 v[4:7], v[166:169], v[224:227], v[4:7]
	v_mfma_f32_16x16x32_bf16 v[62:65], v[162:165], v[204:207], v[62:65]
	v_mfma_f32_16x16x32_bf16 v[54:57], v[170:173], v[204:207], v[54:57]
	v_mfma_f32_16x16x32_bf16 v[46:49], v[162:165], v[212:215], v[46:49]
	v_mfma_f32_16x16x32_bf16 v[38:41], v[170:173], v[212:215], v[38:41]
	v_mfma_f32_16x16x32_bf16 v[28:31], v[162:165], v[220:223], v[28:31]
	v_mfma_f32_16x16x32_bf16 v[20:23], v[170:173], v[220:223], v[20:23]
	v_mfma_f32_16x16x32_bf16 v[12:15], v[162:165], v[238:241], v[12:15]
	v_mfma_f32_16x16x32_bf16 v[4:7], v[170:173], v[238:241], v[4:7]
	v_mfma_f32_16x16x32_bf16 v[58:61], v[174:177], v[190:193], v[58:61]
	v_mfma_f32_16x16x32_bf16 v[50:53], v[182:185], v[190:193], v[50:53]
	v_mfma_f32_16x16x32_bf16 v[42:45], v[174:177], v[208:211], v[42:45]
	v_mfma_f32_16x16x32_bf16 v[34:37], v[182:185], v[208:211], v[34:37]
	v_mfma_f32_16x16x32_bf16 v[24:27], v[174:177], v[216:219], v[24:27]
	v_mfma_f32_16x16x32_bf16 v[16:19], v[182:185], v[216:219], v[16:19]
	v_mfma_f32_16x16x32_bf16 v[8:11], v[174:177], v[224:227], v[8:11]
	v_mfma_f32_16x16x32_bf16 v[0:3], v[182:185], v[224:227], v[0:3]
	v_mfma_f32_16x16x32_bf16 v[58:61], v[178:181], v[204:207], v[58:61]
	v_mfma_f32_16x16x32_bf16 v[50:53], v[186:189], v[204:207], v[50:53]
	v_mfma_f32_16x16x32_bf16 v[42:45], v[178:181], v[212:215], v[42:45]
	v_mfma_f32_16x16x32_bf16 v[34:37], v[186:189], v[212:215], v[34:37]
	v_mfma_f32_16x16x32_bf16 v[24:27], v[178:181], v[220:223], v[24:27]
	v_mfma_f32_16x16x32_bf16 v[16:19], v[186:189], v[220:223], v[16:19]
	v_mfma_f32_16x16x32_bf16 v[8:11], v[178:181], v[238:241], v[8:11]
	v_mfma_f32_16x16x32_bf16 v[0:3], v[186:189], v[238:241], v[0:3]
	s_barrier
	s_add_i32 s91, s91, 2
	s_add_u32 vcc_lo, vcc_lo, 0x100
	s_addc_u32 vcc_hi, vcc_hi, 0
	s_add_u32 s64, s64, 0x100
	s_addc_u32 s65, s65, 0
	s_cmp_gt_u32 s91, 13
	s_cbranch_scc0 .LBB0_549
	s_and_b64 vcc, exec, s[30:31]
	s_cbranch_vccz .LBB0_552
	s_barrier

; #define PG8_STAGE(bufoff, gbase, voff) do { _Pragma("unroll") for (int _i = 0; _i < 2; ++_i) \
;         __builtin_amdgcn_global_load_lds((const unsigned*)((const char*)(gbase) + (voff)[_i]), (PG8_LAS unsigned*)(lds + (bufoff) + ldsw + _i * 8192), 16, 0, 0); } while (0)
; #define PG8_WAIT_V(n) asm volatile("s_waitcnt vmcnt(" #n ")" ::: "memory")
; #define PG8_BAR __builtin_amdgcn_s_barrier()
; template <class Epi, class Sched, bool ALIGN_EPI = false, bool SP2 = false>
; __device__ __forceinline__ void gemm_phase(PG8_LAS unsigned char* lds, const Gemm g, const Sched& S, const Epi& E) {
;     int tid_ = threadIdx.x; asm volatile("" : "+v"(tid_)); const int tid = tid_, wid = __builtin_amdgcn_readfirstlane(tid >> 6), lane = tid & 63, wr = wid >> 2, wc = wid & 3, fr = lane & 15, fq = lane >> 4;
;     const int K = g.K, nt = K / BK;
;     unsigned voffA[2], voffB[2];
; #pragma unroll
;     for (int i = 0; i < 2; ++i) { int R, C; stage_rc(tid * 16 + i * 8192, R, C); const int Rb = Epi::PERM ? ((R & ~31) + perm32(R & 31)) : R;
;         voffA[i] = (unsigned)(R * K + C) * 2u; voffB[i] = (unsigned)(Rb * K + C) * 2u; }
;     ...
;     const char* cA = (const char*)g.A + (size_t)cur.pm * tstep; const char* cB = (const char*)g.Bt + (size_t)cur.pn * tstep;
;     S.a_ready(cur);
;     if constexpr (SP2) {
;         PG8_STAGE(PG8_SB(0, 0), cB, voffB); PG8_STAGE(PG8_SB(0, 1), cB + hstep, voffB); PG8_STAGE(PG8_SA(0, 0), cA, voffA); PG8_STAGE(PG8_SA(0, 1), cA + hstep, voffA);
;         if (wr == 1) PG8_BAR;
;         PG8_WAIT_V(2); PG8_BAR;
;         PG8_STAGE(PG8_SB(1, 0), cB + kstep, voffB); PG8_STAGE(PG8_SA(1, 0), cA + kstep, voffA); PG8_STAGE(PG8_SB(1, 1), cB + hstep + kstep, voffB);
;         PG8_WAIT_V(6); PG8_BAR;
.LBB0_815:
	v_bfe_i32 v1, v195, 27, 1
	v_lshlrev_b32_e32 v3, 4, v195
	v_lshrrev_b32_e32 v1, 22, v1
	v_add_u32_e32 v1, v3, v1
	v_and_b32_e32 v1, 0xfffffc00, v1
	v_sub_u32_e32 v1, v3, v1
	v_lshrrev_b32_e32 v2, 4, v1
	v_ashrrev_i32_e32 v0, 31, v195
	v_bitop3_b32 v1, v2, v1, 32 bitop3:0x6c
	s_and_b64 s[28:29], s[70:71], exec
	s_movk_i32 s7, 0x800
	v_lshrrev_b32_e32 v0, 26, v0
	v_ashrrev_i32_e32 v4, 31, v1
	s_cselect_b32 s40, s7, 0x400
	s_ashr_i32 s44, s94, 6
	v_add_u32_e32 v0, v195, v0
	v_lshrrev_b32_e32 v4, 26, v4
	s_ashr_i32 s35, s94, 8
	v_ashrrev_i32_e32 v0, 6, v0
	v_add_u32_e32 v4, v1, v4
	s_xor_b32 s56, s17, 11
	s_lshl_b32 s17, s40, 8
	s_lshl_b32 s45, s44, 10
	v_lshlrev_b32_e32 v2, 3, v0
	v_ashrrev_i32_e32 v5, 6, v4
	v_and_b32_e32 v4, 0xc0, v4
	s_waitcnt lgkmcnt(0)
	s_add_u32 s49, s22, 0xa300000
	v_and_b32_e32 v2, 0x7ffffff0, v2
	v_lshlrev_b32_e32 v0, 5, v0
	v_sub_u32_e32 v1, v1, v4
	s_addc_u32 s52, s23, 0
	v_and_b32_e32 v0, 32, v0
	v_ashrrev_i16_sdwa v1, v229, sext(v1) dst_sel:DWORD dst_unused:UNUSED_PAD src0_sel:DWORD src1_sel:BYTE_0
	v_add_lshl_u32 v2, v5, v2, s56
	s_add_u32 s53, s22, 0xe00000
	v_bfe_i32 v1, v1, 0, 16
	v_or_b32_e32 v4, v2, v0
	v_add_u32_e32 v3, 0x2000, v3
	s_addc_u32 s55, s23, 0
	s_add_i32 s6, s18, s6
	v_add_lshl_u32 v92, v4, v1, 1
	v_ashrrev_i32_e32 v4, 31, v3
	s_ashr_i32 s7, s6, 31
	v_lshrrev_b32_e32 v4, 22, v4
	s_lshr_b32 s7, s7, 27
	v_add_u32_e32 v4, v3, v4
	s_add_i32 s7, s6, s7
	v_ashrrev_i32_e32 v4, 10, v4
	s_ashr_i32 s18, s7, 5
	s_and_b32 s7, s7, 0xffe0
	v_mul_i32_i24_e32 v5, 0x400, v4
	s_sub_i32 s6, s6, s7
	v_sub_u32_e32 v3, v3, v5
	s_bfe_i32 s7, s6, 0x80000
	v_lshrrev_b32_e32 v5, 4, v3
	s_bfe_u32 s7, s7, 0x3000c
	v_bitop3_b32 v5, v5, v3, 32 bitop3:0x6c
	v_lshlrev_b32_e32 v3, 3, v4
	s_add_i32 s7, s6, s7
	v_and_b32_e32 v6, 0x7ffffff0, v3
	v_ashrrev_i32_e32 v3, 31, v5
	s_bfe_i32 s19, s7, 0x80000
	s_and_b32 s7, s7, 0xf8
	v_lshrrev_b32_e32 v3, 26, v3
	s_sub_i32 s6, s6, s7
	v_add_u32_e32 v7, v5, v3
	s_lshl_b32 s18, s18, 3
	s_sext_i32_i16 s19, s19
	s_sext_i32_i8 s6, s6
	v_ashrrev_i32_e32 v8, 6, v7
	v_lshlrev_b32_e32 v3, 5, v4
	v_and_b32_e32 v4, 0xc0, v7
	s_lshr_b32 s34, s19, 3
	s_add_i32 s18, s18, s6
	v_sub_u32_e32 v4, v5, v4
	v_add_lshl_u32 v5, v8, v6, s56
	s_ashr_i32 s19, s18, 31
	s_add_i32 s56, s56, 9
	s_bfe_i64 s[6:7], s[34:35], 0x100000
	s_lshl_b64 s[28:29], s[18:19], s56
	s_lshl_b64 s[6:7], s[6:7], s56
	s_add_u32 s6, s53, s6
	s_addc_u32 s7, s55, s7
	s_add_i32 s19, s45, 0
	v_and_b32_e32 v3, 32, v3
	v_ashrrev_i16_sdwa v4, v229, sext(v4) dst_sel:DWORD dst_unused:UNUSED_PAD src0_sel:DWORD src1_sel:BYTE_0
	s_add_i32 m0, s19, 0x10000
	v_bfe_i32 v4, v4, 0, 16
	v_or_b32_e32 v6, v5, v3
	global_load_lds_dwordx4 v92, s[6:7]
	s_add_i32 m0, s19, 0x12000
	v_add_lshl_u32 v94, v6, v4, 1
	s_add_u32 s36, s6, s17
	global_load_lds_dwordx4 v94, s[6:7]
	s_addc_u32 s37, s7, 0
	s_add_i32 m0, s19, 0x14000
	s_nop 0
	global_load_lds_dwordx4 v92, s[36:37]
	s_add_i32 m0, s19, 0x16000
	s_add_u32 s30, s49, s28
	s_addc_u32 s31, s52, s29
	s_add_i32 s57, s19, 0x2000
	global_load_lds_dwordx4 v94, s[36:37]
	s_mov_b32 m0, s19
	s_add_u32 s28, s30, s17
	global_load_lds_dwordx4 v92, s[30:31]
	s_mov_b32 m0, s57
	s_addc_u32 s29, s31, 0
	s_add_i32 s58, s19, 0x4000
	global_load_lds_dwordx4 v94, s[30:31]
	s_mov_b32 m0, s58
	s_add_i32 s59, s19, 0x6000
	global_load_lds_dwordx4 v92, s[28:29]
	s_mov_b32 m0, s59
	s_cmp_lg_u32 s35, 1
	global_load_lds_dwordx4 v94, s[28:29]
	s_load_dwordx2 s[28:29], s[24:25], 0x8
	s_cbranch_scc1 .LBB0_817
	s_barrier
	s_setprio 1

; #define PG8_STAGE(bufoff, gbase, voff) do { _Pragma("unroll") for (int _i = 0; _i < 2; ++_i) \
;         __builtin_amdgcn_global_load_lds((const unsigned*)((const char*)(gbase) + (voff)[_i]), (PG8_LAS unsigned*)(lds + (bufoff) + ldsw + _i * 8192), 16, 0, 0); } while (0)
; #define PG8_LDA(dst, b, h) do { _Pragma("unroll") for (int m = 0; m < 4; ++m) _Pragma("unroll") for (int k = 0; k < 2; ++k) dst[m][k] = *(const PG8_LAS bf16x8*)(lds + PG8_SA(b, h) + aoff + m * 2048 + k * 1024); } while (0)
; #define PG8_LDB(dst, b, h) do { _Pragma("unroll") for (int n = 0; n < 2; ++n) _Pragma("unroll") for (int k = 0; k < 2; ++k) dst[n][k] = *(const PG8_LAS bf16x8*)(lds + PG8_SB(b, h) + boff + n * 2048 + k * 1024); } while (0)
; #define PG8_MMA(ai, bj, At, Bt) do { __builtin_amdgcn_s_setprio(1); _Pragma("unroll") for (int m = 0; m < 4; ++m) _Pragma("unroll") for (int n = 0; n < 2; ++n) _Pragma("unroll") for (int k = 0; k < 2; ++k) \
;         acc[ai][bj][m][n] = __builtin_amdgcn_mfma_f32_16x16x32_bf16(Bt[n][k], At[m][k], acc[ai][bj][m][n], 0, 0, 0); __builtin_amdgcn_s_setprio(0); } while (0)
; #define PG8_WAIT_V(n) asm volatile("s_waitcnt vmcnt(" #n ")" ::: "memory")
; #define PG8_WAIT_L(n) asm volatile("s_waitcnt lgkmcnt(" #n ")" ::: "memory")
; #define PG8_BAR __builtin_amdgcn_s_barrier()
; #define PG8_SCHED __builtin_amdgcn_sched_barrier(0)
; template <class Epi, class Sched, bool ALIGN_EPI = false, bool SP2 = false>
; __device__ __forceinline__ void gemm_phase(PG8_LAS unsigned char* lds, const Gemm g, const Sched& S, const Epi& E) {
;     ...
;             PG8_LDB(B0, 0, 0); PG8_LDB(B1, 0, 1); PG8_SCHED; PG8_LDA(At, 0, 0); PG8_STAGE(PG8_SA(1, 1), a1 + hstep, voffA);
;             PG8_WAIT_V(8); PG8_WAIT_L(0); PG8_BAR; PG8_MMA(0, 0, At, B0); PG8_MMA(0, 1, At, B1); PG8_BAR; PG8_SCHED;
;             PG8_LDA(At, 0, 1); PG8_STAGE(PG8_SB(0, 0), b2, voffB); PG8_STAGE(PG8_SB(0, 1), b2 + hstep, voffB); PG8_STAGE(PG8_SA(0, 0), a2, voffA);
;             PG8_WAIT_V(8); PG8_WAIT_L(0); PG8_BAR; PG8_MMA(1, 0, At, B0); PG8_MMA(1, 1, At, B1); PG8_BAR; PG8_SCHED;
.LBB0_826:
	s_add_i32 s68, s46, 2
	s_add_u32 s69, s30, vcc_lo
	s_addc_u32 s47, s31, vcc_hi
	s_add_u32 s70, s6, vcc_lo
	s_addc_u32 s71, s7, vcc_hi
	s_add_i32 s72, 0, 0x10000
	s_cmp_eq_u32 s63, s46
	s_cselect_b32 s47, s37, s47
	s_cselect_b32 s46, s66, s69
	v_add_u32_e32 v33, s72, v106
	s_cselect_b32 s71, s35, s71
	s_cselect_b32 s70, s67, s70
	s_add_i32 s69, 0, 0x14000
	ds_read_b128 v[116:119], v33
	ds_read_b128 v[148:151], v33 offset:1024
	ds_read_b128 v[152:155], v33 offset:2048
	ds_read_b128 v[156:159], v33 offset:3072
	v_add_u32_e32 v33, s69, v106
	ds_read_b128 v[160:163], v33
	ds_read_b128 v[164:167], v33 offset:1024
	ds_read_b128 v[168:171], v33 offset:2048
	ds_read_b128 v[172:175], v33 offset:3072
	v_lshl_add_u64 v[220:221], s[30:31], 0, v[104:105]
	s_add_i32 m0, s19, 0xc000
	ds_read_b128 v[176:179], v107
	ds_read_b128 v[180:183], v107 offset:1024
	ds_read_b128 v[184:187], v107 offset:2048
	ds_read_b128 v[188:191], v107 offset:3072
	ds_read_b128 v[204:207], v107 offset:4096
	ds_read_b128 v[208:211], v107 offset:5120
	ds_read_b128 v[212:215], v107 offset:6144
	ds_read_b128 v[216:219], v107 offset:7168
	global_load_lds_dwordx4 v[220:221], off
	v_lshl_add_u64 v[220:221], s[30:31], 0, v[34:35]
	s_add_i32 m0, s19, 0xe000
	s_nop 0
	global_load_lds_dwordx4 v[220:221], off
	s_waitcnt vmcnt(8)
	s_waitcnt lgkmcnt(0)
	s_barrier
	s_waitcnt lgkmcnt(0)
	v_mfma_f32_16x16x32_bf16 v[144:147], v[116:119], v[176:179], v[144:147]
	v_mfma_f32_16x16x32_bf16 v[140:143], v[152:155], v[176:179], v[140:143]
	v_mfma_f32_16x16x32_bf16 v[128:131], v[116:119], v[184:187], v[128:131]
	v_mfma_f32_16x16x32_bf16 v[124:127], v[152:155], v[184:187], v[124:127]
	v_mfma_f32_16x16x32_bf16 v[108:111], v[116:119], v[204:207], v[108:111]
	v_mfma_f32_16x16x32_bf16 v[96:99], v[152:155], v[204:207], v[96:99]
	v_mfma_f32_16x16x32_bf16 v[80:83], v[116:119], v[212:215], v[80:83]
	v_mfma_f32_16x16x32_bf16 v[76:79], v[152:155], v[212:215], v[76:79]
	v_mfma_f32_16x16x32_bf16 v[144:147], v[148:151], v[180:183], v[144:147]
	v_mfma_f32_16x16x32_bf16 v[140:143], v[156:159], v[180:183], v[140:143]
	v_mfma_f32_16x16x32_bf16 v[128:131], v[148:151], v[188:191], v[128:131]
	v_mfma_f32_16x16x32_bf16 v[124:127], v[156:159], v[188:191], v[124:127]
	v_mfma_f32_16x16x32_bf16 v[108:111], v[148:151], v[208:211], v[108:111]
	v_mfma_f32_16x16x32_bf16 v[96:99], v[156:159], v[208:211], v[96:99]
	v_mfma_f32_16x16x32_bf16 v[80:83], v[148:151], v[216:219], v[80:83]
	v_mfma_f32_16x16x32_bf16 v[76:79], v[156:159], v[216:219], v[76:79]
	v_mfma_f32_16x16x32_bf16 v[136:139], v[160:163], v[176:179], v[136:139]
	v_mfma_f32_16x16x32_bf16 v[132:135], v[168:171], v[176:179], v[132:135]
	v_mfma_f32_16x16x32_bf16 v[120:123], v[160:163], v[184:187], v[120:123]
	v_mfma_f32_16x16x32_bf16 v[112:115], v[168:171], v[184:187], v[112:115]
	v_mfma_f32_16x16x32_bf16 v[88:91], v[160:163], v[204:207], v[88:91]
	v_mfma_f32_16x16x32_bf16 v[84:87], v[168:171], v[204:207], v[84:87]
	v_mfma_f32_16x16x32_bf16 v[72:75], v[160:163], v[212:215], v[72:75]
	v_mfma_f32_16x16x32_bf16 v[68:71], v[168:171], v[212:215], v[68:71]
	v_mfma_f32_16x16x32_bf16 v[136:139], v[164:167], v[180:183], v[136:139]
	v_mfma_f32_16x16x32_bf16 v[132:135], v[172:175], v[180:183], v[132:135]
	v_mfma_f32_16x16x32_bf16 v[120:123], v[164:167], v[188:191], v[120:123]
	v_mfma_f32_16x16x32_bf16 v[112:115], v[172:175], v[188:191], v[112:115]
	v_mfma_f32_16x16x32_bf16 v[88:91], v[164:167], v[208:211], v[88:91]
	v_mfma_f32_16x16x32_bf16 v[84:87], v[172:175], v[208:211], v[84:87]
	v_mfma_f32_16x16x32_bf16 v[72:75], v[164:167], v[216:219], v[72:75]
	v_mfma_f32_16x16x32_bf16 v[68:71], v[172:175], v[216:219], v[68:71]
	s_barrier
	s_add_i32 s72, s72, s45
	v_lshl_add_u64 v[220:221], s[70:71], 0, v[92:93]
	s_mov_b32 m0, s72
	ds_read_b128 v[176:179], v107 offset:16384
	ds_read_b128 v[180:183], v107 offset:17408
	ds_read_b128 v[184:187], v107 offset:18432
	ds_read_b128 v[188:191], v107 offset:19456
	ds_read_b128 v[204:207], v107 offset:20480
	ds_read_b128 v[208:211], v107 offset:21504
	ds_read_b128 v[212:215], v107 offset:22528
	ds_read_b128 v[216:219], v107 offset:23552
	global_load_lds_dwordx4 v[220:221], off
	s_add_i32 m0, s72, 0x2000
	v_lshl_add_u64 v[222:223], s[70:71], 0, v[94:95]
	s_add_u32 s70, s70, s17
	s_addc_u32 s71, s71, 0
	s_add_i32 s69, s69, s45
	global_load_lds_dwordx4 v[222:223], off
	v_lshl_add_u64 v[224:225], s[70:71], 0, v[92:93]
	s_mov_b32 m0, s69
	v_lshl_add_u64 v[226:227], s[70:71], 0, v[94:95]
	global_load_lds_dwordx4 v[224:225], off
	s_add_i32 m0, s69, 0x2000
	v_lshl_add_u64 v[238:239], s[46:47], 0, v[92:93]
	global_load_lds_dwordx4 v[226:227], off
	s_mov_b32 m0, s19
	v_lshl_add_u64 v[240:241], s[46:47], 0, v[94:95]
	global_load_lds_dwordx4 v[238:239], off
	s_mov_b32 m0, s57
	s_nop 0
	global_load_lds_dwordx4 v[240:241], off
	s_waitcnt vmcnt(8)
	s_waitcnt lgkmcnt(0)
	s_barrier
; #define PG8_STAGE(bufoff, gbase, voff) do { _Pragma("unroll") for (int _i = 0; _i < 2; ++_i) \
;         __builtin_amdgcn_global_load_lds((const unsigned*)((const char*)(gbase) + (voff)[_i]), (PG8_LAS unsigned*)(lds + (bufoff) + ldsw + _i * 8192), 16, 0, 0); } while (0)
; #define PG8_LDA(dst, b, h) do { _Pragma("unroll") for (int m = 0; m < 4; ++m) _Pragma("unroll") for (int k = 0; k < 2; ++k) dst[m][k] = *(const PG8_LAS bf16x8*)(lds + PG8_SA(b, h) + aoff + m * 2048 + k * 1024); } while (0)
; #define PG8_LDB(dst, b, h) do { _Pragma("unroll") for (int n = 0; n < 2; ++n) _Pragma("unroll") for (int k = 0; k < 2; ++k) dst[n][k] = *(const PG8_LAS bf16x8*)(lds + PG8_SB(b, h) + boff + n * 2048 + k * 1024); } while (0)
; #define PG8_MMA(ai, bj, At, Bt) do { __builtin_amdgcn_s_setprio(1); _Pragma("unroll") for (int m = 0; m < 4; ++m) _Pragma("unroll") for (int n = 0; n < 2; ++n) _Pragma("unroll") for (int k = 0; k < 2; ++k) \
;         acc[ai][bj][m][n] = __builtin_amdgcn_mfma_f32_16x16x32_bf16(Bt[n][k], At[m][k], acc[ai][bj][m][n], 0, 0, 0); __builtin_amdgcn_s_setprio(0); } while (0)
; #define PG8_BAR __builtin_amdgcn_s_barrier()
; template <class Epi, class Sched, bool ALIGN_EPI = false, bool SP2 = false>
; __device__ __forceinline__ void gemm_phase(PG8_LAS unsigned char* lds, const Gemm g, const Sched& S, const Epi& E) {
;     ...
;             if constexpr (SP2) {
;             PG8_LDB(B0, 0, 0); PG8_LDB(B1, 0, 1); PG8_SCHED; PG8_LDA(At, 0, 0); PG8_STAGE(PG8_SA(1, 1), a1 + hstep, voffA);
;             PG8_WAIT_V(8); PG8_WAIT_L(0); PG8_BAR; PG8_MMA(0, 0, At, B0); PG8_MMA(0, 1, At, B1); PG8_BAR; PG8_SCHED;
;             PG8_LDA(At, 0, 1); PG8_STAGE(PG8_SB(0, 0), b2, voffB); PG8_STAGE(PG8_SB(0, 1), b2 + hstep, voffB); PG8_STAGE(PG8_SA(0, 0), a2, voffA);
;             PG8_WAIT_V(8); PG8_WAIT_L(0); PG8_BAR; PG8_MMA(1, 0, At, B0); PG8_MMA(1, 1, At, B1); PG8_BAR; PG8_SCHED;
;             PG8_LDB(B0, 1, 0); PG8_LDB(B1, 1, 1); PG8_SCHED; PG8_LDA(At, 1, 0); PG8_STAGE(PG8_SA(0, 1), a2 + hstep, voffA);
;             PG8_WAIT_V(8); PG8_WAIT_L(0); PG8_BAR; PG8_MMA(0, 0, At, B0); PG8_MMA(0, 1, At, B1); PG8_BAR; PG8_SCHED;
;             PG8_LDA(At, 1, 1); PG8_STAGE(PG8_SB(1, 0), b3, voffB); PG8_STAGE(PG8_SB(1, 1), b3 + hstep, voffB); PG8_STAGE(PG8_SA(1, 0), a3, voffA);
;             PG8_WAIT_V(8); PG8_WAIT_L(0); PG8_BAR; PG8_MMA(1, 0, At, B0); PG8_MMA(1, 1, At, B1); PG8_BAR; PG8_SCHED;
	s_waitcnt lgkmcnt(0)
	v_mfma_f32_16x16x32_bf16 v[64:67], v[116:119], v[176:179], v[64:67]
	v_mfma_f32_16x16x32_bf16 v[60:63], v[152:155], v[176:179], v[60:63]
	v_mfma_f32_16x16x32_bf16 v[48:51], v[116:119], v[184:187], v[48:51]
	v_mfma_f32_16x16x32_bf16 v[44:47], v[152:155], v[184:187], v[44:47]
	v_mfma_f32_16x16x32_bf16 v[28:31], v[116:119], v[204:207], v[28:31]
	v_mfma_f32_16x16x32_bf16 v[24:27], v[152:155], v[204:207], v[24:27]
	v_mfma_f32_16x16x32_bf16 v[12:15], v[116:119], v[212:215], v[12:15]
	v_mfma_f32_16x16x32_bf16 v[8:11], v[152:155], v[212:215], v[8:11]
	v_mfma_f32_16x16x32_bf16 v[64:67], v[148:151], v[180:183], v[64:67]
	v_mfma_f32_16x16x32_bf16 v[60:63], v[156:159], v[180:183], v[60:63]
	v_mfma_f32_16x16x32_bf16 v[48:51], v[148:151], v[188:191], v[48:51]
	v_mfma_f32_16x16x32_bf16 v[44:47], v[156:159], v[188:191], v[44:47]
	v_mfma_f32_16x16x32_bf16 v[28:31], v[148:151], v[208:211], v[28:31]
	v_mfma_f32_16x16x32_bf16 v[24:27], v[156:159], v[208:211], v[24:27]
	v_mfma_f32_16x16x32_bf16 v[12:15], v[148:151], v[216:219], v[12:15]
	v_mfma_f32_16x16x32_bf16 v[8:11], v[156:159], v[216:219], v[8:11]
	v_mfma_f32_16x16x32_bf16 v[56:59], v[160:163], v[176:179], v[56:59]
	v_mfma_f32_16x16x32_bf16 v[52:55], v[168:171], v[176:179], v[52:55]
	v_mfma_f32_16x16x32_bf16 v[40:43], v[160:163], v[184:187], v[40:43]
	v_mfma_f32_16x16x32_bf16 v[36:39], v[168:171], v[184:187], v[36:39]
	v_mfma_f32_16x16x32_bf16 v[20:23], v[160:163], v[204:207], v[20:23]
	v_mfma_f32_16x16x32_bf16 v[16:19], v[168:171], v[204:207], v[16:19]
	v_mfma_f32_16x16x32_bf16 v[4:7], v[160:163], v[212:215], v[4:7]
	v_mfma_f32_16x16x32_bf16 v[0:3], v[168:171], v[212:215], v[0:3]
	v_mfma_f32_16x16x32_bf16 v[56:59], v[164:167], v[180:183], v[56:59]
	v_mfma_f32_16x16x32_bf16 v[52:55], v[172:175], v[180:183], v[52:55]
	v_mfma_f32_16x16x32_bf16 v[40:43], v[164:167], v[188:191], v[40:43]
	v_mfma_f32_16x16x32_bf16 v[36:39], v[172:175], v[188:191], v[36:39]
	v_mfma_f32_16x16x32_bf16 v[20:23], v[164:167], v[208:211], v[20:23]
	v_mfma_f32_16x16x32_bf16 v[16:19], v[172:175], v[208:211], v[16:19]
	v_mfma_f32_16x16x32_bf16 v[4:7], v[164:167], v[216:219], v[4:7]
	v_mfma_f32_16x16x32_bf16 v[0:3], v[172:175], v[216:219], v[0:3]
	s_barrier
	s_add_i32 s69, 0, 0x18000
	v_add_u32_e32 v33, s69, v106
	s_add_i32 s70, 0, 0x1c000
	ds_read_b128 v[116:119], v33
	ds_read_b128 v[148:151], v33 offset:1024
	ds_read_b128 v[152:155], v33 offset:2048
	ds_read_b128 v[156:159], v33 offset:3072
	v_add_u32_e32 v33, s70, v106
	ds_read_b128 v[160:163], v33
	ds_read_b128 v[164:167], v33 offset:1024
	ds_read_b128 v[168:171], v33 offset:2048
	ds_read_b128 v[172:175], v33 offset:3072
	s_add_u32 s46, s46, s17
	s_addc_u32 s47, s47, 0
	s_mov_b32 m0, s58
	v_lshl_add_u64 v[242:243], s[46:47], 0, v[92:93]
	ds_read_b128 v[176:179], v107 offset:32768
	ds_read_b128 v[180:183], v107 offset:33792
	ds_read_b128 v[184:187], v107 offset:34816
	ds_read_b128 v[188:191], v107 offset:35840
	ds_read_b128 v[204:207], v107 offset:36864
	ds_read_b128 v[208:211], v107 offset:37888
	ds_read_b128 v[212:215], v107 offset:38912
	ds_read_b128 v[216:219], v107 offset:39936
	global_load_lds_dwordx4 v[242:243], off
	v_lshl_add_u64 v[242:243], s[46:47], 0, v[94:95]
	s_mov_b32 m0, s59
	s_nop 0
	global_load_lds_dwordx4 v[242:243], off
	s_waitcnt vmcnt(8)
	s_waitcnt lgkmcnt(0)
	s_barrier
	s_waitcnt lgkmcnt(0)
	v_mfma_f32_16x16x32_bf16 v[144:147], v[116:119], v[176:179], v[144:147]
	v_mfma_f32_16x16x32_bf16 v[140:143], v[152:155], v[176:179], v[140:143]
	v_mfma_f32_16x16x32_bf16 v[128:131], v[116:119], v[184:187], v[128:131]
	v_mfma_f32_16x16x32_bf16 v[124:127], v[152:155], v[184:187], v[124:127]
	v_mfma_f32_16x16x32_bf16 v[108:111], v[116:119], v[204:207], v[108:111]
	v_mfma_f32_16x16x32_bf16 v[96:99], v[152:155], v[204:207], v[96:99]
	v_mfma_f32_16x16x32_bf16 v[80:83], v[116:119], v[212:215], v[80:83]
	v_mfma_f32_16x16x32_bf16 v[76:79], v[152:155], v[212:215], v[76:79]
	v_mfma_f32_16x16x32_bf16 v[144:147], v[148:151], v[180:183], v[144:147]
	v_mfma_f32_16x16x32_bf16 v[140:143], v[156:159], v[180:183], v[140:143]
	v_mfma_f32_16x16x32_bf16 v[128:131], v[148:151], v[188:191], v[128:131]
	v_mfma_f32_16x16x32_bf16 v[124:127], v[156:159], v[188:191], v[124:127]
	v_mfma_f32_16x16x32_bf16 v[108:111], v[148:151], v[208:211], v[108:111]
	v_mfma_f32_16x16x32_bf16 v[96:99], v[156:159], v[208:211], v[96:99]
	v_mfma_f32_16x16x32_bf16 v[80:83], v[148:151], v[216:219], v[80:83]
	v_mfma_f32_16x16x32_bf16 v[76:79], v[156:159], v[216:219], v[76:79]
	v_mfma_f32_16x16x32_bf16 v[136:139], v[160:163], v[176:179], v[136:139]
	v_mfma_f32_16x16x32_bf16 v[132:135], v[168:171], v[176:179], v[132:135]
	v_mfma_f32_16x16x32_bf16 v[120:123], v[160:163], v[184:187], v[120:123]
	v_mfma_f32_16x16x32_bf16 v[112:115], v[168:171], v[184:187], v[112:115]
	v_mfma_f32_16x16x32_bf16 v[88:91], v[160:163], v[204:207], v[88:91]
	v_mfma_f32_16x16x32_bf16 v[84:87], v[168:171], v[204:207], v[84:87]
	v_mfma_f32_16x16x32_bf16 v[72:75], v[160:163], v[212:215], v[72:75]
	v_mfma_f32_16x16x32_bf16 v[68:71], v[168:171], v[212:215], v[68:71]
	v_mfma_f32_16x16x32_bf16 v[136:139], v[164:167], v[180:183], v[136:139]
	v_mfma_f32_16x16x32_bf16 v[132:135], v[172:175], v[180:183], v[132:135]
	v_mfma_f32_16x16x32_bf16 v[120:123], v[164:167], v[188:191], v[120:123]
	v_mfma_f32_16x16x32_bf16 v[112:115], v[172:175], v[188:191], v[112:115]
	v_mfma_f32_16x16x32_bf16 v[88:91], v[164:167], v[208:211], v[88:91]
	v_mfma_f32_16x16x32_bf16 v[84:87], v[172:175], v[208:211], v[84:87]
	v_mfma_f32_16x16x32_bf16 v[72:75], v[164:167], v[216:219], v[72:75]
	v_mfma_f32_16x16x32_bf16 v[68:71], v[172:175], v[216:219], v[68:71]
	s_barrier
; #define PG8_STAGE(bufoff, gbase, voff) do { _Pragma("unroll") for (int _i = 0; _i < 2; ++_i) \
;         __builtin_amdgcn_global_load_lds((const unsigned*)((const char*)(gbase) + (voff)[_i]), (PG8_LAS unsigned*)(lds + (bufoff) + ldsw + _i * 8192), 16, 0, 0); } while (0)
; #define PG8_LDA(dst, b, h) do { _Pragma("unroll") for (int m = 0; m < 4; ++m) _Pragma("unroll") for (int k = 0; k < 2; ++k) dst[m][k] = *(const PG8_LAS bf16x8*)(lds + PG8_SA(b, h) + aoff + m * 2048 + k * 1024); } while (0)
; #define PG8_MMA(ai, bj, At, Bt) do { __builtin_amdgcn_s_setprio(1); _Pragma("unroll") for (int m = 0; m < 4; ++m) _Pragma("unroll") for (int n = 0; n < 2; ++n) _Pragma("unroll") for (int k = 0; k < 2; ++k) \
;         acc[ai][bj][m][n] = __builtin_amdgcn_mfma_f32_16x16x32_bf16(Bt[n][k], At[m][k], acc[ai][bj][m][n], 0, 0, 0); __builtin_amdgcn_s_setprio(0); } while (0)
; #define PG8_WAIT_V(n) asm volatile("s_waitcnt vmcnt(" #n ")" ::: "memory")
; #define PG8_WAIT_L(n) asm volatile("s_waitcnt lgkmcnt(" #n ")" ::: "memory")
; #define PG8_BAR __builtin_amdgcn_s_barrier()
; #define PG8_SCHED __builtin_amdgcn_sched_barrier(0)
; template <class Epi, class Sched, bool ALIGN_EPI = false, bool SP2 = false>
; __device__ __forceinline__ void gemm_phase(PG8_LAS unsigned char* lds, const Gemm g, const Sched& S, const Epi& E) {
;     ...
;             PG8_WAIT_V(8); PG8_WAIT_L(0); PG8_BAR; PG8_MMA(0, 0, At, B0); PG8_MMA(0, 1, At, B1); PG8_BAR; PG8_SCHED;
;             PG8_LDA(At, 1, 1); PG8_STAGE(PG8_SB(1, 0), b3, voffB); PG8_STAGE(PG8_SB(1, 1), b3 + hstep, voffB); PG8_STAGE(PG8_SA(1, 0), a3, voffA);
;             PG8_WAIT_V(8); PG8_WAIT_L(0); PG8_BAR; PG8_MMA(1, 0, At, B0); PG8_MMA(1, 1, At, B1); PG8_BAR; PG8_SCHED;
;     ...
;         if constexpr (ALIGN_EPI) { if (wr == 0) PG8_BAR; }
;         if constexpr (!Epi::AFTER_DRAIN) { E(acc, cur, wr, wc, fr, fq); S.done(cur); }
;         if (!has_next) break;
; #pragma unroll
;         for (int a = 0; a < 2; ++a)
; #pragma unroll
;             for (int b = 0; b < 2; ++b)
; #pragma unroll
;                 for (int m = 0; m < 4; ++m)
; #pragma unroll
;                     for (int n = 0; n < 2; ++n) acc[a][b][m][n] = (f32x4){0.f, 0.f, 0.f, 0.f};
;         cur = nxt; cA = nA; cB = nB; ++ui;
	s_add_i32 s46, s69, s45
	v_lshl_add_u64 v[220:221], v[220:221], 0, s[8:9]
	s_mov_b32 m0, s46
	ds_read_b128 v[176:179], v107 offset:49152
	ds_read_b128 v[180:183], v107 offset:50176
	ds_read_b128 v[184:187], v107 offset:51200
	ds_read_b128 v[188:191], v107 offset:52224
	ds_read_b128 v[204:207], v107 offset:53248
	ds_read_b128 v[208:211], v107 offset:54272
	ds_read_b128 v[212:215], v107 offset:55296
	ds_read_b128 v[216:219], v107 offset:56320
	global_load_lds_dwordx4 v[220:221], off
	v_lshl_add_u64 v[220:221], v[222:223], 0, s[8:9]
	s_add_i32 m0, s46, 0x2000
	s_add_i32 s46, s70, s45
	global_load_lds_dwordx4 v[220:221], off
	v_lshl_add_u64 v[220:221], v[224:225], 0, s[8:9]
	s_mov_b32 m0, s46
	s_nop 0
	global_load_lds_dwordx4 v[220:221], off
	v_lshl_add_u64 v[220:221], v[226:227], 0, s[8:9]
	s_add_i32 m0, s46, 0x2000
	s_nop 0
	global_load_lds_dwordx4 v[220:221], off
	v_lshl_add_u64 v[220:221], v[238:239], 0, s[8:9]
	s_mov_b32 m0, s60
	s_nop 0
	global_load_lds_dwordx4 v[220:221], off
	v_lshl_add_u64 v[220:221], v[240:241], 0, s[8:9]
	s_mov_b32 m0, s61
	s_nop 0
	global_load_lds_dwordx4 v[220:221], off
	s_waitcnt vmcnt(8)
	s_waitcnt lgkmcnt(0)
	s_barrier
	s_waitcnt lgkmcnt(0)
	v_mfma_f32_16x16x32_bf16 v[64:67], v[116:119], v[176:179], v[64:67]
	v_mfma_f32_16x16x32_bf16 v[60:63], v[152:155], v[176:179], v[60:63]
	v_mfma_f32_16x16x32_bf16 v[48:51], v[116:119], v[184:187], v[48:51]
	v_mfma_f32_16x16x32_bf16 v[44:47], v[152:155], v[184:187], v[44:47]
	v_mfma_f32_16x16x32_bf16 v[28:31], v[116:119], v[204:207], v[28:31]
	v_mfma_f32_16x16x32_bf16 v[24:27], v[152:155], v[204:207], v[24:27]
	v_mfma_f32_16x16x32_bf16 v[12:15], v[116:119], v[212:215], v[12:15]
	v_mfma_f32_16x16x32_bf16 v[8:11], v[152:155], v[212:215], v[8:11]
	v_mfma_f32_16x16x32_bf16 v[64:67], v[148:151], v[180:183], v[64:67]
	v_mfma_f32_16x16x32_bf16 v[60:63], v[156:159], v[180:183], v[60:63]
	v_mfma_f32_16x16x32_bf16 v[48:51], v[148:151], v[188:191], v[48:51]
	v_mfma_f32_16x16x32_bf16 v[44:47], v[156:159], v[188:191], v[44:47]
	v_mfma_f32_16x16x32_bf16 v[28:31], v[148:151], v[208:211], v[28:31]
	v_mfma_f32_16x16x32_bf16 v[24:27], v[156:159], v[208:211], v[24:27]
	v_mfma_f32_16x16x32_bf16 v[12:15], v[148:151], v[216:219], v[12:15]
	v_mfma_f32_16x16x32_bf16 v[8:11], v[156:159], v[216:219], v[8:11]
	v_mfma_f32_16x16x32_bf16 v[56:59], v[160:163], v[176:179], v[56:59]
	v_mfma_f32_16x16x32_bf16 v[52:55], v[168:171], v[176:179], v[52:55]
	v_mfma_f32_16x16x32_bf16 v[40:43], v[160:163], v[184:187], v[40:43]
	v_mfma_f32_16x16x32_bf16 v[36:39], v[168:171], v[184:187], v[36:39]
	v_mfma_f32_16x16x32_bf16 v[20:23], v[160:163], v[204:207], v[20:23]
	v_mfma_f32_16x16x32_bf16 v[16:19], v[168:171], v[204:207], v[16:19]
	v_mfma_f32_16x16x32_bf16 v[4:7], v[160:163], v[212:215], v[4:7]
	v_mfma_f32_16x16x32_bf16 v[0:3], v[168:171], v[212:215], v[0:3]
	v_mfma_f32_16x16x32_bf16 v[56:59], v[164:167], v[180:183], v[56:59]
	v_mfma_f32_16x16x32_bf16 v[52:55], v[172:175], v[180:183], v[52:55]
	v_mfma_f32_16x16x32_bf16 v[40:43], v[164:167], v[188:191], v[40:43]
	v_mfma_f32_16x16x32_bf16 v[36:39], v[172:175], v[188:191], v[36:39]
	v_mfma_f32_16x16x32_bf16 v[20:23], v[164:167], v[208:211], v[20:23]
	v_mfma_f32_16x16x32_bf16 v[16:19], v[172:175], v[208:211], v[16:19]
	v_mfma_f32_16x16x32_bf16 v[4:7], v[164:167], v[216:219], v[4:7]
	v_mfma_f32_16x16x32_bf16 v[0:3], v[172:175], v[216:219], v[0:3]
	s_barrier
	s_add_u32 vcc_lo, vcc_lo, 0x100
	s_addc_u32 vcc_hi, vcc_hi, 0
	v_lshl_add_u64 v[104:105], v[104:105], 0, s[10:11]
	v_lshl_add_u64 v[34:35], v[34:35], 0, s[10:11]
	s_cmp_ge_u32 s68, s62
	s_mov_b32 s46, s68
	s_cbranch_scc0 .LBB0_826
	s_setprio 0
	s_andn2_b64 vcc, exec, s[42:43]
	s_cbranch_vccnz .LBB0_818
	v_mov_b32_e32 v0, 0
	s_mov_b32 s24, s34
	s_mov_b32 s18, s36
	s_mov_b64 s[6:7], s[50:51]
	s_mov_b64 s[30:31], s[90:91]
	s_mov_b32 s64, s65
	v_mov_b32_e32 v1, v0
	v_mov_b32_e32 v2, v0
	v_mov_b32_e32 v3, v0
	v_mov_b32_e32 v4, v0
	v_mov_b32_e32 v5, v0
	v_mov_b32_e32 v6, v0
	v_mov_b32_e32 v7, v0
	v_mov_b32_e32 v16, v0
	v_mov_b32_e32 v17, v0
	v_mov_b32_e32 v18, v0
	v_mov_b32_e32 v19, v0
	v_mov_b32_e32 v20, v0
	v_mov_b32_e32 v21, v0
	v_mov_b32_e32 v22, v0
	v_mov_b32_e32 v23, v0
	v_mov_b32_e32 v36, v0
	v_mov_b32_e32 v37, v0
	v_mov_b32_e32 v38, v0
	v_mov_b32_e32 v39, v0
	v_mov_b32_e32 v40, v0
	v_mov_b32_e32 v41, v0
	v_mov_b32_e32 v42, v0
	v_mov_b32_e32 v43, v0
	v_mov_b32_e32 v52, v0
	v_mov_b32_e32 v53, v0
	v_mov_b32_e32 v54, v0
	v_mov_b32_e32 v55, v0
	v_mov_b32_e32 v56, v0
	v_mov_b32_e32 v57, v0
	v_mov_b32_e32 v58, v0
	v_mov_b32_e32 v59, v0
	v_mov_b32_e32 v8, v0
	v_mov_b32_e32 v9, v0
	v_mov_b32_e32 v10, v0
	v_mov_b32_e32 v11, v0
	v_mov_b32_e32 v12, v0
	v_mov_b32_e32 v13, v0
	v_mov_b32_e32 v14, v0
	v_mov_b32_e32 v15, v0
	v_mov_b32_e32 v24, v0
	v_mov_b32_e32 v25, v0
	v_mov_b32_e32 v26, v0
	v_mov_b32_e32 v27, v0
	v_mov_b32_e32 v28, v0
	v_mov_b32_e32 v29, v0
	v_mov_b32_e32 v30, v0
	v_mov_b32_e32 v31, v0
	v_mov_b32_e32 v44, v0
	v_mov_b32_e32 v45, v0
	v_mov_b32_e32 v46, v0
	v_mov_b32_e32 v47, v0
	v_mov_b32_e32 v48, v0
	v_mov_b32_e32 v49, v0
	v_mov_b32_e32 v50, v0
	v_mov_b32_e32 v51, v0
	v_mov_b32_e32 v60, v0
	v_mov_b32_e32 v61, v0
	v_mov_b32_e32 v62, v0
	v_mov_b32_e32 v63, v0
	v_mov_b32_e32 v64, v0
	v_mov_b32_e32 v65, v0
	v_mov_b32_e32 v66, v0
	v_mov_b32_e32 v67, v0
	v_mov_b32_e32 v68, v0
	v_mov_b32_e32 v69, v0
	v_mov_b32_e32 v70, v0
	v_mov_b32_e32 v71, v0
	v_mov_b32_e32 v72, v0
	v_mov_b32_e32 v73, v0
	v_mov_b32_e32 v74, v0
	v_mov_b32_e32 v75, v0
	v_mov_b32_e32 v84, v0
	v_mov_b32_e32 v85, v0
	v_mov_b32_e32 v86, v0
	v_mov_b32_e32 v87, v0
	v_mov_b32_e32 v88, v0
	v_mov_b32_e32 v89, v0
	v_mov_b32_e32 v90, v0
	v_mov_b32_e32 v91, v0
	v_mov_b32_e32 v112, v0
	v_mov_b32_e32 v113, v0
	v_mov_b32_e32 v114, v0
	v_mov_b32_e32 v115, v0
	v_mov_b32_e32 v120, v0
	v_mov_b32_e32 v121, v0
	v_mov_b32_e32 v122, v0
	v_mov_b32_e32 v123, v0
	v_mov_b32_e32 v132, v0
	v_mov_b32_e32 v133, v0
	v_mov_b32_e32 v134, v0
	v_mov_b32_e32 v135, v0
	v_mov_b32_e32 v136, v0
	v_mov_b32_e32 v137, v0
	v_mov_b32_e32 v138, v0
	v_mov_b32_e32 v139, v0
	v_mov_b32_e32 v76, v0
	v_mov_b32_e32 v77, v0
	v_mov_b32_e32 v78, v0
	v_mov_b32_e32 v79, v0
	v_mov_b32_e32 v80, v0
	v_mov_b32_e32 v81, v0
	v_mov_b32_e32 v82, v0
	v_mov_b32_e32 v83, v0
	v_mov_b32_e32 v96, v0
	v_mov_b32_e32 v97, v0
	v_mov_b32_e32 v98, v0
	v_mov_b32_e32 v99, v0
	v_mov_b32_e32 v108, v0
	v_mov_b32_e32 v109, v0
	v_mov_b32_e32 v110, v0
	v_mov_b32_e32 v111, v0
	v_mov_b32_e32 v124, v0
	v_mov_b32_e32 v125, v0
	v_mov_b32_e32 v126, v0
	v_mov_b32_e32 v127, v0
	v_mov_b32_e32 v128, v0
	v_mov_b32_e32 v129, v0
	v_mov_b32_e32 v130, v0
	v_mov_b32_e32 v131, v0
	v_mov_b32_e32 v140, v0
	v_mov_b32_e32 v141, v0
	v_mov_b32_e32 v142, v0
	v_mov_b32_e32 v143, v0
	v_mov_b32_e32 v144, v0
	v_mov_b32_e32 v145, v0
	v_mov_b32_e32 v146, v0
	v_mov_b32_e32 v147, v0
	s_branch .LBB0_818

; #define PG8_WAIT_V(n) asm volatile("s_waitcnt vmcnt(" #n ")" ::: "memory")
; #define PG8_BAR __builtin_amdgcn_s_barrier()
; template <class Epi, class Sched, bool ALIGN_EPI = false, bool SP2 = false>
; __device__ __forceinline__ void gemm_phase(PG8_LAS unsigned char* lds, const Gemm g, const Sched& S, const Epi& E) {
;     ...
;     Unit cur, nxt; int ui = 0;
;     if (!S.next(0, cur)) return;
;     f32x4 acc[2][2][4][2];
; #pragma unroll
;     for (int a = 0; a < 2; ++a)
; #pragma unroll
;         for (int b = 0; b < 2; ++b)
; #pragma unroll
;             for (int m = 0; m < 4; ++m)
; #pragma unroll
;                 for (int n = 0; n < 2; ++n) acc[a][b][m][n] = (f32x4){0.f, 0.f, 0.f, 0.f};
;     bf16x8 At[4][2], B0[2][2], B1[2][2];
;     const char* cA = (const char*)g.A + (size_t)cur.pm * tstep; const char* cB = (const char*)g.Bt + (size_t)cur.pn * tstep;
;     S.a_ready(cur);
;     if constexpr (SP2) {
;         PG8_STAGE(PG8_SB(0, 0), cB, voffB); PG8_STAGE(PG8_SB(0, 1), cB + hstep, voffB); PG8_STAGE(PG8_SA(0, 0), cA, voffA); PG8_STAGE(PG8_SA(0, 1), cA + hstep, voffA);
;         if (wr == 1) PG8_BAR;
;         PG8_WAIT_V(2); PG8_BAR;
;         PG8_STAGE(PG8_SB(1, 0), cB + kstep, voffB); PG8_STAGE(PG8_SA(1, 0), cA + kstep, voffA); PG8_STAGE(PG8_SB(1, 1), cB + hstep + kstep, voffB);
;         PG8_WAIT_V(6); PG8_BAR;
;     } else {
;         PG8_STAGE(PG8_SB(0, 0), cB, voffB); PG8_STAGE(PG8_SA(0, 0), cA, voffA); PG8_STAGE(PG8_SB(0, 1), cB + hstep, voffB); PG8_STAGE(PG8_SA(0, 1), cA + hstep, voffA);
;         if (wr == 1) PG8_BAR;
;         PG8_WAIT_V(4); PG8_BAR;
;         PG8_STAGE(PG8_SB(1, 0), cB + kstep, voffB); PG8_STAGE(PG8_SA(1, 0), cA + kstep, voffA); PG8_STAGE(PG8_SB(1, 1), cB + hstep + kstep, voffB);
;         PG8_WAIT_V(6); PG8_BAR;
;     }
; __global__ void __launch_bounds__(NTHR, 2) fwd_mega(Args args_unused, int ph_lo, int ph_hi) {
;     ...
;         for (int rep_ = 0; rep_ < ((PROBE_DUP & 8) ? 2 : 1); ++rep_) if (IN(pb + 4)) { PH_BEGIN
;           pg8::Gemm g{(const bf16*)(ws + WS_XN), (const bf16*)(ws + WS_WGU), M, 2 * FF, D}; pg8::StaticOrder S; S.init(M, 2 * FF, G, bid);
;           pg8::EpiSwiGLU E{(bf16*)(ws + WS_ACT)};
;           pg8::gemm_phase<pg8::EpiSwiGLU, pg8::StaticOrder, true, true>(lds, g, S, E); }
.LBB0_926:
	s_cmp_le_i32 s58, s4
	s_cselect_b64 s[6:7], -1, 0
	s_cmp_lt_i32 s4, s59
	s_cselect_b64 s[4:5], -1, 0
	s_and_b64 s[6:7], s[6:7], s[4:5]
	s_andn2_b64 vcc, exec, s[6:7]
	s_cbranch_vccnz .LBB0_943
	s_mov_b64 s[18:19], s[56:57]
	s_waitcnt vmcnt(0)
	v_mov_b32_e32 v0, v228
	v_readlane_b32 s4, v254, 0
	v_mov_b32_e32 v14, v228
	s_cmpk_gt_i32 s4, 0x57f
	v_readfirstlane_b32 s23, v14
	s_cbranch_scc1 .LBB0_943
	v_lshlrev_b32_e32 v0, 4, v14
	v_add_u32_e32 v1, 0x2000, v0
	v_ashrrev_i32_e32 v2, 31, v1
	v_lshrrev_b32_e32 v2, 22, v2
	v_add_u32_e32 v2, v1, v2
	v_ashrrev_i32_e32 v8, 10, v2
	v_mul_i32_i24_e32 v2, 0x400, v8
	v_sub_u32_e32 v1, v1, v2
	v_lshrrev_b32_e32 v2, 4, v1
	v_bitop3_b32 v1, v2, v1, 32 bitop3:0x6c
	v_ashrrev_i32_e32 v2, 31, v1
	v_lshrrev_b32_e32 v2, 26, v2
	v_add_u32_e32 v2, v1, v2
	v_lshlrev_b32_e32 v3, 3, v8
	v_ashrrev_i32_e32 v9, 6, v2
	v_and_b32_e32 v3, -16, v3
	v_add_u32_e32 v3, v9, v3
	s_load_dwordx2 s[20:21], s[18:19], 0x68
	v_and_b32_e32 v4, 3, v9
	s_mov_b32 s18, 0x1fffe0
	v_lshrrev_b32_e32 v5, 2, v3
	v_lshlrev_b32_e32 v6, 1, v3
	v_and_b32_e32 v2, 0xc0, v2
	v_and_or_b32 v4, v3, s18, v4
	v_and_b32_e32 v5, 4, v5
	v_and_b32_e32 v6, 24, v6
	v_sub_u32_e32 v1, v1, v2
	v_or3_b32 v4, v4, v5, v6
	v_lshlrev_b32_e32 v5, 5, v8
	v_ashrrev_i16_sdwa v1, v229, sext(v1) dst_sel:DWORD dst_unused:UNUSED_PAD src0_sel:DWORD src1_sel:BYTE_0
	v_and_b32_e32 v5, 32, v5
	v_bfe_i32 v10, v1, 0, 16
	v_add_lshl_u32 v1, v5, v10, 1
	v_lshl_add_u32 v130, v4, 11, v1
	v_lshl_add_u32 v132, v3, 11, v1
	v_bfe_i32 v1, v14, 27, 1
	v_lshrrev_b32_e32 v1, 22, v1
	v_add_u32_e32 v1, v0, v1
	v_and_b32_e32 v1, 0xfffffc00, v1
	v_sub_u32_e32 v0, v0, v1
	v_lshrrev_b32_e32 v1, 4, v0
	v_ashrrev_i32_e32 v2, 31, v14
	v_bitop3_b32 v0, v1, v0, 32 bitop3:0x6c
	v_lshrrev_b32_e32 v2, 26, v2
	v_ashrrev_i32_e32 v1, 31, v0
	v_add_u32_e32 v2, v14, v2
	s_waitcnt lgkmcnt(0)
	s_add_u32 s5, s20, 0xe300000
	v_lshrrev_b32_e32 v1, 26, v1
	v_ashrrev_i32_e32 v12, 6, v2
	s_addc_u32 s17, s21, 0
	v_add_u32_e32 v1, v0, v1
	v_lshlrev_b32_e32 v2, 3, v12
	s_add_u32 s44, s20, 0x1200000
	v_ashrrev_i32_e32 v11, 6, v1
	v_and_b32_e32 v2, -16, v2
	s_addc_u32 s45, s21, 0
	v_add_u32_e32 v2, v11, v2
	v_and_b32_e32 v3, 3, v11
	s_ashr_i32 s50, s4, 31
	v_and_or_b32 v3, v2, s18, v3
	s_lshr_b32 s18, s50, 29
	s_add_i32 s18, s4, s18
	s_ashr_i32 s24, s23, 6
	s_ashr_i32 s19, s18, 3
	s_and_b32 s18, s18, -8
	s_ashr_i32 s25, s23, 8
	s_lshl_b32 s49, s24, 10
	s_sub_i32 s18, s4, s18
	s_cmp_lt_i32 s18, 0
	s_movk_i32 s22, 0xb1
	s_cselect_b32 s22, s22, 0xb0
	s_mul_i32 s18, s18, s22
	s_add_i32 s18, s18, s19
	s_mul_hi_i32 s19, s18, 0x2e8ba2e9
	s_lshr_b32 s22, s19, 31
	s_ashr_i32 s19, s19, 5
	s_add_i32 s19, s19, s22
	s_lshl_b32 s26, s19, 3
	s_mulk_i32 s19, 0xb0
	s_sub_i32 s18, s18, s19
	s_bfe_u32 s19, s18, 0x3001c
	s_add_i32 s19, s18, s19
	s_sext_i32_i16 s22, s19
	s_and_b32 s19, s19, 0xfff8
	s_sub_i32 s18, s18, s19
	s_sext_i32_i16 s18, s18
	v_lshrrev_b32_e32 v4, 2, v2
	v_lshlrev_b32_e32 v5, 1, v2
	v_and_b32_e32 v1, 0xc0, v1
	s_lshr_b32 s22, s22, 3
	s_add_i32 s34, s26, s18
	v_and_b32_e32 v4, 4, v4
	v_and_b32_e32 v5, 24, v5
	v_sub_u32_e32 v0, v0, v1
	s_ashr_i32 s35, s34, 31
	s_bfe_i64 s[26:27], s[22:23], 0x100000
	v_or3_b32 v3, v3, v4, v5
	v_lshlrev_b32_e32 v4, 5, v12
	v_ashrrev_i16_sdwa v0, v229, sext(v0) dst_sel:DWORD dst_unused:UNUSED_PAD src0_sel:DWORD src1_sel:BYTE_0
	s_lshl_b64 s[18:19], s[34:35], 19
	s_lshl_b64 s[26:27], s[26:27], 19
	v_and_b32_e32 v4, 32, v4
	v_bfe_i32 v13, v0, 0, 16
	s_add_u32 s42, s44, s26
	v_add_lshl_u32 v0, v4, v13, 1
	s_addc_u32 s43, s45, s27
	s_add_i32 s51, s49, 0
	v_lshl_add_u32 v134, v3, 11, v0
	s_add_i32 m0, s51, 0x10000
	v_lshl_add_u32 v136, v2, 11, v0
	global_load_lds_dwordx4 v134, s[42:43]
	s_add_i32 m0, s51, 0x12000
	s_add_u32 s26, s42, 0x40000
	global_load_lds_dwordx4 v130, s[42:43]
	s_addc_u32 s27, s43, 0
	s_add_i32 m0, s51, 0x14000
	v_mov_b32_e32 v135, v32
	global_load_lds_dwordx4 v134, s[26:27]
	s_add_i32 m0, s51, 0x16000
	s_add_u32 s36, s5, s18
	s_addc_u32 s37, s17, s19
	s_add_i32 s52, s51, 0x2000
	global_load_lds_dwordx4 v130, s[26:27]
	s_mov_b32 m0, s51
	s_add_u32 s18, s36, 0x40000
	global_load_lds_dwordx4 v136, s[36:37]
	s_mov_b32 m0, s52
	s_addc_u32 s19, s37, 0
	s_add_i32 s53, s51, 0x4000
	global_load_lds_dwordx4 v132, s[36:37]
	s_mov_b32 m0, s53
	s_add_i32 s55, s51, 0x6000
	global_load_lds_dwordx4 v136, s[18:19]
	s_mov_b32 m0, s55
	v_mov_b32_e32 v131, v32
	global_load_lds_dwordx4 v132, s[18:19]
	v_mov_b32_e32 v137, v32
	v_mov_b32_e32 v133, v32
	s_cmp_eq_u32 s25, 1
	v_lshl_add_u64 v[6:7], s[42:43], 0, v[134:135]
	v_lshl_add_u64 v[4:5], s[42:43], 0, v[130:131]
	v_lshl_add_u64 v[0:1], s[36:37], 0, v[136:137]
	s_cselect_b64 s[18:19], -1, 0
	s_cmp_lg_u32 s25, 1
	v_lshl_add_u64 v[2:3], s[36:37], 0, v[132:133]
	s_cbranch_scc1 .LBB0_930
	s_barrier
	s_setprio 1

; #define PG8_STAGE(bufoff, gbase, voff) do { _Pragma("unroll") for (int _i = 0; _i < 2; ++_i) \
;         __builtin_amdgcn_global_load_lds((const unsigned*)((const char*)(gbase) + (voff)[_i]), (PG8_LAS unsigned*)(lds + (bufoff) + ldsw + _i * 8192), 16, 0, 0); } while (0)
; #define PG8_LDA(dst, b, h) do { _Pragma("unroll") for (int m = 0; m < 4; ++m) _Pragma("unroll") for (int k = 0; k < 2; ++k) dst[m][k] = *(const PG8_LAS bf16x8*)(lds + PG8_SA(b, h) + aoff + m * 2048 + k * 1024); } while (0)
; #define PG8_LDB(dst, b, h) do { _Pragma("unroll") for (int n = 0; n < 2; ++n) _Pragma("unroll") for (int k = 0; k < 2; ++k) dst[n][k] = *(const PG8_LAS bf16x8*)(lds + PG8_SB(b, h) + boff + n * 2048 + k * 1024); } while (0)
; #define PG8_MMA(ai, bj, At, Bt) do { __builtin_amdgcn_s_setprio(1); _Pragma("unroll") for (int m = 0; m < 4; ++m) _Pragma("unroll") for (int n = 0; n < 2; ++n) _Pragma("unroll") for (int k = 0; k < 2; ++k) \
;         acc[ai][bj][m][n] = __builtin_amdgcn_mfma_f32_16x16x32_bf16(Bt[n][k], At[m][k], acc[ai][bj][m][n], 0, 0, 0); __builtin_amdgcn_s_setprio(0); } while (0)
; #define PG8_BAR __builtin_amdgcn_s_barrier()
; template <class Epi, class Sched, bool ALIGN_EPI = false, bool SP2 = false>
; __device__ __forceinline__ void gemm_phase(PG8_LAS unsigned char* lds, const Gemm g, const Sched& S, const Epi& E) {
;     ...
;             if constexpr (SP2) {
;             PG8_LDB(B0, 0, 0); PG8_LDB(B1, 0, 1); PG8_SCHED; PG8_LDA(At, 0, 0); PG8_STAGE(PG8_SA(1, 1), a1 + hstep, voffA);
;             PG8_WAIT_V(8); PG8_WAIT_L(0); PG8_BAR; PG8_MMA(0, 0, At, B0); PG8_MMA(0, 1, At, B1); PG8_BAR; PG8_SCHED;
;             PG8_LDA(At, 0, 1); PG8_STAGE(PG8_SB(0, 0), b2, voffB); PG8_STAGE(PG8_SB(0, 1), b2 + hstep, voffB); PG8_STAGE(PG8_SA(0, 0), a2, voffA);
;             PG8_WAIT_V(8); PG8_WAIT_L(0); PG8_BAR; PG8_MMA(1, 0, At, B0); PG8_MMA(1, 1, At, B1); PG8_BAR; PG8_SCHED;
;             PG8_LDB(B0, 1, 0); PG8_LDB(B1, 1, 1); PG8_SCHED; PG8_LDA(At, 1, 0); PG8_STAGE(PG8_SA(0, 1), a2 + hstep, voffA);
;             PG8_WAIT_V(8); PG8_WAIT_L(0); PG8_BAR; PG8_MMA(0, 0, At, B0); PG8_MMA(0, 1, At, B1); PG8_BAR; PG8_SCHED;
;             PG8_LDA(At, 1, 1); PG8_STAGE(PG8_SB(1, 0), b3, voffB); PG8_STAGE(PG8_SB(1, 1), b3 + hstep, voffB); PG8_STAGE(PG8_SA(1, 0), a3, voffA);
;             PG8_WAIT_V(8); PG8_WAIT_L(0); PG8_BAR; PG8_MMA(1, 0, At, B0); PG8_MMA(1, 1, At, B1); PG8_BAR; PG8_SCHED;
.LBB0_936:
	s_add_u32 s42, s36, 0xfffc0080
	s_addc_u32 s43, s37, -1
	s_add_i32 s64, 0, 0x10000
	s_cmp_eq_u32 s63, 12
	s_cselect_b32 s47, s27, s43
	s_cselect_b32 s46, s59, s42
	v_add_u32_e32 v145, s64, v142
	s_cselect_b32 s43, s25, s62
	s_cselect_b32 s42, s60, s61
	s_add_i32 s66, 0, 0x14000
	ds_read_b128 v[146:149], v145
	ds_read_b128 v[150:153], v145 offset:1024
	ds_read_b128 v[154:157], v145 offset:2048
	ds_read_b128 v[158:161], v145 offset:3072
	v_add_u32_e32 v145, s66, v142
	ds_read_b128 v[162:165], v145
	ds_read_b128 v[166:169], v145 offset:1024
	ds_read_b128 v[170:173], v145 offset:2048
	ds_read_b128 v[174:177], v145 offset:3072
	v_lshl_add_u64 v[220:221], s[36:37], 0, v[138:139]
	s_add_i32 m0, s51, 0xc000
	ds_read_b128 v[178:181], v144
	ds_read_b128 v[182:185], v144 offset:1024
	ds_read_b128 v[186:189], v144 offset:2048
	ds_read_b128 v[190:193], v144 offset:3072
	ds_read_b128 v[204:207], v144 offset:4096
	ds_read_b128 v[208:211], v144 offset:5120
	ds_read_b128 v[212:215], v144 offset:6144
	ds_read_b128 v[216:219], v144 offset:7168
	global_load_lds_dwordx4 v[220:221], off
	v_lshl_add_u64 v[220:221], s[36:37], 0, v[140:141]
	s_add_i32 m0, s51, 0xe000
	s_nop 0
	global_load_lds_dwordx4 v[220:221], off
	s_waitcnt vmcnt(8)
	s_waitcnt lgkmcnt(0)
	s_barrier
	s_waitcnt lgkmcnt(0)
	v_mfma_f32_16x16x32_bf16 v[126:129], v[146:149], v[178:181], v[126:129]
	v_mfma_f32_16x16x32_bf16 v[122:125], v[154:157], v[178:181], v[122:125]
	v_mfma_f32_16x16x32_bf16 v[110:113], v[146:149], v[186:189], v[110:113]
	v_mfma_f32_16x16x32_bf16 v[106:109], v[154:157], v[186:189], v[106:109]
	v_mfma_f32_16x16x32_bf16 v[94:97], v[146:149], v[204:207], v[94:97]
	v_mfma_f32_16x16x32_bf16 v[90:93], v[154:157], v[204:207], v[90:93]
	v_mfma_f32_16x16x32_bf16 v[78:81], v[146:149], v[212:215], v[78:81]
	v_mfma_f32_16x16x32_bf16 v[74:77], v[154:157], v[212:215], v[74:77]
	v_mfma_f32_16x16x32_bf16 v[126:129], v[150:153], v[182:185], v[126:129]
	v_mfma_f32_16x16x32_bf16 v[122:125], v[158:161], v[182:185], v[122:125]
	v_mfma_f32_16x16x32_bf16 v[110:113], v[150:153], v[190:193], v[110:113]
	v_mfma_f32_16x16x32_bf16 v[106:109], v[158:161], v[190:193], v[106:109]
	v_mfma_f32_16x16x32_bf16 v[94:97], v[150:153], v[208:211], v[94:97]
	v_mfma_f32_16x16x32_bf16 v[90:93], v[158:161], v[208:211], v[90:93]
	v_mfma_f32_16x16x32_bf16 v[78:81], v[150:153], v[216:219], v[78:81]
	v_mfma_f32_16x16x32_bf16 v[74:77], v[158:161], v[216:219], v[74:77]
	v_mfma_f32_16x16x32_bf16 v[118:121], v[162:165], v[178:181], v[118:121]
	v_mfma_f32_16x16x32_bf16 v[114:117], v[170:173], v[178:181], v[114:117]
	v_mfma_f32_16x16x32_bf16 v[102:105], v[162:165], v[186:189], v[102:105]
	v_mfma_f32_16x16x32_bf16 v[98:101], v[170:173], v[186:189], v[98:101]
	v_mfma_f32_16x16x32_bf16 v[86:89], v[162:165], v[204:207], v[86:89]
	v_mfma_f32_16x16x32_bf16 v[82:85], v[170:173], v[204:207], v[82:85]
	v_mfma_f32_16x16x32_bf16 v[70:73], v[162:165], v[212:215], v[70:73]
	v_mfma_f32_16x16x32_bf16 v[66:69], v[170:173], v[212:215], v[66:69]
	v_mfma_f32_16x16x32_bf16 v[118:121], v[166:169], v[182:185], v[118:121]
	v_mfma_f32_16x16x32_bf16 v[114:117], v[174:177], v[182:185], v[114:117]
	v_mfma_f32_16x16x32_bf16 v[102:105], v[166:169], v[190:193], v[102:105]
	v_mfma_f32_16x16x32_bf16 v[98:101], v[174:177], v[190:193], v[98:101]
	v_mfma_f32_16x16x32_bf16 v[86:89], v[166:169], v[208:211], v[86:89]
	v_mfma_f32_16x16x32_bf16 v[82:85], v[174:177], v[208:211], v[82:85]
	v_mfma_f32_16x16x32_bf16 v[70:73], v[166:169], v[216:219], v[70:73]
	v_mfma_f32_16x16x32_bf16 v[66:69], v[174:177], v[216:219], v[66:69]
	s_barrier
	s_add_i32 s64, s64, s49
	v_lshl_add_u64 v[220:221], s[42:43], 0, v[134:135]
	s_mov_b32 m0, s64
	ds_read_b128 v[178:181], v144 offset:16384
	ds_read_b128 v[182:185], v144 offset:17408
	ds_read_b128 v[186:189], v144 offset:18432
	ds_read_b128 v[190:193], v144 offset:19456
	ds_read_b128 v[204:207], v144 offset:20480
	ds_read_b128 v[208:211], v144 offset:21504
	ds_read_b128 v[212:215], v144 offset:22528
	ds_read_b128 v[216:219], v144 offset:23552
	global_load_lds_dwordx4 v[220:221], off
	s_add_i32 m0, s64, 0x2000
	s_add_u32 s64, s42, 0x40000
	v_lshl_add_u64 v[222:223], s[42:43], 0, v[130:131]
	s_addc_u32 s65, s43, 0
	s_add_i32 s66, s66, s49
	global_load_lds_dwordx4 v[222:223], off
	v_lshl_add_u64 v[224:225], s[64:65], 0, v[134:135]
	s_mov_b32 m0, s66
	v_lshl_add_u64 v[226:227], s[46:47], 0, v[132:133]
	global_load_lds_dwordx4 v[224:225], off
	v_lshl_add_u64 v[224:225], s[64:65], 0, v[130:131]
	s_add_i32 m0, s66, 0x2000
	s_nop 0
	global_load_lds_dwordx4 v[224:225], off
	v_lshl_add_u64 v[224:225], s[46:47], 0, v[136:137]
	s_mov_b32 m0, s51
	s_nop 0
	global_load_lds_dwordx4 v[224:225], off
	s_mov_b32 m0, s52
	s_nop 0
	global_load_lds_dwordx4 v[226:227], off
	s_waitcnt vmcnt(8)
	s_waitcnt lgkmcnt(0)
	s_barrier
; #define PG8_STAGE(bufoff, gbase, voff) do { _Pragma("unroll") for (int _i = 0; _i < 2; ++_i) \
;         __builtin_amdgcn_global_load_lds((const unsigned*)((const char*)(gbase) + (voff)[_i]), (PG8_LAS unsigned*)(lds + (bufoff) + ldsw + _i * 8192), 16, 0, 0); } while (0)
; #define PG8_LDA(dst, b, h) do { _Pragma("unroll") for (int m = 0; m < 4; ++m) _Pragma("unroll") for (int k = 0; k < 2; ++k) dst[m][k] = *(const PG8_LAS bf16x8*)(lds + PG8_SA(b, h) + aoff + m * 2048 + k * 1024); } while (0)
; #define PG8_LDB(dst, b, h) do { _Pragma("unroll") for (int n = 0; n < 2; ++n) _Pragma("unroll") for (int k = 0; k < 2; ++k) dst[n][k] = *(const PG8_LAS bf16x8*)(lds + PG8_SB(b, h) + boff + n * 2048 + k * 1024); } while (0)
; #define PG8_MMA(ai, bj, At, Bt) do { __builtin_amdgcn_s_setprio(1); _Pragma("unroll") for (int m = 0; m < 4; ++m) _Pragma("unroll") for (int n = 0; n < 2; ++n) _Pragma("unroll") for (int k = 0; k < 2; ++k) \
;         acc[ai][bj][m][n] = __builtin_amdgcn_mfma_f32_16x16x32_bf16(Bt[n][k], At[m][k], acc[ai][bj][m][n], 0, 0, 0); __builtin_amdgcn_s_setprio(0); } while (0)
; #define PG8_WAIT_V(n) asm volatile("s_waitcnt vmcnt(" #n ")" ::: "memory")
; #define PG8_WAIT_L(n) asm volatile("s_waitcnt lgkmcnt(" #n ")" ::: "memory")
; #define PG8_BAR __builtin_amdgcn_s_barrier()
; #define PG8_SCHED __builtin_amdgcn_sched_barrier(0)
; template <class Epi, class Sched, bool ALIGN_EPI = false, bool SP2 = false>
; __device__ __forceinline__ void gemm_phase(PG8_LAS unsigned char* lds, const Gemm g, const Sched& S, const Epi& E) {
;     ...
;             PG8_WAIT_V(8); PG8_WAIT_L(0); PG8_BAR; PG8_MMA(1, 0, At, B0); PG8_MMA(1, 1, At, B1); PG8_BAR; PG8_SCHED;
;             PG8_LDB(B0, 1, 0); PG8_LDB(B1, 1, 1); PG8_SCHED; PG8_LDA(At, 1, 0); PG8_STAGE(PG8_SA(0, 1), a2 + hstep, voffA);
;             PG8_WAIT_V(8); PG8_WAIT_L(0); PG8_BAR; PG8_MMA(0, 0, At, B0); PG8_MMA(0, 1, At, B1); PG8_BAR; PG8_SCHED;
;             PG8_LDA(At, 1, 1); PG8_STAGE(PG8_SB(1, 0), b3, voffB); PG8_STAGE(PG8_SB(1, 1), b3 + hstep, voffB); PG8_STAGE(PG8_SA(1, 0), a3, voffA);
;             PG8_WAIT_V(8); PG8_WAIT_L(0); PG8_BAR; PG8_MMA(1, 0, At, B0); PG8_MMA(1, 1, At, B1); PG8_BAR; PG8_SCHED;
	s_waitcnt lgkmcnt(0)
	v_mfma_f32_16x16x32_bf16 v[62:65], v[146:149], v[178:181], v[62:65]
	v_mfma_f32_16x16x32_bf16 v[58:61], v[154:157], v[178:181], v[58:61]
	v_mfma_f32_16x16x32_bf16 v[46:49], v[146:149], v[186:189], v[46:49]
	v_mfma_f32_16x16x32_bf16 v[42:45], v[154:157], v[186:189], v[42:45]
	v_mfma_f32_16x16x32_bf16 v[28:31], v[146:149], v[204:207], v[28:31]
	v_mfma_f32_16x16x32_bf16 v[24:27], v[154:157], v[204:207], v[24:27]
	v_mfma_f32_16x16x32_bf16 v[12:15], v[146:149], v[212:215], v[12:15]
	v_mfma_f32_16x16x32_bf16 v[8:11], v[154:157], v[212:215], v[8:11]
	v_mfma_f32_16x16x32_bf16 v[62:65], v[150:153], v[182:185], v[62:65]
	v_mfma_f32_16x16x32_bf16 v[58:61], v[158:161], v[182:185], v[58:61]
	v_mfma_f32_16x16x32_bf16 v[46:49], v[150:153], v[190:193], v[46:49]
	v_mfma_f32_16x16x32_bf16 v[42:45], v[158:161], v[190:193], v[42:45]
	v_mfma_f32_16x16x32_bf16 v[28:31], v[150:153], v[208:211], v[28:31]
	v_mfma_f32_16x16x32_bf16 v[24:27], v[158:161], v[208:211], v[24:27]
	v_mfma_f32_16x16x32_bf16 v[12:15], v[150:153], v[216:219], v[12:15]
	v_mfma_f32_16x16x32_bf16 v[8:11], v[158:161], v[216:219], v[8:11]
	v_mfma_f32_16x16x32_bf16 v[54:57], v[162:165], v[178:181], v[54:57]
	v_mfma_f32_16x16x32_bf16 v[50:53], v[170:173], v[178:181], v[50:53]
	v_mfma_f32_16x16x32_bf16 v[38:41], v[162:165], v[186:189], v[38:41]
	v_mfma_f32_16x16x32_bf16 v[34:37], v[170:173], v[186:189], v[34:37]
	v_mfma_f32_16x16x32_bf16 v[20:23], v[162:165], v[204:207], v[20:23]
	v_mfma_f32_16x16x32_bf16 v[16:19], v[170:173], v[204:207], v[16:19]
	v_mfma_f32_16x16x32_bf16 v[4:7], v[162:165], v[212:215], v[4:7]
	v_mfma_f32_16x16x32_bf16 v[0:3], v[170:173], v[212:215], v[0:3]
	v_mfma_f32_16x16x32_bf16 v[54:57], v[166:169], v[182:185], v[54:57]
	v_mfma_f32_16x16x32_bf16 v[50:53], v[174:177], v[182:185], v[50:53]
	v_mfma_f32_16x16x32_bf16 v[38:41], v[166:169], v[190:193], v[38:41]
	v_mfma_f32_16x16x32_bf16 v[34:37], v[174:177], v[190:193], v[34:37]
	v_mfma_f32_16x16x32_bf16 v[20:23], v[166:169], v[208:211], v[20:23]
	v_mfma_f32_16x16x32_bf16 v[16:19], v[174:177], v[208:211], v[16:19]
	v_mfma_f32_16x16x32_bf16 v[4:7], v[166:169], v[216:219], v[4:7]
	v_mfma_f32_16x16x32_bf16 v[0:3], v[174:177], v[216:219], v[0:3]
	s_barrier
	s_add_i32 s64, 0, 0x18000
	v_add_u32_e32 v145, s64, v142
	s_add_i32 s65, 0, 0x1c000
	ds_read_b128 v[146:149], v145
	ds_read_b128 v[150:153], v145 offset:1024
	ds_read_b128 v[154:157], v145 offset:2048
	ds_read_b128 v[158:161], v145 offset:3072
	v_add_u32_e32 v145, s65, v142
	ds_read_b128 v[162:165], v145
	ds_read_b128 v[166:169], v145 offset:1024
	ds_read_b128 v[170:173], v145 offset:2048
	ds_read_b128 v[174:177], v145 offset:3072
	s_add_u32 s46, s46, 0x40000
	s_addc_u32 s47, s47, 0
	s_mov_b32 m0, s53
	v_lshl_add_u64 v[238:239], s[46:47], 0, v[136:137]
	ds_read_b128 v[178:181], v144 offset:32768
	ds_read_b128 v[182:185], v144 offset:33792
	ds_read_b128 v[186:189], v144 offset:34816
	ds_read_b128 v[190:193], v144 offset:35840
	ds_read_b128 v[204:207], v144 offset:36864
	ds_read_b128 v[208:211], v144 offset:37888
	ds_read_b128 v[212:215], v144 offset:38912
	ds_read_b128 v[216:219], v144 offset:39936
	global_load_lds_dwordx4 v[238:239], off
	v_lshl_add_u64 v[238:239], s[46:47], 0, v[132:133]
	s_mov_b32 m0, s55
	s_nop 0
	global_load_lds_dwordx4 v[238:239], off
	s_waitcnt vmcnt(8)
	s_waitcnt lgkmcnt(0)
	s_barrier
	s_waitcnt lgkmcnt(0)
	v_mfma_f32_16x16x32_bf16 v[126:129], v[146:149], v[178:181], v[126:129]
	v_mfma_f32_16x16x32_bf16 v[122:125], v[154:157], v[178:181], v[122:125]
	v_mfma_f32_16x16x32_bf16 v[110:113], v[146:149], v[186:189], v[110:113]
	v_mfma_f32_16x16x32_bf16 v[106:109], v[154:157], v[186:189], v[106:109]
	v_mfma_f32_16x16x32_bf16 v[94:97], v[146:149], v[204:207], v[94:97]
	v_mfma_f32_16x16x32_bf16 v[90:93], v[154:157], v[204:207], v[90:93]
	v_mfma_f32_16x16x32_bf16 v[78:81], v[146:149], v[212:215], v[78:81]
	v_mfma_f32_16x16x32_bf16 v[74:77], v[154:157], v[212:215], v[74:77]
	v_mfma_f32_16x16x32_bf16 v[126:129], v[150:153], v[182:185], v[126:129]
	v_mfma_f32_16x16x32_bf16 v[122:125], v[158:161], v[182:185], v[122:125]
	v_mfma_f32_16x16x32_bf16 v[110:113], v[150:153], v[190:193], v[110:113]
	v_mfma_f32_16x16x32_bf16 v[106:109], v[158:161], v[190:193], v[106:109]
	v_mfma_f32_16x16x32_bf16 v[94:97], v[150:153], v[208:211], v[94:97]
	v_mfma_f32_16x16x32_bf16 v[90:93], v[158:161], v[208:211], v[90:93]
	v_mfma_f32_16x16x32_bf16 v[78:81], v[150:153], v[216:219], v[78:81]
	v_mfma_f32_16x16x32_bf16 v[74:77], v[158:161], v[216:219], v[74:77]
	v_mfma_f32_16x16x32_bf16 v[118:121], v[162:165], v[178:181], v[118:121]
	v_mfma_f32_16x16x32_bf16 v[114:117], v[170:173], v[178:181], v[114:117]
	v_mfma_f32_16x16x32_bf16 v[102:105], v[162:165], v[186:189], v[102:105]
	v_mfma_f32_16x16x32_bf16 v[98:101], v[170:173], v[186:189], v[98:101]
	v_mfma_f32_16x16x32_bf16 v[86:89], v[162:165], v[204:207], v[86:89]
	v_mfma_f32_16x16x32_bf16 v[82:85], v[170:173], v[204:207], v[82:85]
	v_mfma_f32_16x16x32_bf16 v[70:73], v[162:165], v[212:215], v[70:73]
	v_mfma_f32_16x16x32_bf16 v[66:69], v[170:173], v[212:215], v[66:69]
	v_mfma_f32_16x16x32_bf16 v[118:121], v[166:169], v[182:185], v[118:121]
	v_mfma_f32_16x16x32_bf16 v[114:117], v[174:177], v[182:185], v[114:117]
	v_mfma_f32_16x16x32_bf16 v[102:105], v[166:169], v[190:193], v[102:105]
	v_mfma_f32_16x16x32_bf16 v[98:101], v[174:177], v[190:193], v[98:101]
	v_mfma_f32_16x16x32_bf16 v[86:89], v[166:169], v[208:211], v[86:89]
	v_mfma_f32_16x16x32_bf16 v[82:85], v[174:177], v[208:211], v[82:85]
	v_mfma_f32_16x16x32_bf16 v[70:73], v[166:169], v[216:219], v[70:73]
	v_mfma_f32_16x16x32_bf16 v[66:69], v[174:177], v[216:219], v[66:69]
	s_barrier
; #define PG8_STAGE(bufoff, gbase, voff) do { _Pragma("unroll") for (int _i = 0; _i < 2; ++_i) \
;         __builtin_amdgcn_global_load_lds((const unsigned*)((const char*)(gbase) + (voff)[_i]), (PG8_LAS unsigned*)(lds + (bufoff) + ldsw + _i * 8192), 16, 0, 0); } while (0)
; #define PG8_LDA(dst, b, h) do { _Pragma("unroll") for (int m = 0; m < 4; ++m) _Pragma("unroll") for (int k = 0; k < 2; ++k) dst[m][k] = *(const PG8_LAS bf16x8*)(lds + PG8_SA(b, h) + aoff + m * 2048 + k * 1024); } while (0)
; #define PG8_MMA(ai, bj, At, Bt) do { __builtin_amdgcn_s_setprio(1); _Pragma("unroll") for (int m = 0; m < 4; ++m) _Pragma("unroll") for (int n = 0; n < 2; ++n) _Pragma("unroll") for (int k = 0; k < 2; ++k) \
;         acc[ai][bj][m][n] = __builtin_amdgcn_mfma_f32_16x16x32_bf16(Bt[n][k], At[m][k], acc[ai][bj][m][n], 0, 0, 0); __builtin_amdgcn_s_setprio(0); } while (0)
; #define PG8_WAIT_V(n) asm volatile("s_waitcnt vmcnt(" #n ")" ::: "memory")
; #define PG8_WAIT_L(n) asm volatile("s_waitcnt lgkmcnt(" #n ")" ::: "memory")
; #define PG8_BAR __builtin_amdgcn_s_barrier()
; #define PG8_SCHED __builtin_amdgcn_sched_barrier(0)
; template <class Epi, class Sched, bool ALIGN_EPI = false, bool SP2 = false>
; __device__ __forceinline__ void gemm_phase(PG8_LAS unsigned char* lds, const Gemm g, const Sched& S, const Epi& E) {
;     ...
;         for (int t = 0; t < nt; t += 2) {
;     ...
;             PG8_WAIT_V(8); PG8_WAIT_L(0); PG8_BAR; PG8_MMA(0, 0, At, B0); PG8_MMA(0, 1, At, B1); PG8_BAR; PG8_SCHED;
;             PG8_LDA(At, 1, 1); PG8_STAGE(PG8_SB(1, 0), b3, voffB); PG8_STAGE(PG8_SB(1, 1), b3 + hstep, voffB); PG8_STAGE(PG8_SA(1, 0), a3, voffA);
;             PG8_WAIT_V(8); PG8_WAIT_L(0); PG8_BAR; PG8_MMA(1, 0, At, B0); PG8_MMA(1, 1, At, B1); PG8_BAR; PG8_SCHED;
	s_add_i32 s46, s64, s49
	v_lshl_add_u64 v[220:221], v[220:221], 0, s[8:9]
	s_mov_b32 m0, s46
	ds_read_b128 v[178:181], v144 offset:49152
	ds_read_b128 v[182:185], v144 offset:50176
	ds_read_b128 v[186:189], v144 offset:51200
	ds_read_b128 v[190:193], v144 offset:52224
	ds_read_b128 v[204:207], v144 offset:53248
	ds_read_b128 v[208:211], v144 offset:54272
	ds_read_b128 v[212:215], v144 offset:55296
	ds_read_b128 v[216:219], v144 offset:56320
	global_load_lds_dwordx4 v[220:221], off
	s_add_i32 m0, s46, 0x2000
	s_add_u32 s42, s42, 0x40080
	v_lshl_add_u64 v[220:221], v[222:223], 0, s[8:9]
	s_addc_u32 s43, s43, 0
	s_add_i32 s46, s65, s49
	global_load_lds_dwordx4 v[220:221], off
	v_lshl_add_u64 v[220:221], s[42:43], 0, v[134:135]
	s_mov_b32 m0, s46
	s_nop 0
	global_load_lds_dwordx4 v[220:221], off
	v_lshl_add_u64 v[220:221], s[42:43], 0, v[130:131]
	s_add_i32 m0, s46, 0x2000
	s_nop 0
	global_load_lds_dwordx4 v[220:221], off
	v_lshl_add_u64 v[220:221], v[224:225], 0, s[8:9]
	s_mov_b32 m0, s56
	s_nop 0
	global_load_lds_dwordx4 v[220:221], off
	v_lshl_add_u64 v[220:221], v[226:227], 0, s[8:9]
	s_mov_b32 m0, s57
	s_nop 0
	global_load_lds_dwordx4 v[220:221], off
	s_waitcnt vmcnt(8)
	s_waitcnt lgkmcnt(0)
	s_barrier
	s_waitcnt lgkmcnt(0)
	v_mfma_f32_16x16x32_bf16 v[62:65], v[146:149], v[178:181], v[62:65]
	v_mfma_f32_16x16x32_bf16 v[58:61], v[154:157], v[178:181], v[58:61]
	v_mfma_f32_16x16x32_bf16 v[46:49], v[146:149], v[186:189], v[46:49]
	v_mfma_f32_16x16x32_bf16 v[42:45], v[154:157], v[186:189], v[42:45]
	v_mfma_f32_16x16x32_bf16 v[28:31], v[146:149], v[204:207], v[28:31]
	v_mfma_f32_16x16x32_bf16 v[24:27], v[154:157], v[204:207], v[24:27]
	v_mfma_f32_16x16x32_bf16 v[12:15], v[146:149], v[212:215], v[12:15]
	v_mfma_f32_16x16x32_bf16 v[8:11], v[154:157], v[212:215], v[8:11]
	v_mfma_f32_16x16x32_bf16 v[62:65], v[150:153], v[182:185], v[62:65]
	v_mfma_f32_16x16x32_bf16 v[58:61], v[158:161], v[182:185], v[58:61]
	v_mfma_f32_16x16x32_bf16 v[46:49], v[150:153], v[190:193], v[46:49]
	v_mfma_f32_16x16x32_bf16 v[42:45], v[158:161], v[190:193], v[42:45]
	v_mfma_f32_16x16x32_bf16 v[28:31], v[150:153], v[208:211], v[28:31]
	v_mfma_f32_16x16x32_bf16 v[24:27], v[158:161], v[208:211], v[24:27]
	v_mfma_f32_16x16x32_bf16 v[12:15], v[150:153], v[216:219], v[12:15]
	v_mfma_f32_16x16x32_bf16 v[8:11], v[158:161], v[216:219], v[8:11]
	v_mfma_f32_16x16x32_bf16 v[54:57], v[162:165], v[178:181], v[54:57]
	v_mfma_f32_16x16x32_bf16 v[50:53], v[170:173], v[178:181], v[50:53]
	v_mfma_f32_16x16x32_bf16 v[38:41], v[162:165], v[186:189], v[38:41]
	v_mfma_f32_16x16x32_bf16 v[34:37], v[170:173], v[186:189], v[34:37]
	v_mfma_f32_16x16x32_bf16 v[20:23], v[162:165], v[204:207], v[20:23]
	v_mfma_f32_16x16x32_bf16 v[16:19], v[170:173], v[204:207], v[16:19]
	v_mfma_f32_16x16x32_bf16 v[4:7], v[162:165], v[212:215], v[4:7]
	v_mfma_f32_16x16x32_bf16 v[0:3], v[170:173], v[212:215], v[0:3]
	v_mfma_f32_16x16x32_bf16 v[54:57], v[166:169], v[182:185], v[54:57]
	v_mfma_f32_16x16x32_bf16 v[50:53], v[174:177], v[182:185], v[50:53]
	v_mfma_f32_16x16x32_bf16 v[38:41], v[166:169], v[190:193], v[38:41]
	v_mfma_f32_16x16x32_bf16 v[34:37], v[174:177], v[190:193], v[34:37]
	v_mfma_f32_16x16x32_bf16 v[20:23], v[166:169], v[208:211], v[20:23]
	v_mfma_f32_16x16x32_bf16 v[16:19], v[174:177], v[208:211], v[16:19]
	v_mfma_f32_16x16x32_bf16 v[4:7], v[166:169], v[216:219], v[4:7]
	v_mfma_f32_16x16x32_bf16 v[0:3], v[174:177], v[216:219], v[0:3]
	s_barrier
	s_add_i32 s63, s63, 2
	s_add_u32 s36, s36, 0x100
	s_addc_u32 s37, s37, 0
	s_add_u32 s61, s61, 0x100
	s_addc_u32 s62, s62, 0
	s_cmp_gt_u32 s63, 13
	s_cbranch_scc0 .LBB0_936
	s_and_b64 vcc, exec, s[22:23]
	s_cbranch_vccz .LBB0_939
	s_barrier

; #define PG8_WAIT_V(n) asm volatile("s_waitcnt vmcnt(" #n ")" ::: "memory")
; #define PG8_BAR __builtin_amdgcn_s_barrier()
; __device__ __forceinline__ const float* ka_in(kaptr p, int i) { return *(const float* const __attribute__((address_space(4)))*)(p + 8 * i); }
; template <class Epi, class Sched, bool ALIGN_EPI = false, bool SP2 = false>
; __device__ __forceinline__ void gemm_phase(PG8_LAS unsigned char* lds, const Gemm g, const Sched& S, const Epi& E) {
;     ...
;     PG8_WAIT_V(0);
;     if constexpr (!ALIGN_EPI) { if (wr == 0) PG8_BAR; }
;     PG8_BAR;
; __device__ __forceinline__ void tr_load(float (&v)[32], const TrItem& t, int lane) {
; #pragma unroll
;     for (int i = 0; i < 32; ++i) { const int kk = 2 * i + (lane >> 5); v[i] = t.W[(size_t)(t.k0 + kk) * t.Nsrc + t.c0 + (lane & 31)]; }
; __global__ void __launch_bounds__(NTHR, 2) fwd_mega(Args args_unused, int ph_lo, int ph_hi) {
;     ...
;         if (L + 1 < DEPTH && IN(pb + 5)) { PH_BEGIN
;             const int nj = (L + 1) >> 1;
;             if ((L + 1) & 1) { conv_plain(ka_in(ka, 4) + (size_t)nj * D * DIFF_IN, D, DIFF_IN, (bf16*)(ws + WS_WIN), scr, gw, ngw, lane); conv_plain(ka_in(ka, 5) + (size_t)nj * D * D, D, D, (bf16*)(ws + WS_WOUT), scr, gw, ngw, lane); }
;             else { conv_plain(ka_in(ka, 2) + (size_t)nj * D * RET_IN, D, RET_IN, (bf16*)(ws + WS_WIN), scr, gw, ngw, lane); conv_plain(ka_in(ka, 3) + (size_t)nj * 2048 * D, 2048, D, (bf16*)(ws + WS_WOUT), scr, gw, ngw, lane); }
;             conv_gu(ka_in(ka, 9) + (size_t)(L + 1) * D * FF, ka_in(ka, 10) + (size_t)(L + 1) * D * FF, (bf16*)(ws + WS_WGU), scr, gw, ngw, lane);
.LBB0_942:
	s_setprio 0
	s_waitcnt vmcnt(0)
	v_readlane_b32 s56, v255, 4
	v_readlane_b32 s58, v255, 6
	v_readlane_b32 s52, v255, 8
	v_readlane_b32 s57, v255, 5
	v_readlane_b32 s59, v255, 7
	v_readlane_b32 s53, v255, 9
	v_readlane_b32 s55, v255, 10
	s_barrier
	v_readlane_b32 s5, v254, 0
	s_nop 3
	s_cmp_lt_u32 s5, 0x80
	s_cbranch_scc1 .Lcv_skip
	s_mov_b64 s[44:45], s[6:7]
	s_cmp_lt_i32 s16, 3
	s_cbranch_scc0 .Lcv_done
	s_add_i32 s18, s16, 1
	s_waitcnt lgkmcnt(0)
	s_mov_b64 s[26:27], s[56:57]
	s_waitcnt vmcnt(0)
	v_mov_b32_e32 v0, v228
	v_readlane_b32 s5, v254, 0
	s_load_dwordx2 s[24:25], s[26:27], 0x68
	s_lshl_b32 s5, s5, 3
	v_readfirstlane_b32 s4, v0
	s_ashr_i32 s4, s4, 6
	s_add_i32 s17, s5, s4
	s_addk_i32 s17, 0xfc00
	s_lshl_b32 s4, s4, 14
	v_bfe_u32 v33, v0, 5, 1
	v_and_b32_e32 v1, 31, v0
	v_bfe_u32 v45, v0, 3, 3
	v_lshlrev_b32_e32 v0, 3, v0
	s_add_i32 s4, s4, 0
	v_lshlrev_b32_e32 v34, 2, v1
	v_mul_u32_u24_e32 v1, 0x84, v33
	v_and_b32_e32 v50, 56, v0
	s_ashr_i32 s28, s18, 1
	v_add3_u32 v44, s4, v34, v1
	v_mul_u32_u24_e32 v0, 0x84, v50
	v_lshlrev_b32_e32 v1, 2, v45
	s_ashr_i32 s29, s28, 31
	v_add3_u32 v46, s4, v0, v1
	v_readlane_b32 s4, v255, 11
	s_waitcnt lgkmcnt(0)
	s_add_u32 s30, s24, 0x200000
	v_readlane_b32 s5, v255, 12
	s_addc_u32 s31, s25, 0
	v_or_b32_e32 v47, 8, v45
	v_or_b32_e32 v48, 16, v45
	v_or_b32_e32 v49, 24, v45
	s_mov_b64 s[6:7], -1
	s_and_b64 vcc, exec, s[4:5]
	s_cbranch_vccz .LcvA_b1032
	s_cmpk_gt_i32 s17, 0xbff
	s_cbranch_scc1 .LcvA_b1022
	s_load_dwordx2 s[4:5], s[26:27], 0x10
	s_mul_i32 s7, s28, 0x1800000
	s_mul_hi_i32 s6, s28, 0x1800000
	v_mov_b32_e32 v35, v32
	s_waitcnt lgkmcnt(0)
	s_add_u32 s4, s4, s7
	s_addc_u32 s5, s5, s6
	v_lshl_add_u64 v[36:37], s[4:5], 0, v[34:35]
	s_mul_hi_i32 s4, s17, 0x2aaaaaab
	s_lshr_b32 s5, s4, 31
	s_ashr_i32 s4, s4, 5
	s_add_i32 s5, s4, s5
	s_mul_i32 s4, s5, 0xc0
	s_sub_i32 s4, s17, s4
	s_lshl_b32 s4, s4, 5
	v_lshl_or_b32 v35, s5, 6, v33
	s_ashr_i32 s5, s4, 31
	v_lshl_add_u64 v[38:39], s[4:5], 2, v[36:37]
	v_mad_i64_i32 v[0:1], s[4:5], v35, s54, v[38:39]
	global_load_dword v0, v[0:1], off
	v_or_b32_e32 v1, 2, v35
	v_mad_i64_i32 v[2:3], s[4:5], v1, s54, v[38:39]
	global_load_dword v1, v[2:3], off
	v_or_b32_e32 v2, 4, v35
	v_mad_i64_i32 v[2:3], s[4:5], v2, s54, v[38:39]
	global_load_dword v2, v[2:3], off
	v_or_b32_e32 v3, 6, v35
	v_mad_i64_i32 v[4:5], s[4:5], v3, s54, v[38:39]
	global_load_dword v3, v[4:5], off
	v_or_b32_e32 v4, 8, v35
	v_mad_i64_i32 v[4:5], s[4:5], v4, s54, v[38:39]
	global_load_dword v4, v[4:5], off
	v_or_b32_e32 v5, 10, v35
	v_mad_i64_i32 v[6:7], s[4:5], v5, s54, v[38:39]
	global_load_dword v5, v[6:7], off
	v_or_b32_e32 v6, 12, v35
	v_mad_i64_i32 v[6:7], s[4:5], v6, s54, v[38:39]
	global_load_dword v6, v[6:7], off
	v_or_b32_e32 v7, 14, v35
	v_mad_i64_i32 v[8:9], s[4:5], v7, s54, v[38:39]
	global_load_dword v7, v[8:9], off
	v_or_b32_e32 v8, 16, v35
	v_mad_i64_i32 v[8:9], s[4:5], v8, s54, v[38:39]
	global_load_dword v8, v[8:9], off
	v_or_b32_e32 v9, 18, v35
	v_mad_i64_i32 v[10:11], s[4:5], v9, s54, v[38:39]
	global_load_dword v9, v[10:11], off
	v_or_b32_e32 v10, 20, v35
	v_mad_i64_i32 v[10:11], s[4:5], v10, s54, v[38:39]
	global_load_dword v10, v[10:11], off
	v_or_b32_e32 v11, 22, v35
	v_mad_i64_i32 v[12:13], s[4:5], v11, s54, v[38:39]
	global_load_dword v11, v[12:13], off
	v_or_b32_e32 v12, 24, v35
	v_mad_i64_i32 v[12:13], s[4:5], v12, s54, v[38:39]
	global_load_dword v12, v[12:13], off
	v_or_b32_e32 v13, 26, v35
	v_mad_i64_i32 v[14:15], s[4:5], v13, s54, v[38:39]
	global_load_dword v13, v[14:15], off
	v_or_b32_e32 v14, 28, v35
	v_mad_i64_i32 v[14:15], s[4:5], v14, s54, v[38:39]
	global_load_dword v14, v[14:15], off
	v_or_b32_e32 v15, 30, v35
	v_mad_i64_i32 v[16:17], s[4:5], v15, s54, v[38:39]
	global_load_dword v15, v[16:17], off
	v_or_b32_e32 v16, 32, v35
	v_mad_i64_i32 v[16:17], s[4:5], v16, s54, v[38:39]
	global_load_dword v16, v[16:17], off
	v_or_b32_e32 v17, 34, v35
	v_mad_i64_i32 v[18:19], s[4:5], v17, s54, v[38:39]
	global_load_dword v17, v[18:19], off
	v_or_b32_e32 v18, 36, v35
	v_mad_i64_i32 v[18:19], s[4:5], v18, s54, v[38:39]
	global_load_dword v18, v[18:19], off
	v_or_b32_e32 v19, 38, v35
	v_mad_i64_i32 v[20:21], s[4:5], v19, s54, v[38:39]
	global_load_dword v19, v[20:21], off
	v_or_b32_e32 v20, 40, v35
	v_mad_i64_i32 v[20:21], s[4:5], v20, s54, v[38:39]
	global_load_dword v20, v[20:21], off
	v_or_b32_e32 v21, 42, v35
	v_mad_i64_i32 v[22:23], s[4:5], v21, s54, v[38:39]
	global_load_dword v21, v[22:23], off
	v_or_b32_e32 v22, 44, v35
	v_mad_i64_i32 v[22:23], s[4:5], v22, s54, v[38:39]
	global_load_dword v22, v[22:23], off
	v_or_b32_e32 v23, 46, v35
	v_mad_i64_i32 v[24:25], s[4:5], v23, s54, v[38:39]
	global_load_dword v23, v[24:25], off
	v_or_b32_e32 v24, 48, v35
	v_mad_i64_i32 v[24:25], s[4:5], v24, s54, v[38:39]
	global_load_dword v24, v[24:25], off
	v_or_b32_e32 v25, 50, v35
	v_mad_i64_i32 v[26:27], s[4:5], v25, s54, v[38:39]
	global_load_dword v25, v[26:27], off
	v_or_b32_e32 v26, 52, v35
	v_mad_i64_i32 v[26:27], s[4:5], v26, s54, v[38:39]
	global_load_dword v26, v[26:27], off
	v_or_b32_e32 v27, 54, v35
	v_mad_i64_i32 v[28:29], s[4:5], v27, s54, v[38:39]
	global_load_dword v27, v[28:29], off
	v_or_b32_e32 v28, 56, v35
	v_mad_i64_i32 v[28:29], s[4:5], v28, s54, v[38:39]
	global_load_dword v28, v[28:29], off
	v_or_b32_e32 v29, 58, v35
	v_mad_i64_i32 v[30:31], s[4:5], v29, s54, v[38:39]
	global_load_dword v29, v[30:31], off
	v_or_b32_e32 v30, 60, v35
	v_mad_i64_i32 v[30:31], s[4:5], v30, s54, v[38:39]
	global_load_dword v30, v[30:31], off
	v_or_b32_e32 v31, 62, v35
	v_mad_i64_i32 v[38:39], s[4:5], v31, s54, v[38:39]
	global_load_dword v31, v[38:39], off
	v_lshlrev_b32_e32 v38, 1, v50
	s_mov_b32 s4, s17
	s_branch .LcvA_b1017

; #define PG8_BAR __builtin_amdgcn_s_barrier()
; template <class Epi, class Sched, bool ALIGN_EPI = false, bool SP2 = false>
; __device__ __forceinline__ void gemm_phase(PG8_LAS unsigned char* lds, const Gemm g, const Sched& S, const Epi& E) {
;     ...
;     Unit cur, nxt; int ui = 0;
;     if (!S.next(0, cur)) return;
;     f32x4 acc[2][2][4][2];
; #pragma unroll
;     for (int a = 0; a < 2; ++a)
; #pragma unroll
;         for (int b = 0; b < 2; ++b)
; #pragma unroll
;             for (int m = 0; m < 4; ++m)
; #pragma unroll
;                 for (int n = 0; n < 2; ++n) acc[a][b][m][n] = (f32x4){0.f, 0.f, 0.f, 0.f};
;     bf16x8 At[4][2], B0[2][2], B1[2][2];
;     const char* cA = (const char*)g.A + (size_t)cur.pm * tstep; const char* cB = (const char*)g.Bt + (size_t)cur.pn * tstep;
;     S.a_ready(cur);
;     if constexpr (SP2) {
;         PG8_STAGE(PG8_SB(0, 0), cB, voffB); PG8_STAGE(PG8_SB(0, 1), cB + hstep, voffB); PG8_STAGE(PG8_SA(0, 0), cA, voffA); PG8_STAGE(PG8_SA(0, 1), cA + hstep, voffA);
;         if (wr == 1) PG8_BAR;
;         PG8_WAIT_V(2); PG8_BAR;
;         PG8_STAGE(PG8_SB(1, 0), cB + kstep, voffB); PG8_STAGE(PG8_SA(1, 0), cA + kstep, voffA); PG8_STAGE(PG8_SB(1, 1), cB + hstep + kstep, voffB);
;         PG8_WAIT_V(6); PG8_BAR;
;     } else {
;         PG8_STAGE(PG8_SB(0, 0), cB, voffB); PG8_STAGE(PG8_SA(0, 0), cA, voffA); PG8_STAGE(PG8_SB(0, 1), cB + hstep, voffB); PG8_STAGE(PG8_SA(0, 1), cA + hstep, voffA);
;         if (wr == 1) PG8_BAR;
;         PG8_WAIT_V(4); PG8_BAR;
;         PG8_STAGE(PG8_SB(1, 0), cB + kstep, voffB); PG8_STAGE(PG8_SA(1, 0), cA + kstep, voffA); PG8_STAGE(PG8_SB(1, 1), cB + hstep + kstep, voffB);
;         PG8_WAIT_V(6); PG8_BAR;
;     }
; __global__ void __launch_bounds__(NTHR, 2) fwd_mega(Args args_unused, int ph_lo, int ph_hi) {
;     ...
;         if (IN(pb + 5)) { PH_BEGIN
;           const float* gains = ka_in(ka, 1); const float* gL = gains + (size_t)L * 4 * D; float* out = ka_out(ka); unsigned* ctl = (unsigned*)(ws + WS_CTL);
;           pg8::Gemm g{(const bf16*)(ws + WS_ACT), (const bf16*)(ws + WS_WDN), M, D, FF}; pg8::StaticOrder S; S.init(M, D, G, bid);
;           const float* gnext = (L + 1 < DEPTH) ? gains + (size_t)(L + 1) * 4 * D : gL;
;           pg8::EpiNormResNorm E{(const float*)out, out, (bf16*)(ws + WS_XN), gL + 3 * D, gnext, (float*)(ws + WS_X), ctl + CW_CNT + (L * 4 + 2) * 64 * 64, RMS_EPS, 0};
.LBB0_1067:
	v_ashrrev_i32_e32 v1, 31, v195
	v_lshrrev_b32_e32 v1, 26, v1
	v_add_u32_e32 v1, v195, v1
	v_ashrrev_i32_e32 v8, 6, v1
	v_bfe_i32 v1, v195, 27, 1
	v_lshlrev_b32_e32 v0, 4, v195
	v_lshrrev_b32_e32 v1, 22, v1
	v_add_u32_e32 v1, v0, v1
	v_and_b32_e32 v1, 0xfffffc00, v1
	v_sub_u32_e32 v1, v0, v1
	v_lshrrev_b32_e32 v2, 4, v1
	v_bitop3_b32 v1, v2, v1, 32 bitop3:0x6c
	v_ashrrev_i32_e32 v3, 31, v1
	v_lshrrev_b32_e32 v3, 26, v3
	v_add_u32_e32 v3, v1, v3
	s_waitcnt lgkmcnt(0)
	s_add_u32 s17, s24, 0x4300000
	v_lshlrev_b32_e32 v2, 3, v8
	v_ashrrev_i32_e32 v10, 6, v3
	v_and_b32_e32 v3, 0xc0, v3
	s_addc_u32 s49, s25, 0
	v_and_b32_e32 v2, 0xfffff0, v2
	v_sub_u32_e32 v1, v1, v3
	s_add_u32 s52, s24, 0x1d00000
	v_add_u32_e32 v2, v10, v2
	v_lshlrev_b32_e32 v4, 5, v8
	v_ashrrev_i16_sdwa v1, v229, sext(v1) dst_sel:DWORD dst_unused:UNUSED_PAD src0_sel:DWORD src1_sel:BYTE_0
	s_addc_u32 s53, s25, 0
	v_and_b32_e32 v9, 32, v4
	v_bfe_i32 v11, v1, 0, 16
	v_mul_lo_u32 v1, v2, s97
	s_add_i32 s6, s26, s6
	v_or_b32_e32 v1, v1, v9
	v_add_u32_e32 v0, 0x2000, v0
	s_ashr_i32 s7, s6, 31
	v_add_lshl_u32 v132, v1, v11, 1
	v_ashrrev_i32_e32 v1, 31, v0
	s_lshr_b32 s7, s7, 27
	v_lshrrev_b32_e32 v1, 22, v1
	s_add_i32 s7, s6, s7
	v_add_u32_e32 v1, v0, v1
	s_ashr_i32 s26, s7, 5
	s_and_b32 s7, s7, 0xffe0
	v_ashrrev_i32_e32 v12, 10, v1
	s_sub_i32 s6, s6, s7
	v_mul_i32_i24_e32 v1, 0x400, v12
	s_bfe_i32 s7, s6, 0x80000
	v_sub_u32_e32 v0, v0, v1
	s_bfe_u32 s7, s7, 0x3000c
	v_lshrrev_b32_e32 v1, 4, v0
	s_add_i32 s7, s6, s7
	v_bitop3_b32 v0, v1, v0, 32 bitop3:0x6c
	s_bfe_i32 s27, s7, 0x80000
	s_and_b32 s7, s7, 0xf8
	v_ashrrev_i32_e32 v2, 31, v0
	s_sub_i32 s6, s6, s7
	v_lshrrev_b32_e32 v2, 26, v2
	s_lshl_b32 s26, s26, 3
	s_sext_i32_i16 s35, s27
	s_sext_i32_i8 s6, s6
	s_ashr_i32 s91, s19, 6
	v_add_u32_e32 v2, v0, v2
	s_add_i32 s90, s26, s6
	s_ashr_i32 s6, s35, 3
	s_ashr_i32 s34, s19, 8
	v_lshlrev_b32_e32 v1, 3, v12
	v_ashrrev_i32_e32 v14, 6, v2
	v_and_b32_e32 v2, 0xc0, v2
	s_lshl_b32 s55, s91, 10
	s_mul_hi_i32 s7, s6, 0x160000
	s_mul_i32 s6, s6, 0x160000
	v_and_b32_e32 v1, 0xfffff0, v1
	v_sub_u32_e32 v0, v0, v2
	s_add_u32 s50, s52, s6
	v_add_u32_e32 v1, v14, v1
	v_lshlrev_b32_e32 v3, 5, v12
	v_ashrrev_i16_sdwa v0, v229, sext(v0) dst_sel:DWORD dst_unused:UNUSED_PAD src0_sel:DWORD src1_sel:BYTE_0
	s_addc_u32 s51, s53, s7
	s_add_i32 s56, s55, 0
	v_and_b32_e32 v13, 32, v3
	v_bfe_i32 v15, v0, 0, 16
	v_mul_lo_u32 v0, v1, s97
	s_add_i32 m0, s56, 0x10000
	v_or_b32_e32 v0, v0, v13
	global_load_lds_dwordx4 v132, s[50:51]
	s_add_i32 m0, s56, 0x12000
	v_add_lshl_u32 v134, v0, v15, 1
	s_add_u32 s6, s50, 0xb0000
	global_load_lds_dwordx4 v134, s[50:51]
	s_addc_u32 s7, s51, 0
	s_add_i32 m0, s56, 0x14000
	s_mul_i32 s27, s90, 0x160000
	global_load_lds_dwordx4 v132, s[6:7]
	s_add_i32 m0, s56, 0x16000
	s_mul_hi_i32 s26, s90, 0x160000
	global_load_lds_dwordx4 v134, s[6:7]
	s_add_u32 s6, s17, s27
	s_addc_u32 s7, s49, s26
	s_add_i32 s57, s56, 0x2000
	s_mov_b32 m0, s56
	s_add_u32 s26, s6, 0xb0000
	global_load_lds_dwordx4 v132, s[6:7]
	s_mov_b32 m0, s57
	s_addc_u32 s27, s7, 0
	s_add_i32 s58, s56, 0x4000
	global_load_lds_dwordx4 v134, s[6:7]
	s_mov_b32 m0, s58
	s_add_i32 s59, s56, 0x6000
	global_load_lds_dwordx4 v132, s[26:27]
	s_mov_b32 m0, s59
	v_mov_b32_e32 v133, v32
	global_load_lds_dwordx4 v134, s[26:27]
	s_load_dwordx2 s[26:27], s[28:29], 0x8
	s_load_dwordx2 s[30:31], s[28:29], 0x60
	v_mov_b32_e32 v135, v32
	v_lshl_add_u64 v[6:7], s[50:51], 0, v[132:133]
	v_lshl_add_u64 v[4:5], s[50:51], 0, v[134:135]
	v_lshl_add_u64 v[2:3], s[6:7], 0, v[132:133]
	s_cmp_lg_u32 s34, 1
	v_lshl_add_u64 v[0:1], s[6:7], 0, v[134:135]
	s_cbranch_scc1 .LBB0_1069
	s_barrier
	s_setprio 1

; #define PG8_STAGE(bufoff, gbase, voff) do { _Pragma("unroll") for (int _i = 0; _i < 2; ++_i) \
;         __builtin_amdgcn_global_load_lds((const unsigned*)((const char*)(gbase) + (voff)[_i]), (PG8_LAS unsigned*)(lds + (bufoff) + ldsw + _i * 8192), 16, 0, 0); } while (0)
; #define PG8_LDA(dst, b, h) do { _Pragma("unroll") for (int m = 0; m < 4; ++m) _Pragma("unroll") for (int k = 0; k < 2; ++k) dst[m][k] = *(const PG8_LAS bf16x8*)(lds + PG8_SA(b, h) + aoff + m * 2048 + k * 1024); } while (0)
; #define PG8_LDB(dst, b, h) do { _Pragma("unroll") for (int n = 0; n < 2; ++n) _Pragma("unroll") for (int k = 0; k < 2; ++k) dst[n][k] = *(const PG8_LAS bf16x8*)(lds + PG8_SB(b, h) + boff + n * 2048 + k * 1024); } while (0)
; #define PG8_MMA(ai, bj, At, Bt) do { __builtin_amdgcn_s_setprio(1); _Pragma("unroll") for (int m = 0; m < 4; ++m) _Pragma("unroll") for (int n = 0; n < 2; ++n) _Pragma("unroll") for (int k = 0; k < 2; ++k) \
;         acc[ai][bj][m][n] = __builtin_amdgcn_mfma_f32_16x16x32_bf16(Bt[n][k], At[m][k], acc[ai][bj][m][n], 0, 0, 0); __builtin_amdgcn_s_setprio(0); } while (0)
; #define PG8_BAR __builtin_amdgcn_s_barrier()
; template <class Epi, class Sched, bool ALIGN_EPI = false, bool SP2 = false>
; __device__ __forceinline__ void gemm_phase(PG8_LAS unsigned char* lds, const Gemm g, const Sched& S, const Epi& E) {
;     ...
;             if constexpr (SP2) {
;             PG8_LDB(B0, 0, 0); PG8_LDB(B1, 0, 1); PG8_SCHED; PG8_LDA(At, 0, 0); PG8_STAGE(PG8_SA(1, 1), a1 + hstep, voffA);
;             PG8_WAIT_V(8); PG8_WAIT_L(0); PG8_BAR; PG8_MMA(0, 0, At, B0); PG8_MMA(0, 1, At, B1); PG8_BAR; PG8_SCHED;
;             PG8_LDA(At, 0, 1); PG8_STAGE(PG8_SB(0, 0), b2, voffB); PG8_STAGE(PG8_SB(0, 1), b2 + hstep, voffB); PG8_STAGE(PG8_SA(0, 0), a2, voffA);
;             PG8_WAIT_V(8); PG8_WAIT_L(0); PG8_BAR; PG8_MMA(1, 0, At, B0); PG8_MMA(1, 1, At, B1); PG8_BAR; PG8_SCHED;
;             PG8_LDB(B0, 1, 0); PG8_LDB(B1, 1, 1); PG8_SCHED; PG8_LDA(At, 1, 0); PG8_STAGE(PG8_SA(0, 1), a2 + hstep, voffA);
;             PG8_WAIT_V(8); PG8_WAIT_L(0); PG8_BAR; PG8_MMA(0, 0, At, B0); PG8_MMA(0, 1, At, B1); PG8_BAR; PG8_SCHED;
;             PG8_LDA(At, 1, 1); PG8_STAGE(PG8_SB(1, 0), b3, voffB); PG8_STAGE(PG8_SB(1, 1), b3 + hstep, voffB); PG8_STAGE(PG8_SA(1, 0), a3, voffA);
;             PG8_WAIT_V(8); PG8_WAIT_L(0); PG8_BAR; PG8_MMA(1, 0, At, B0); PG8_MMA(1, 1, At, B1); PG8_BAR; PG8_SCHED;
.LBB0_1081:
	s_add_u32 s46, s6, s44
	s_addc_u32 s47, s7, s45
	s_add_u32 s46, s46, 0x100
	s_addc_u32 s47, s47, 0
	s_add_u32 s68, s66, s44
	s_addc_u32 s69, s67, s45
	s_add_i32 s70, 0, 0x10000
	s_cmpk_eq_i32 s44, 0x1500
	s_cselect_b32 s51, s37, s47
	s_cselect_b32 s50, s36, s46
	v_add_u32_e32 v33, s70, v142
	s_cselect_b32 s47, s35, s69
	s_cselect_b32 s46, s34, s68
	s_add_i32 s71, 0, 0x14000
	ds_read_b128 v[144:147], v33
	ds_read_b128 v[148:151], v33 offset:1024
	ds_read_b128 v[152:155], v33 offset:2048
	ds_read_b128 v[156:159], v33 offset:3072
	v_add_u32_e32 v33, s71, v142
	ds_read_b128 v[160:163], v33
	ds_read_b128 v[164:167], v33 offset:1024
	ds_read_b128 v[168:171], v33 offset:2048
	ds_read_b128 v[172:175], v33 offset:3072
	v_lshl_add_u64 v[220:221], v[34:35], 0, s[44:45]
	s_add_i32 m0, s56, 0xc000
	ds_read_b128 v[176:179], v143
	ds_read_b128 v[180:183], v143 offset:1024
	ds_read_b128 v[184:187], v143 offset:2048
	ds_read_b128 v[188:191], v143 offset:3072
	ds_read_b128 v[204:207], v143 offset:4096
	ds_read_b128 v[208:211], v143 offset:5120
	ds_read_b128 v[212:215], v143 offset:6144
	ds_read_b128 v[216:219], v143 offset:7168
	global_load_lds_dwordx4 v[220:221], off
	v_lshl_add_u64 v[220:221], v[140:141], 0, s[44:45]
	s_add_i32 m0, s56, 0xe000
	s_nop 0
	global_load_lds_dwordx4 v[220:221], off
	s_waitcnt vmcnt(8)
	s_waitcnt lgkmcnt(0)
	s_barrier
	s_waitcnt lgkmcnt(0)
	v_mfma_f32_16x16x32_bf16 v[128:131], v[144:147], v[176:179], v[128:131]
	v_mfma_f32_16x16x32_bf16 v[124:127], v[152:155], v[176:179], v[124:127]
	v_mfma_f32_16x16x32_bf16 v[112:115], v[144:147], v[184:187], v[112:115]
	v_mfma_f32_16x16x32_bf16 v[108:111], v[152:155], v[184:187], v[108:111]
	v_mfma_f32_16x16x32_bf16 v[96:99], v[144:147], v[204:207], v[96:99]
	v_mfma_f32_16x16x32_bf16 v[92:95], v[152:155], v[204:207], v[92:95]
	v_mfma_f32_16x16x32_bf16 v[80:83], v[144:147], v[212:215], v[80:83]
	v_mfma_f32_16x16x32_bf16 v[76:79], v[152:155], v[212:215], v[76:79]
	v_mfma_f32_16x16x32_bf16 v[128:131], v[148:151], v[180:183], v[128:131]
	v_mfma_f32_16x16x32_bf16 v[124:127], v[156:159], v[180:183], v[124:127]
	v_mfma_f32_16x16x32_bf16 v[112:115], v[148:151], v[188:191], v[112:115]
	v_mfma_f32_16x16x32_bf16 v[108:111], v[156:159], v[188:191], v[108:111]
	v_mfma_f32_16x16x32_bf16 v[96:99], v[148:151], v[208:211], v[96:99]
	v_mfma_f32_16x16x32_bf16 v[92:95], v[156:159], v[208:211], v[92:95]
	v_mfma_f32_16x16x32_bf16 v[80:83], v[148:151], v[216:219], v[80:83]
	v_mfma_f32_16x16x32_bf16 v[76:79], v[156:159], v[216:219], v[76:79]
	v_mfma_f32_16x16x32_bf16 v[120:123], v[160:163], v[176:179], v[120:123]
	v_mfma_f32_16x16x32_bf16 v[116:119], v[168:171], v[176:179], v[116:119]
	v_mfma_f32_16x16x32_bf16 v[104:107], v[160:163], v[184:187], v[104:107]
	v_mfma_f32_16x16x32_bf16 v[100:103], v[168:171], v[184:187], v[100:103]
	v_mfma_f32_16x16x32_bf16 v[88:91], v[160:163], v[204:207], v[88:91]
	v_mfma_f32_16x16x32_bf16 v[84:87], v[168:171], v[204:207], v[84:87]
	v_mfma_f32_16x16x32_bf16 v[72:75], v[160:163], v[212:215], v[72:75]
	v_mfma_f32_16x16x32_bf16 v[68:71], v[168:171], v[212:215], v[68:71]
	v_mfma_f32_16x16x32_bf16 v[120:123], v[164:167], v[180:183], v[120:123]
	v_mfma_f32_16x16x32_bf16 v[116:119], v[172:175], v[180:183], v[116:119]
	v_mfma_f32_16x16x32_bf16 v[104:107], v[164:167], v[188:191], v[104:107]
	v_mfma_f32_16x16x32_bf16 v[100:103], v[172:175], v[188:191], v[100:103]
	v_mfma_f32_16x16x32_bf16 v[88:91], v[164:167], v[208:211], v[88:91]
	v_mfma_f32_16x16x32_bf16 v[84:87], v[172:175], v[208:211], v[84:87]
	v_mfma_f32_16x16x32_bf16 v[72:75], v[164:167], v[216:219], v[72:75]
	v_mfma_f32_16x16x32_bf16 v[68:71], v[172:175], v[216:219], v[68:71]
	s_barrier
	s_add_i32 s68, s70, s55
	v_lshl_add_u64 v[220:221], s[46:47], 0, v[132:133]
	s_mov_b32 m0, s68
	ds_read_b128 v[176:179], v143 offset:16384
	ds_read_b128 v[180:183], v143 offset:17408
	ds_read_b128 v[184:187], v143 offset:18432
	ds_read_b128 v[188:191], v143 offset:19456
	ds_read_b128 v[204:207], v143 offset:20480
	ds_read_b128 v[208:211], v143 offset:21504
	ds_read_b128 v[212:215], v143 offset:22528
	ds_read_b128 v[216:219], v143 offset:23552
	global_load_lds_dwordx4 v[220:221], off
	s_add_i32 m0, s68, 0x2000
	s_add_u32 s68, s46, 0xb0000
	v_lshl_add_u64 v[222:223], s[46:47], 0, v[134:135]
	s_addc_u32 s69, s47, 0
	s_add_i32 s70, s71, s55
	global_load_lds_dwordx4 v[222:223], off
	v_lshl_add_u64 v[224:225], s[68:69], 0, v[132:133]
	s_mov_b32 m0, s70
	v_lshl_add_u64 v[226:227], s[50:51], 0, v[134:135]
	global_load_lds_dwordx4 v[224:225], off
	v_lshl_add_u64 v[224:225], s[68:69], 0, v[134:135]
	s_add_i32 m0, s70, 0x2000
	s_nop 0
	global_load_lds_dwordx4 v[224:225], off
	v_lshl_add_u64 v[224:225], s[50:51], 0, v[132:133]
	s_mov_b32 m0, s56
	s_nop 0
	global_load_lds_dwordx4 v[224:225], off
	s_mov_b32 m0, s57
	s_nop 0
	global_load_lds_dwordx4 v[226:227], off
	s_waitcnt vmcnt(8)
	s_waitcnt lgkmcnt(0)
	s_barrier
; #define PG8_STAGE(bufoff, gbase, voff) do { _Pragma("unroll") for (int _i = 0; _i < 2; ++_i) \
;         __builtin_amdgcn_global_load_lds((const unsigned*)((const char*)(gbase) + (voff)[_i]), (PG8_LAS unsigned*)(lds + (bufoff) + ldsw + _i * 8192), 16, 0, 0); } while (0)
; #define PG8_LDA(dst, b, h) do { _Pragma("unroll") for (int m = 0; m < 4; ++m) _Pragma("unroll") for (int k = 0; k < 2; ++k) dst[m][k] = *(const PG8_LAS bf16x8*)(lds + PG8_SA(b, h) + aoff + m * 2048 + k * 1024); } while (0)
; #define PG8_LDB(dst, b, h) do { _Pragma("unroll") for (int n = 0; n < 2; ++n) _Pragma("unroll") for (int k = 0; k < 2; ++k) dst[n][k] = *(const PG8_LAS bf16x8*)(lds + PG8_SB(b, h) + boff + n * 2048 + k * 1024); } while (0)
; #define PG8_MMA(ai, bj, At, Bt) do { __builtin_amdgcn_s_setprio(1); _Pragma("unroll") for (int m = 0; m < 4; ++m) _Pragma("unroll") for (int n = 0; n < 2; ++n) _Pragma("unroll") for (int k = 0; k < 2; ++k) \
;         acc[ai][bj][m][n] = __builtin_amdgcn_mfma_f32_16x16x32_bf16(Bt[n][k], At[m][k], acc[ai][bj][m][n], 0, 0, 0); __builtin_amdgcn_s_setprio(0); } while (0)
; #define PG8_WAIT_V(n) asm volatile("s_waitcnt vmcnt(" #n ")" ::: "memory")
; #define PG8_WAIT_L(n) asm volatile("s_waitcnt lgkmcnt(" #n ")" ::: "memory")
; #define PG8_BAR __builtin_amdgcn_s_barrier()
; #define PG8_SCHED __builtin_amdgcn_sched_barrier(0)
; template <class Epi, class Sched, bool ALIGN_EPI = false, bool SP2 = false>
; __device__ __forceinline__ void gemm_phase(PG8_LAS unsigned char* lds, const Gemm g, const Sched& S, const Epi& E) {
;     ...
;             PG8_WAIT_V(8); PG8_WAIT_L(0); PG8_BAR; PG8_MMA(1, 0, At, B0); PG8_MMA(1, 1, At, B1); PG8_BAR; PG8_SCHED;
;             PG8_LDB(B0, 1, 0); PG8_LDB(B1, 1, 1); PG8_SCHED; PG8_LDA(At, 1, 0); PG8_STAGE(PG8_SA(0, 1), a2 + hstep, voffA);
;             PG8_WAIT_V(8); PG8_WAIT_L(0); PG8_BAR; PG8_MMA(0, 0, At, B0); PG8_MMA(0, 1, At, B1); PG8_BAR; PG8_SCHED;
;             PG8_LDA(At, 1, 1); PG8_STAGE(PG8_SB(1, 0), b3, voffB); PG8_STAGE(PG8_SB(1, 1), b3 + hstep, voffB); PG8_STAGE(PG8_SA(1, 0), a3, voffA);
;             PG8_WAIT_V(8); PG8_WAIT_L(0); PG8_BAR; PG8_MMA(1, 0, At, B0); PG8_MMA(1, 1, At, B1); PG8_BAR; PG8_SCHED;
	s_waitcnt lgkmcnt(0)
	v_mfma_f32_16x16x32_bf16 v[64:67], v[144:147], v[176:179], v[64:67]
	v_mfma_f32_16x16x32_bf16 v[60:63], v[152:155], v[176:179], v[60:63]
	v_mfma_f32_16x16x32_bf16 v[48:51], v[144:147], v[184:187], v[48:51]
	v_mfma_f32_16x16x32_bf16 v[44:47], v[152:155], v[184:187], v[44:47]
	v_mfma_f32_16x16x32_bf16 v[28:31], v[144:147], v[204:207], v[28:31]
	v_mfma_f32_16x16x32_bf16 v[24:27], v[152:155], v[204:207], v[24:27]
	v_mfma_f32_16x16x32_bf16 v[12:15], v[144:147], v[212:215], v[12:15]
	v_mfma_f32_16x16x32_bf16 v[8:11], v[152:155], v[212:215], v[8:11]
	v_mfma_f32_16x16x32_bf16 v[64:67], v[148:151], v[180:183], v[64:67]
	v_mfma_f32_16x16x32_bf16 v[60:63], v[156:159], v[180:183], v[60:63]
	v_mfma_f32_16x16x32_bf16 v[48:51], v[148:151], v[188:191], v[48:51]
	v_mfma_f32_16x16x32_bf16 v[44:47], v[156:159], v[188:191], v[44:47]
	v_mfma_f32_16x16x32_bf16 v[28:31], v[148:151], v[208:211], v[28:31]
	v_mfma_f32_16x16x32_bf16 v[24:27], v[156:159], v[208:211], v[24:27]
	v_mfma_f32_16x16x32_bf16 v[12:15], v[148:151], v[216:219], v[12:15]
	v_mfma_f32_16x16x32_bf16 v[8:11], v[156:159], v[216:219], v[8:11]
	v_mfma_f32_16x16x32_bf16 v[56:59], v[160:163], v[176:179], v[56:59]
	v_mfma_f32_16x16x32_bf16 v[52:55], v[168:171], v[176:179], v[52:55]
	v_mfma_f32_16x16x32_bf16 v[40:43], v[160:163], v[184:187], v[40:43]
	v_mfma_f32_16x16x32_bf16 v[36:39], v[168:171], v[184:187], v[36:39]
	v_mfma_f32_16x16x32_bf16 v[20:23], v[160:163], v[204:207], v[20:23]
	v_mfma_f32_16x16x32_bf16 v[16:19], v[168:171], v[204:207], v[16:19]
	v_mfma_f32_16x16x32_bf16 v[4:7], v[160:163], v[212:215], v[4:7]
	v_mfma_f32_16x16x32_bf16 v[0:3], v[168:171], v[212:215], v[0:3]
	v_mfma_f32_16x16x32_bf16 v[56:59], v[164:167], v[180:183], v[56:59]
	v_mfma_f32_16x16x32_bf16 v[52:55], v[172:175], v[180:183], v[52:55]
	v_mfma_f32_16x16x32_bf16 v[40:43], v[164:167], v[188:191], v[40:43]
	v_mfma_f32_16x16x32_bf16 v[36:39], v[172:175], v[188:191], v[36:39]
	v_mfma_f32_16x16x32_bf16 v[20:23], v[164:167], v[208:211], v[20:23]
	v_mfma_f32_16x16x32_bf16 v[16:19], v[172:175], v[208:211], v[16:19]
	v_mfma_f32_16x16x32_bf16 v[4:7], v[164:167], v[216:219], v[4:7]
	v_mfma_f32_16x16x32_bf16 v[0:3], v[172:175], v[216:219], v[0:3]
	s_barrier
	s_add_i32 s68, 0, 0x18000
	v_add_u32_e32 v33, s68, v142
	s_add_i32 s69, 0, 0x1c000
	ds_read_b128 v[144:147], v33
	ds_read_b128 v[148:151], v33 offset:1024
	ds_read_b128 v[152:155], v33 offset:2048
	ds_read_b128 v[156:159], v33 offset:3072
	v_add_u32_e32 v33, s69, v142
	ds_read_b128 v[160:163], v33
	ds_read_b128 v[164:167], v33 offset:1024
	ds_read_b128 v[168:171], v33 offset:2048
	ds_read_b128 v[172:175], v33 offset:3072
	s_add_u32 s50, s50, 0xb0000
	s_addc_u32 s51, s51, 0
	s_mov_b32 m0, s58
	v_lshl_add_u64 v[238:239], s[50:51], 0, v[132:133]
	ds_read_b128 v[176:179], v143 offset:32768
	ds_read_b128 v[180:183], v143 offset:33792
	ds_read_b128 v[184:187], v143 offset:34816
	ds_read_b128 v[188:191], v143 offset:35840
	ds_read_b128 v[204:207], v143 offset:36864
	ds_read_b128 v[208:211], v143 offset:37888
	ds_read_b128 v[212:215], v143 offset:38912
	ds_read_b128 v[216:219], v143 offset:39936
	global_load_lds_dwordx4 v[238:239], off
	v_lshl_add_u64 v[238:239], s[50:51], 0, v[134:135]
	s_mov_b32 m0, s59
	s_nop 0
	global_load_lds_dwordx4 v[238:239], off
	s_waitcnt vmcnt(8)
	s_waitcnt lgkmcnt(0)
	s_barrier
	s_waitcnt lgkmcnt(0)
	v_mfma_f32_16x16x32_bf16 v[128:131], v[144:147], v[176:179], v[128:131]
	v_mfma_f32_16x16x32_bf16 v[124:127], v[152:155], v[176:179], v[124:127]
	v_mfma_f32_16x16x32_bf16 v[112:115], v[144:147], v[184:187], v[112:115]
	v_mfma_f32_16x16x32_bf16 v[108:111], v[152:155], v[184:187], v[108:111]
	v_mfma_f32_16x16x32_bf16 v[96:99], v[144:147], v[204:207], v[96:99]
	v_mfma_f32_16x16x32_bf16 v[92:95], v[152:155], v[204:207], v[92:95]
	v_mfma_f32_16x16x32_bf16 v[80:83], v[144:147], v[212:215], v[80:83]
	v_mfma_f32_16x16x32_bf16 v[76:79], v[152:155], v[212:215], v[76:79]
	v_mfma_f32_16x16x32_bf16 v[128:131], v[148:151], v[180:183], v[128:131]
	v_mfma_f32_16x16x32_bf16 v[124:127], v[156:159], v[180:183], v[124:127]
	v_mfma_f32_16x16x32_bf16 v[112:115], v[148:151], v[188:191], v[112:115]
	v_mfma_f32_16x16x32_bf16 v[108:111], v[156:159], v[188:191], v[108:111]
	v_mfma_f32_16x16x32_bf16 v[96:99], v[148:151], v[208:211], v[96:99]
	v_mfma_f32_16x16x32_bf16 v[92:95], v[156:159], v[208:211], v[92:95]
	v_mfma_f32_16x16x32_bf16 v[80:83], v[148:151], v[216:219], v[80:83]
	v_mfma_f32_16x16x32_bf16 v[76:79], v[156:159], v[216:219], v[76:79]
	v_mfma_f32_16x16x32_bf16 v[120:123], v[160:163], v[176:179], v[120:123]
	v_mfma_f32_16x16x32_bf16 v[116:119], v[168:171], v[176:179], v[116:119]
	v_mfma_f32_16x16x32_bf16 v[104:107], v[160:163], v[184:187], v[104:107]
	v_mfma_f32_16x16x32_bf16 v[100:103], v[168:171], v[184:187], v[100:103]
	v_mfma_f32_16x16x32_bf16 v[88:91], v[160:163], v[204:207], v[88:91]
	v_mfma_f32_16x16x32_bf16 v[84:87], v[168:171], v[204:207], v[84:87]
	v_mfma_f32_16x16x32_bf16 v[72:75], v[160:163], v[212:215], v[72:75]
	v_mfma_f32_16x16x32_bf16 v[68:71], v[168:171], v[212:215], v[68:71]
	v_mfma_f32_16x16x32_bf16 v[120:123], v[164:167], v[180:183], v[120:123]
	v_mfma_f32_16x16x32_bf16 v[116:119], v[172:175], v[180:183], v[116:119]
	v_mfma_f32_16x16x32_bf16 v[104:107], v[164:167], v[188:191], v[104:107]
	v_mfma_f32_16x16x32_bf16 v[100:103], v[172:175], v[188:191], v[100:103]
	v_mfma_f32_16x16x32_bf16 v[88:91], v[164:167], v[208:211], v[88:91]
	v_mfma_f32_16x16x32_bf16 v[84:87], v[172:175], v[208:211], v[84:87]
	v_mfma_f32_16x16x32_bf16 v[72:75], v[164:167], v[216:219], v[72:75]
	v_mfma_f32_16x16x32_bf16 v[68:71], v[172:175], v[216:219], v[68:71]
	s_barrier
; #define PG8_STAGE(bufoff, gbase, voff) do { _Pragma("unroll") for (int _i = 0; _i < 2; ++_i) \
;         __builtin_amdgcn_global_load_lds((const unsigned*)((const char*)(gbase) + (voff)[_i]), (PG8_LAS unsigned*)(lds + (bufoff) + ldsw + _i * 8192), 16, 0, 0); } while (0)
; #define PG8_LDA(dst, b, h) do { _Pragma("unroll") for (int m = 0; m < 4; ++m) _Pragma("unroll") for (int k = 0; k < 2; ++k) dst[m][k] = *(const PG8_LAS bf16x8*)(lds + PG8_SA(b, h) + aoff + m * 2048 + k * 1024); } while (0)
; #define PG8_MMA(ai, bj, At, Bt) do { __builtin_amdgcn_s_setprio(1); _Pragma("unroll") for (int m = 0; m < 4; ++m) _Pragma("unroll") for (int n = 0; n < 2; ++n) _Pragma("unroll") for (int k = 0; k < 2; ++k) \
;         acc[ai][bj][m][n] = __builtin_amdgcn_mfma_f32_16x16x32_bf16(Bt[n][k], At[m][k], acc[ai][bj][m][n], 0, 0, 0); __builtin_amdgcn_s_setprio(0); } while (0)
; #define PG8_WAIT_V(n) asm volatile("s_waitcnt vmcnt(" #n ")" ::: "memory")
; #define PG8_WAIT_L(n) asm volatile("s_waitcnt lgkmcnt(" #n ")" ::: "memory")
; #define PG8_BAR __builtin_amdgcn_s_barrier()
; #define PG8_SCHED __builtin_amdgcn_sched_barrier(0)
; template <class Epi, class Sched, bool ALIGN_EPI = false, bool SP2 = false>
; __device__ __forceinline__ void gemm_phase(PG8_LAS unsigned char* lds, const Gemm g, const Sched& S, const Epi& E) {
;     ...
;         for (int t = 0; t < nt; t += 2) {
;     ...
;             PG8_WAIT_V(8); PG8_WAIT_L(0); PG8_BAR; PG8_MMA(0, 0, At, B0); PG8_MMA(0, 1, At, B1); PG8_BAR; PG8_SCHED;
;             PG8_LDA(At, 1, 1); PG8_STAGE(PG8_SB(1, 0), b3, voffB); PG8_STAGE(PG8_SB(1, 1), b3 + hstep, voffB); PG8_STAGE(PG8_SA(1, 0), a3, voffA);
;             PG8_WAIT_V(8); PG8_WAIT_L(0); PG8_BAR; PG8_MMA(1, 0, At, B0); PG8_MMA(1, 1, At, B1); PG8_BAR; PG8_SCHED;
;     ...
;         if constexpr (ALIGN_EPI) { if (wr == 0) PG8_BAR; }
;         if constexpr (!Epi::AFTER_DRAIN) { E(acc, cur, wr, wc, fr, fq); S.done(cur); }
;         if (!has_next) break;
; #pragma unroll
;         for (int a = 0; a < 2; ++a)
; #pragma unroll
;             for (int b = 0; b < 2; ++b)
; #pragma unroll
;                 for (int m = 0; m < 4; ++m)
; #pragma unroll
;                     for (int n = 0; n < 2; ++n) acc[a][b][m][n] = (f32x4){0.f, 0.f, 0.f, 0.f};
;         cur = nxt; cA = nA; cB = nB; ++ui;
	s_add_i32 s50, s68, s55
	v_lshl_add_u64 v[220:221], v[220:221], 0, s[8:9]
	s_mov_b32 m0, s50
	ds_read_b128 v[176:179], v143 offset:49152
	ds_read_b128 v[180:183], v143 offset:50176
	ds_read_b128 v[184:187], v143 offset:51200
	ds_read_b128 v[188:191], v143 offset:52224
	ds_read_b128 v[204:207], v143 offset:53248
	ds_read_b128 v[208:211], v143 offset:54272
	ds_read_b128 v[212:215], v143 offset:55296
	ds_read_b128 v[216:219], v143 offset:56320
	global_load_lds_dwordx4 v[220:221], off
	s_add_i32 m0, s50, 0x2000
	s_add_u32 s46, s46, 0xb0080
	v_lshl_add_u64 v[220:221], v[222:223], 0, s[8:9]
	s_addc_u32 s47, s47, 0
	s_add_i32 s50, s69, s55
	global_load_lds_dwordx4 v[220:221], off
	v_lshl_add_u64 v[220:221], s[46:47], 0, v[132:133]
	s_mov_b32 m0, s50
	s_nop 0
	global_load_lds_dwordx4 v[220:221], off
	v_lshl_add_u64 v[220:221], s[46:47], 0, v[134:135]
	s_add_i32 m0, s50, 0x2000
	s_nop 0
	global_load_lds_dwordx4 v[220:221], off
	v_lshl_add_u64 v[220:221], v[224:225], 0, s[8:9]
	s_mov_b32 m0, s60
	s_nop 0
	global_load_lds_dwordx4 v[220:221], off
	v_lshl_add_u64 v[220:221], v[226:227], 0, s[8:9]
	s_mov_b32 m0, s61
	s_nop 0
	global_load_lds_dwordx4 v[220:221], off
	s_waitcnt vmcnt(8)
	s_waitcnt lgkmcnt(0)
	s_barrier
	s_waitcnt lgkmcnt(0)
	v_mfma_f32_16x16x32_bf16 v[64:67], v[144:147], v[176:179], v[64:67]
	v_mfma_f32_16x16x32_bf16 v[60:63], v[152:155], v[176:179], v[60:63]
	v_mfma_f32_16x16x32_bf16 v[48:51], v[144:147], v[184:187], v[48:51]
	v_mfma_f32_16x16x32_bf16 v[44:47], v[152:155], v[184:187], v[44:47]
	v_mfma_f32_16x16x32_bf16 v[28:31], v[144:147], v[204:207], v[28:31]
	v_mfma_f32_16x16x32_bf16 v[24:27], v[152:155], v[204:207], v[24:27]
	v_mfma_f32_16x16x32_bf16 v[12:15], v[144:147], v[212:215], v[12:15]
	v_mfma_f32_16x16x32_bf16 v[8:11], v[152:155], v[212:215], v[8:11]
	v_mfma_f32_16x16x32_bf16 v[64:67], v[148:151], v[180:183], v[64:67]
	v_mfma_f32_16x16x32_bf16 v[60:63], v[156:159], v[180:183], v[60:63]
	v_mfma_f32_16x16x32_bf16 v[48:51], v[148:151], v[188:191], v[48:51]
	v_mfma_f32_16x16x32_bf16 v[44:47], v[156:159], v[188:191], v[44:47]
	v_mfma_f32_16x16x32_bf16 v[28:31], v[148:151], v[208:211], v[28:31]
	v_mfma_f32_16x16x32_bf16 v[24:27], v[156:159], v[208:211], v[24:27]
	v_mfma_f32_16x16x32_bf16 v[12:15], v[148:151], v[216:219], v[12:15]
	v_mfma_f32_16x16x32_bf16 v[8:11], v[156:159], v[216:219], v[8:11]
	v_mfma_f32_16x16x32_bf16 v[56:59], v[160:163], v[176:179], v[56:59]
	v_mfma_f32_16x16x32_bf16 v[52:55], v[168:171], v[176:179], v[52:55]
	v_mfma_f32_16x16x32_bf16 v[40:43], v[160:163], v[184:187], v[40:43]
	v_mfma_f32_16x16x32_bf16 v[36:39], v[168:171], v[184:187], v[36:39]
	v_mfma_f32_16x16x32_bf16 v[20:23], v[160:163], v[204:207], v[20:23]
	v_mfma_f32_16x16x32_bf16 v[16:19], v[168:171], v[204:207], v[16:19]
	v_mfma_f32_16x16x32_bf16 v[4:7], v[160:163], v[212:215], v[4:7]
	v_mfma_f32_16x16x32_bf16 v[0:3], v[168:171], v[212:215], v[0:3]
	v_mfma_f32_16x16x32_bf16 v[56:59], v[164:167], v[180:183], v[56:59]
	v_mfma_f32_16x16x32_bf16 v[52:55], v[172:175], v[180:183], v[52:55]
	v_mfma_f32_16x16x32_bf16 v[40:43], v[164:167], v[188:191], v[40:43]
	v_mfma_f32_16x16x32_bf16 v[36:39], v[172:175], v[188:191], v[36:39]
	v_mfma_f32_16x16x32_bf16 v[20:23], v[164:167], v[208:211], v[20:23]
	v_mfma_f32_16x16x32_bf16 v[16:19], v[172:175], v[208:211], v[16:19]
	v_mfma_f32_16x16x32_bf16 v[4:7], v[164:167], v[216:219], v[4:7]
	v_mfma_f32_16x16x32_bf16 v[0:3], v[172:175], v[216:219], v[0:3]
	s_barrier
	s_add_i32 s94, s94, 2
	s_add_u32 s44, s44, 0x100
	s_addc_u32 s45, s45, 0
	s_cmp_gt_u32 s94, 41
	s_cbranch_scc0 .LBB0_1081
	s_setprio 0
	s_add_u32 s44, s66, 0xffffff00
	s_addc_u32 s45, s67, -1
	s_and_b64 vcc, exec, s[42:43]
	s_cbranch_vccnz .LBB0_1084
	v_mov_b32_e32 v0, 0
	s_mov_b32 s28, s63
	s_mov_b32 s90, s64
	s_mov_b64 s[6:7], s[36:37]
	s_mov_b32 s62, s65
	v_mov_b32_e32 v1, v0
	v_mov_b32_e32 v2, v0
	v_mov_b32_e32 v3, v0
	v_mov_b32_e32 v4, v0
	v_mov_b32_e32 v5, v0
	v_mov_b32_e32 v6, v0
	v_mov_b32_e32 v7, v0
	v_mov_b32_e32 v16, v0
	v_mov_b32_e32 v17, v0
	v_mov_b32_e32 v18, v0
	v_mov_b32_e32 v19, v0
	v_mov_b32_e32 v20, v0
	v_mov_b32_e32 v21, v0
	v_mov_b32_e32 v22, v0
	v_mov_b32_e32 v23, v0
	v_mov_b32_e32 v36, v0
	v_mov_b32_e32 v37, v0
	v_mov_b32_e32 v38, v0
	v_mov_b32_e32 v39, v0
	v_mov_b32_e32 v40, v0
	v_mov_b32_e32 v41, v0
	v_mov_b32_e32 v42, v0
	v_mov_b32_e32 v43, v0
	v_mov_b32_e32 v52, v0
	v_mov_b32_e32 v53, v0
	v_mov_b32_e32 v54, v0
	v_mov_b32_e32 v55, v0
	v_mov_b32_e32 v56, v0
	v_mov_b32_e32 v57, v0
	v_mov_b32_e32 v58, v0
	v_mov_b32_e32 v59, v0
	v_mov_b32_e32 v8, v0
	v_mov_b32_e32 v9, v0
	v_mov_b32_e32 v10, v0
	v_mov_b32_e32 v11, v0
	v_mov_b32_e32 v12, v0
	v_mov_b32_e32 v13, v0
	v_mov_b32_e32 v14, v0
	v_mov_b32_e32 v15, v0
	v_mov_b32_e32 v24, v0
	v_mov_b32_e32 v25, v0
	v_mov_b32_e32 v26, v0
	v_mov_b32_e32 v27, v0
	v_mov_b32_e32 v28, v0
	v_mov_b32_e32 v29, v0
	v_mov_b32_e32 v30, v0
	v_mov_b32_e32 v31, v0
	v_mov_b32_e32 v44, v0
	v_mov_b32_e32 v45, v0
	v_mov_b32_e32 v46, v0
	v_mov_b32_e32 v47, v0
	v_mov_b32_e32 v48, v0
	v_mov_b32_e32 v49, v0
	v_mov_b32_e32 v50, v0
	v_mov_b32_e32 v51, v0
	v_mov_b32_e32 v60, v0
	v_mov_b32_e32 v61, v0
	v_mov_b32_e32 v62, v0
	v_mov_b32_e32 v63, v0
	v_mov_b32_e32 v64, v0
	v_mov_b32_e32 v65, v0
	v_mov_b32_e32 v66, v0
	v_mov_b32_e32 v67, v0
	v_mov_b32_e32 v68, v0
	v_mov_b32_e32 v69, v0
	v_mov_b32_e32 v70, v0
	v_mov_b32_e32 v71, v0
	v_mov_b32_e32 v72, v0
	v_mov_b32_e32 v73, v0
	v_mov_b32_e32 v74, v0
	v_mov_b32_e32 v75, v0
	v_mov_b32_e32 v84, v0
	v_mov_b32_e32 v85, v0
	v_mov_b32_e32 v86, v0
	v_mov_b32_e32 v87, v0
	v_mov_b32_e32 v88, v0
	v_mov_b32_e32 v89, v0
	v_mov_b32_e32 v90, v0
	v_mov_b32_e32 v91, v0
	v_mov_b32_e32 v100, v0
	v_mov_b32_e32 v101, v0
	v_mov_b32_e32 v102, v0
	v_mov_b32_e32 v103, v0
	v_mov_b32_e32 v104, v0
	v_mov_b32_e32 v105, v0
	v_mov_b32_e32 v106, v0
	v_mov_b32_e32 v107, v0
	v_mov_b32_e32 v116, v0
	v_mov_b32_e32 v117, v0
	v_mov_b32_e32 v118, v0
	v_mov_b32_e32 v119, v0
	v_mov_b32_e32 v120, v0
	v_mov_b32_e32 v121, v0
	v_mov_b32_e32 v122, v0
	v_mov_b32_e32 v123, v0
	v_mov_b32_e32 v76, v0
	v_mov_b32_e32 v77, v0
	v_mov_b32_e32 v78, v0
	v_mov_b32_e32 v79, v0
	v_mov_b32_e32 v80, v0
	v_mov_b32_e32 v81, v0
	v_mov_b32_e32 v82, v0
	v_mov_b32_e32 v83, v0
	v_mov_b32_e32 v92, v0
	v_mov_b32_e32 v93, v0
	v_mov_b32_e32 v94, v0
	v_mov_b32_e32 v95, v0
	v_mov_b32_e32 v96, v0
	v_mov_b32_e32 v97, v0
	v_mov_b32_e32 v98, v0
	v_mov_b32_e32 v99, v0
	v_mov_b32_e32 v108, v0
	v_mov_b32_e32 v109, v0
	v_mov_b32_e32 v110, v0
	v_mov_b32_e32 v111, v0
	v_mov_b32_e32 v112, v0
	v_mov_b32_e32 v113, v0
	v_mov_b32_e32 v114, v0
	v_mov_b32_e32 v115, v0
	v_mov_b32_e32 v124, v0
	v_mov_b32_e32 v125, v0
	v_mov_b32_e32 v126, v0
	v_mov_b32_e32 v127, v0
	v_mov_b32_e32 v128, v0
	v_mov_b32_e32 v129, v0
	v_mov_b32_e32 v130, v0
	v_mov_b32_e32 v131, v0
	s_andn2_b64 vcc, exec, s[40:41]
	s_cbranch_vccnz .LBB0_1085
	s_branch .LBB0_1086
